# bf16 rounding peephole extended: ds_write/global_store d16_hi consumers with offsets, attention and RG-LRU regions (214 single conversions + 46 packed pairs now use v_cvt_pk_bf16_f32)
# speedup vs baseline: 1.0029x; 1.0029x over previous
; #define MFMA16(a, b, c) __builtin_amdgcn_mfma_f32_16x16x32_bf16((a), (b), (c), 0, 0, 0)
; DI void attn_unit(const bf16_t* proj, bf16_t* ycat, const float* sinks, int b, int n, int kvh, LAS unsigned char* lds) {
;     ...
;     for (int rt = 0; rt < 2; ++rt) {
;         const int c0 = rh * 32 + rt * 16;
;         bf16x8 qa[2];
; #pragma unroll
;         for (int ks = 0; ks < 2; ++ks) qa[ks] = (rt == 0) ? qall[0][ks] : qall[1][ks];
;         f32x4 sc[12];
; #pragma unroll
;         for (int kt = 0; kt < 12; ++kt) {
;             f32x4 a = (f32x4){0.f, 0.f, 0.f, 0.f};
; #pragma unroll
;             for (int ks = 0; ks < 2; ++ks) a = MFMA16(qa[ks], ldsfrag(lds + KS_OFF + (kt * 16 + fr) * 144 + (ks * 32 + fq * 8) * 2), a);
;             sc[kt] = a;
;         }
;         float mx[4] = {-3.0e38f, -3.0e38f, -3.0e38f, -3.0e38f};
; #pragma unroll
;         for (int kt = 0; kt < 12; ++kt) {
;             const int s = kt * 16 + fr;
;             const bool valid = ((n - 2) * 64 + s) >= 0;
; #pragma unroll
;             for (int j = 0; j < 4; ++j) {
;                 const int c = c0 + fq * 4 + j;
;                 const float dist = fabsf((float)(c + 128 - s));
;                 const float v = valid ? (sc[kt][j] * 0.125f - slope * dist) : -3.0e38f;
;                 sc[kt][j] = v; mx[j] = fmaxf(mx[j], v);
;             }
.LBB0_251:
	v_cndmask_b32_e64 v19, v11, v3, s[0:1]
	v_cndmask_b32_e64 v18, v10, v2, s[0:1]
	v_cndmask_b32_e64 v17, v9, v1, s[0:1]
	v_cndmask_b32_e64 v16, v8, v0, s[0:1]
	ds_read_b128 v[20:23], v68
	ds_read_b128 v[24:27], v68 offset:64
	v_cndmask_b32_e64 v47, v15, v7, s[0:1]
	v_cndmask_b32_e64 v46, v14, v6, s[0:1]
	v_cndmask_b32_e64 v45, v13, v5, s[0:1]
	v_cndmask_b32_e64 v44, v12, v4, s[0:1]
	s_waitcnt lgkmcnt(1)
	v_mfma_f32_16x16x32_bf16 v[20:23], v[16:19], v[20:23], 0
	ds_read_b128 v[94:97], v68 offset:23104
	s_waitcnt lgkmcnt(1)
	v_mfma_f32_16x16x32_bf16 v[48:51], v[44:47], v[24:27], v[20:23]
	ds_read_b128 v[24:27], v68 offset:2368
	s_nop 3
	ds_read_b128 v[20:23], v68 offset:2304
	s_waitcnt lgkmcnt(0)
	v_mfma_f32_16x16x32_bf16 v[20:23], v[16:19], v[20:23], 0
	v_mov_b32_e32 v40, v48
	v_mfma_f32_16x16x32_bf16 v[74:77], v[44:47], v[24:27], v[20:23]
	ds_read_b128 v[24:27], v68 offset:4672
	s_nop 4
	ds_read_b128 v[20:23], v68 offset:4608
	s_waitcnt lgkmcnt(0)
	v_mfma_f32_16x16x32_bf16 v[20:23], v[16:19], v[20:23], 0
	v_mfma_f32_16x16x32_bf16 v[78:81], v[44:47], v[24:27], v[20:23]
	ds_read_b128 v[24:27], v68 offset:6976
	s_nop 5
	ds_read_b128 v[20:23], v68 offset:6912
	s_waitcnt lgkmcnt(0)
	v_mfma_f32_16x16x32_bf16 v[20:23], v[16:19], v[20:23], 0
	v_mfma_f32_16x16x32_bf16 v[82:85], v[44:47], v[24:27], v[20:23]
	ds_read_b128 v[24:27], v68 offset:9280
	s_nop 5
	ds_read_b128 v[20:23], v68 offset:9216
	s_waitcnt lgkmcnt(0)
	v_mfma_f32_16x16x32_bf16 v[20:23], v[16:19], v[20:23], 0
	v_mfma_f32_16x16x32_bf16 v[86:89], v[44:47], v[24:27], v[20:23]
	ds_read_b128 v[24:27], v68 offset:11584
	s_nop 5
	ds_read_b128 v[20:23], v68 offset:11520
	s_waitcnt lgkmcnt(0)
	v_mfma_f32_16x16x32_bf16 v[20:23], v[16:19], v[20:23], 0
	v_mfma_f32_16x16x32_bf16 v[90:93], v[44:47], v[24:27], v[20:23]
	ds_read_b128 v[24:27], v68 offset:13888
	s_nop 5
	ds_read_b128 v[20:23], v68 offset:13824
	s_waitcnt lgkmcnt(0)
	v_mfma_f32_16x16x32_bf16 v[20:23], v[16:19], v[20:23], 0
	v_mfma_f32_16x16x32_bf16 v[36:39], v[44:47], v[24:27], v[20:23]
	ds_read_b128 v[24:27], v68 offset:16192
	s_nop 5
	ds_read_b128 v[20:23], v68 offset:16128
	s_waitcnt lgkmcnt(0)
	v_mfma_f32_16x16x32_bf16 v[20:23], v[16:19], v[20:23], 0
	v_mfma_f32_16x16x32_bf16 v[32:35], v[44:47], v[24:27], v[20:23]
	ds_read_b128 v[24:27], v68 offset:18496
	s_nop 5
	ds_read_b128 v[20:23], v68 offset:18432
	s_waitcnt lgkmcnt(0)
	v_mfma_f32_16x16x32_bf16 v[20:23], v[16:19], v[20:23], 0
	v_mfma_f32_16x16x32_bf16 v[28:31], v[44:47], v[24:27], v[20:23]
	ds_read_b128 v[24:27], v68 offset:20800
	s_nop 5
	ds_read_b128 v[20:23], v68 offset:20736
	s_waitcnt lgkmcnt(0)
	v_mfma_f32_16x16x32_bf16 v[20:23], v[16:19], v[20:23], 0
	v_mfma_f32_16x16x32_bf16 v[24:27], v[44:47], v[24:27], v[20:23]
	s_nop 6
	ds_read_b128 v[20:23], v68 offset:23040
	s_waitcnt lgkmcnt(0)
	v_mfma_f32_16x16x32_bf16 v[20:23], v[16:19], v[20:23], 0
	v_mfma_f32_16x16x32_bf16 v[20:23], v[44:47], v[94:97], v[20:23]
	ds_read_b128 v[94:97], v68 offset:25344
	s_waitcnt lgkmcnt(0)
	v_mfma_f32_16x16x32_bf16 v[16:19], v[16:19], v[94:97], 0
	ds_read_b128 v[94:97], v68 offset:25408
	s_waitcnt lgkmcnt(0)
	v_mfma_f32_16x16x32_bf16 v[16:19], v[44:47], v[94:97], v[16:19]
	v_or_b32_e32 v44, s26, v53
	v_or_b32_e32 v94, v44, v55
	v_or_b32_e32 v95, 0x80, v94
	v_sub_u32_e32 v45, v95, v52
	v_cvt_f32_u32_e32 v143, v45
	v_sub_u32_e32 v48, v95, v57
	s_mov_b32 s26, 16
	v_pk_mul_f32 v[46:47], v[40:41], v[142:143]
	s_nop 0
	v_sub_f32_e32 v40, v46, v47
	v_cndmask_b32_e64 v96, v170, v40, s[4:5]
	v_add_u32_e32 v40, 1, v45
	v_cvt_f32_u32_e32 v143, v40
	v_mov_b32_e32 v40, v49
	v_cmp_lt_f32_e32 vcc, s25, v96
	v_pk_mul_f32 v[46:47], v[40:41], v[142:143]
	s_nop 0
	v_sub_f32_e32 v40, v46, v47
	v_cndmask_b32_e64 v97, v170, v40, s[4:5]
	v_add_u32_e32 v40, 2, v45
	v_cvt_f32_u32_e32 v143, v40
	v_mov_b32_e32 v40, v50
	v_pk_mul_f32 v[46:47], v[40:41], v[142:143]
	s_nop 0
	v_sub_f32_e32 v40, v46, v47
	v_cndmask_b32_e64 v50, v170, v40, s[4:5]
	v_add_u32_e32 v40, 3, v45
	v_cvt_f32_u32_e32 v143, v40
	v_mov_b32_e32 v40, v51
	v_pk_mul_f32 v[46:47], v[40:41], v[142:143]
	v_cvt_f32_u32_e32 v143, v48
	v_sub_f32_e32 v40, v46, v47
	v_cndmask_b32_e64 v45, v170, v40, s[4:5]
	v_mov_b32_e32 v40, v74
	v_pk_mul_f32 v[46:47], v[40:41], v[142:143]
	s_nop 0
	v_sub_f32_e32 v40, v46, v47
	v_cndmask_b32_e64 v98, v170, v40, s[6:7]
	v_add_u32_e32 v40, 1, v48
	v_cvt_f32_u32_e32 v143, v40
	v_mov_b32_e32 v40, v75
	v_max3_f32 v51, v96, s41, v98
	v_pk_mul_f32 v[46:47], v[40:41], v[142:143]
	s_nop 0
	v_sub_f32_e32 v40, v46, v47
	v_cndmask_b32_e64 v99, v170, v40, s[6:7]
	v_add_u32_e32 v40, 2, v48
	v_cvt_f32_u32_e32 v143, v40
	v_mov_b32_e32 v40, v76
	v_max3_f32 v74, v97, s41, v99
	v_pk_mul_f32 v[46:47], v[40:41], v[142:143]
	s_nop 0
	v_sub_f32_e32 v40, v46, v47
	v_cndmask_b32_e64 v76, v170, v40, s[6:7]
	v_add_u32_e32 v40, 3, v48
	v_cvt_f32_u32_e32 v143, v40
	v_mov_b32_e32 v40, v77
	v_max3_f32 v75, v50, s41, v76
	v_pk_mul_f32 v[46:47], v[40:41], v[142:143]
	s_nop 0
	v_sub_f32_e32 v40, v46, v47
	v_sub_u32_e32 v47, v95, v58
	v_cvt_f32_u32_e32 v143, v47
	v_cndmask_b32_e64 v46, v170, v40, s[6:7]
	v_mov_b32_e32 v40, v78
	v_max3_f32 v77, v45, s41, v46
	v_pk_mul_f32 v[48:49], v[40:41], v[142:143]
	s_nop 0
	v_sub_f32_e32 v40, v48, v49
	v_cndmask_b32_e64 v78, v170, v40, s[8:9]
	v_add_u32_e32 v40, 1, v47
	v_cvt_f32_u32_e32 v143, v40
	v_mov_b32_e32 v40, v79
	v_pk_mul_f32 v[48:49], v[40:41], v[142:143]
	s_nop 0
	v_sub_f32_e32 v40, v48, v49
	v_cndmask_b32_e64 v79, v170, v40, s[8:9]
	v_add_u32_e32 v40, 2, v47
	v_cvt_f32_u32_e32 v143, v40
	v_mov_b32_e32 v40, v80
	v_pk_mul_f32 v[48:49], v[40:41], v[142:143]
	s_nop 0
	v_sub_f32_e32 v40, v48, v49
; DI void attn_unit(const bf16_t* proj, bf16_t* ycat, const float* sinks, int b, int n, int kvh, LAS unsigned char* lds) {
;     ...
;         float mx[4] = {-3.0e38f, -3.0e38f, -3.0e38f, -3.0e38f};
; #pragma unroll
;         for (int kt = 0; kt < 12; ++kt) {
;             const int s = kt * 16 + fr;
;             const bool valid = ((n - 2) * 64 + s) >= 0;
; #pragma unroll
;             for (int j = 0; j < 4; ++j) {
;                 const int c = c0 + fq * 4 + j;
;                 const float dist = fabsf((float)(c + 128 - s));
;                 const float v = valid ? (sc[kt][j] * 0.125f - slope * dist) : -3.0e38f;
;                 sc[kt][j] = v; mx[j] = fmaxf(mx[j], v);
;             }
	v_cndmask_b32_e64 v80, v170, v40, s[8:9]
	v_add_u32_e32 v40, 3, v47
	v_cvt_f32_u32_e32 v143, v40
	v_mov_b32_e32 v40, v81
	v_sub_u32_e32 v81, v95, v59
	v_pk_mul_f32 v[48:49], v[40:41], v[142:143]
	v_cvt_f32_u32_e32 v143, v81
	v_sub_f32_e32 v40, v48, v49
	v_cndmask_b32_e64 v47, v170, v40, s[8:9]
	v_mov_b32_e32 v40, v82
	v_pk_mul_f32 v[48:49], v[40:41], v[142:143]
	s_nop 0
	v_sub_f32_e32 v40, v48, v49
	v_cndmask_b32_e64 v82, v170, v40, s[10:11]
	v_add_u32_e32 v40, 1, v81
	v_cvt_f32_u32_e32 v143, v40
	v_mov_b32_e32 v40, v83
	v_max3_f32 v51, v51, v78, v82
	v_pk_mul_f32 v[48:49], v[40:41], v[142:143]
	s_nop 0
	v_sub_f32_e32 v40, v48, v49
	v_cndmask_b32_e64 v83, v170, v40, s[10:11]
	v_add_u32_e32 v40, 2, v81
	v_cvt_f32_u32_e32 v143, v40
	v_mov_b32_e32 v40, v84
	v_max3_f32 v100, v74, v79, v83
	v_pk_mul_f32 v[48:49], v[40:41], v[142:143]
	s_nop 0
	v_sub_f32_e32 v40, v48, v49
	v_cndmask_b32_e64 v84, v170, v40, s[10:11]
	v_add_u32_e32 v40, 3, v81
	v_cvt_f32_u32_e32 v143, v40
	v_mov_b32_e32 v40, v85
	v_max3_f32 v101, v75, v80, v84
	v_pk_mul_f32 v[48:49], v[40:41], v[142:143]
	s_nop 0
	v_sub_f32_e32 v40, v48, v49
	v_sub_u32_e32 v49, v95, v60
	v_cvt_f32_u32_e32 v143, v49
	v_cndmask_b32_e64 v48, v170, v40, s[10:11]
	v_mov_b32_e32 v40, v86
	v_max3_f32 v77, v77, v47, v48
	v_pk_mul_f32 v[74:75], v[40:41], v[142:143]
	s_nop 0
	v_sub_f32_e32 v40, v74, v75
	v_cndmask_b32_e64 v81, v170, v40, s[12:13]
	v_add_u32_e32 v40, 1, v49
	v_cvt_f32_u32_e32 v143, v40
	v_mov_b32_e32 v40, v87
	v_sub_u32_e32 v87, v95, v61
	v_pk_mul_f32 v[74:75], v[40:41], v[142:143]
	s_nop 0
	v_sub_f32_e32 v40, v74, v75
	v_cndmask_b32_e64 v85, v170, v40, s[12:13]
	v_add_u32_e32 v40, 2, v49
	v_cvt_f32_u32_e32 v143, v40
	v_mov_b32_e32 v40, v88
	v_pk_mul_f32 v[74:75], v[40:41], v[142:143]
	s_nop 0
	v_sub_f32_e32 v40, v74, v75
	v_cndmask_b32_e64 v86, v170, v40, s[12:13]
	v_add_u32_e32 v40, 3, v49
	v_cvt_f32_u32_e32 v143, v40
	v_mov_b32_e32 v40, v89
	v_pk_mul_f32 v[74:75], v[40:41], v[142:143]
	v_cvt_f32_u32_e32 v143, v87
	v_sub_f32_e32 v40, v74, v75
	v_cndmask_b32_e64 v49, v170, v40, s[12:13]
	v_mov_b32_e32 v40, v90
	v_pk_mul_f32 v[74:75], v[40:41], v[142:143]
	s_nop 0
	v_sub_f32_e32 v40, v74, v75
	v_cndmask_b32_e64 v88, v170, v40, s[14:15]
	v_add_u32_e32 v40, 1, v87
	v_cvt_f32_u32_e32 v143, v40
	v_mov_b32_e32 v40, v91
	v_max3_f32 v89, v51, v81, v88
	v_pk_mul_f32 v[74:75], v[40:41], v[142:143]
	s_nop 0
	v_sub_f32_e32 v40, v74, v75
	v_cndmask_b32_e64 v90, v170, v40, s[14:15]
	v_add_u32_e32 v40, 2, v87
	v_cvt_f32_u32_e32 v143, v40
	v_mov_b32_e32 v40, v92
	v_max3_f32 v91, v100, v85, v90
	v_pk_mul_f32 v[74:75], v[40:41], v[142:143]
	s_nop 0
	v_sub_f32_e32 v40, v74, v75
	v_cndmask_b32_e64 v92, v170, v40, s[14:15]
	v_add_u32_e32 v40, 3, v87
	v_cvt_f32_u32_e32 v143, v40
	v_mov_b32_e32 v40, v93
	v_sub_u32_e32 v87, v95, v62
	v_max3_f32 v100, v101, v86, v92
	v_pk_mul_f32 v[74:75], v[40:41], v[142:143]
	v_cvt_f32_u32_e32 v143, v87
	v_sub_f32_e32 v40, v74, v75
	v_cndmask_b32_e64 v51, v170, v40, s[14:15]
	v_mov_b32_e32 v40, v36
	v_pk_mul_f32 v[74:75], v[40:41], v[142:143]
	v_mov_b32_e32 v40, v37
	v_sub_f32_e32 v36, v74, v75
	v_cndmask_b32_e64 v74, v170, v36, s[16:17]
	v_add_u32_e32 v36, 1, v87
	v_cvt_f32_u32_e32 v143, v36
	v_max3_f32 v77, v77, v49, v51
	v_pk_mul_f32 v[36:37], v[40:41], v[142:143]
	s_nop 0
	v_sub_f32_e32 v36, v36, v37
	v_cndmask_b32_e64 v75, v170, v36, s[16:17]
	v_add_u32_e32 v36, 2, v87
	v_cvt_f32_u32_e32 v143, v36
	v_mov_b32_e32 v40, v38
	v_pk_mul_f32 v[36:37], v[40:41], v[142:143]
	s_nop 0
	v_sub_f32_e32 v36, v36, v37
	v_cndmask_b32_e64 v38, v170, v36, s[16:17]
	v_add_u32_e32 v36, 3, v87
	v_cvt_f32_u32_e32 v143, v36
	v_mov_b32_e32 v40, v39
	v_sub_u32_e32 v87, v95, v63
	v_pk_mul_f32 v[36:37], v[40:41], v[142:143]
	v_cvt_f32_u32_e32 v143, v87
	v_sub_f32_e32 v36, v36, v37
	v_mov_b32_e32 v40, v32
	v_cndmask_b32_e64 v39, v170, v36, s[16:17]
	v_pk_mul_f32 v[36:37], v[40:41], v[142:143]
	v_mov_b32_e32 v40, v33
	v_sub_f32_e32 v32, v36, v37
	v_cndmask_b32_e64 v36, v170, v32, s[18:19]
	v_add_u32_e32 v32, 1, v87
	v_cvt_f32_u32_e32 v143, v32
	v_max3_f32 v37, v89, v74, v36
	v_pk_mul_f32 v[32:33], v[40:41], v[142:143]
	s_nop 0
	v_sub_f32_e32 v32, v32, v33
	v_cndmask_b32_e64 v89, v170, v32, s[18:19]
	v_add_u32_e32 v32, 2, v87
	v_cvt_f32_u32_e32 v143, v32
	v_mov_b32_e32 v40, v34
	v_max3_f32 v91, v91, v75, v89
	v_pk_mul_f32 v[32:33], v[40:41], v[142:143]
	s_nop 0
	v_sub_f32_e32 v32, v32, v33
	v_cndmask_b32_e64 v34, v170, v32, s[18:19]
	v_add_u32_e32 v32, 3, v87
	v_cvt_f32_u32_e32 v143, v32
	v_mov_b32_e32 v40, v35
	v_sub_u32_e32 v87, v94, v52
	v_max3_f32 v93, v100, v38, v34
	v_pk_mul_f32 v[32:33], v[40:41], v[142:143]
	v_mov_b32_e32 v40, v28
	v_sub_f32_e32 v32, v32, v33
	v_cndmask_b32_e64 v35, v170, v32, s[18:19]
	v_cvt_f32_i32_e32 v32, v87
	v_add_u32_e32 v28, 1, v87
	v_cvt_f32_i32_e32 v28, v28
	v_max3_f32 v77, v77, v39, v35
	v_and_b32_e32 v143, 0x7fffffff, v32
	v_pk_mul_f32 v[32:33], v[40:41], v[142:143]
	v_and_b32_e32 v143, 0x7fffffff, v28
	v_mov_b32_e32 v40, v29
	v_pk_mul_f32 v[28:29], v[40:41], v[142:143]
	v_sub_f32_e32 v32, v32, v33
	v_sub_f32_e32 v33, v28, v29
	v_add_u32_e32 v28, 2, v87
	v_cvt_f32_i32_e32 v28, v28
	v_mov_b32_e32 v40, v30
	v_and_b32_e32 v143, 0x7fffffff, v28
	v_pk_mul_f32 v[28:29], v[40:41], v[142:143]
	v_mov_b32_e32 v40, v31
	v_sub_f32_e32 v30, v28, v29
	v_add_u32_e32 v28, 3, v87
	v_cvt_f32_i32_e32 v28, v28
	v_sub_u32_e32 v87, v95, v64
	v_and_b32_e32 v143, 0x7fffffff, v28
	v_pk_mul_f32 v[28:29], v[40:41], v[142:143]
	v_mov_b32_e32 v40, v24
	v_sub_f32_e32 v31, v28, v29
	v_cvt_f32_i32_e32 v28, v87
	v_add_u32_e32 v24, 1, v87
	v_cvt_f32_i32_e32 v24, v24
	v_and_b32_e32 v143, 0x7fffffff, v28
; DI float row16_sum(float v) { v += dppf<0xB1>(v); v += dppf<0x4E>(v); v += dppf<0x141>(v); v += dppf<0x140>(v); return v; }
; DI float row16_max(float v) { v = fmaxf(v, dppf<0xB1>(v)); v = fmaxf(v, dppf<0x4E>(v)); v = fmaxf(v, dppf<0x141>(v)); v = fmaxf(v, dppf<0x140>(v)); return v; }
; DI void attn_unit(const bf16_t* proj, bf16_t* ycat, const float* sinks, int b, int n, int kvh, LAS unsigned char* lds) {
;     ...
;         float mx[4] = {-3.0e38f, -3.0e38f, -3.0e38f, -3.0e38f};
; #pragma unroll
;         for (int kt = 0; kt < 12; ++kt) {
;             const int s = kt * 16 + fr;
;             const bool valid = ((n - 2) * 64 + s) >= 0;
; #pragma unroll
;             for (int j = 0; j < 4; ++j) {
;                 const int c = c0 + fq * 4 + j;
;                 const float dist = fabsf((float)(c + 128 - s));
;                 const float v = valid ? (sc[kt][j] * 0.125f - slope * dist) : -3.0e38f;
;                 sc[kt][j] = v; mx[j] = fmaxf(mx[j], v);
;             }
;         }
;         float den[4];
; #pragma unroll
;         for (int j = 0; j < 4; ++j) {
;             float m = mx[j];
;             m = row16_max(m);
;             m = fmaxf(m, sink); mx[j] = m;
;             float ssum = 0.f;
; #pragma unroll
;             for (int kt = 0; kt < 12; ++kt) { const float p = (sc[kt][j] > -1.0e38f) ? __expf(sc[kt][j] - m) : 0.f; sc[kt][j] = p; ssum += p; }
;             ssum = row16_sum(ssum);
;             den[j] = 1.0f / (ssum + __expf(sink - m));
	v_pk_mul_f32 v[28:29], v[40:41], v[142:143]
	v_and_b32_e32 v143, 0x7fffffff, v24
	v_mov_b32_e32 v40, v25
	v_sub_f32_e32 v28, v28, v29
	v_pk_mul_f32 v[24:25], v[40:41], v[142:143]
	v_max3_f32 v29, v37, v32, v28
	v_sub_f32_e32 v37, v24, v25
	v_add_u32_e32 v24, 2, v87
	v_cvt_f32_i32_e32 v24, v24
	v_mov_b32_e32 v40, v26
	v_max3_f32 v91, v91, v33, v37
	v_and_b32_e32 v143, 0x7fffffff, v24
	v_pk_mul_f32 v[24:25], v[40:41], v[142:143]
	v_mov_b32_e32 v40, v27
	v_sub_f32_e32 v26, v24, v25
	v_add_u32_e32 v24, 3, v87
	v_cvt_f32_i32_e32 v24, v24
	v_sub_u32_e32 v87, v95, v65
	v_max3_f32 v93, v93, v30, v26
	v_and_b32_e32 v143, 0x7fffffff, v24
	v_pk_mul_f32 v[24:25], v[40:41], v[142:143]
	v_mov_b32_e32 v40, v20
	v_sub_f32_e32 v27, v24, v25
	v_cvt_f32_i32_e32 v24, v87
	v_add_u32_e32 v20, 1, v87
	v_cvt_f32_i32_e32 v20, v20
	v_max3_f32 v77, v77, v31, v27
	v_and_b32_e32 v143, 0x7fffffff, v24
	v_pk_mul_f32 v[24:25], v[40:41], v[142:143]
	v_and_b32_e32 v143, 0x7fffffff, v20
	v_mov_b32_e32 v40, v21
	v_pk_mul_f32 v[20:21], v[40:41], v[142:143]
	v_sub_f32_e32 v24, v24, v25
	v_sub_f32_e32 v25, v20, v21
	v_add_u32_e32 v20, 2, v87
	v_cvt_f32_i32_e32 v20, v20
	v_mov_b32_e32 v40, v22
	v_and_b32_e32 v143, 0x7fffffff, v20
	v_pk_mul_f32 v[20:21], v[40:41], v[142:143]
	v_mov_b32_e32 v40, v23
	v_sub_f32_e32 v22, v20, v21
	v_add_u32_e32 v20, 3, v87
	v_cvt_f32_i32_e32 v20, v20
	v_sub_u32_e32 v87, v95, v66
	v_and_b32_e32 v143, 0x7fffffff, v20
	v_pk_mul_f32 v[20:21], v[40:41], v[142:143]
	v_mov_b32_e32 v40, v16
	v_sub_f32_e32 v23, v20, v21
	v_cvt_f32_i32_e32 v20, v87
	v_add_u32_e32 v16, 1, v87
	v_cvt_f32_i32_e32 v16, v16
	v_and_b32_e32 v143, 0x7fffffff, v20
	v_pk_mul_f32 v[20:21], v[40:41], v[142:143]
	v_and_b32_e32 v143, 0x7fffffff, v16
	v_mov_b32_e32 v40, v17
	v_sub_f32_e32 v20, v20, v21
	v_pk_mul_f32 v[16:17], v[40:41], v[142:143]
	v_max3_f32 v21, v29, v24, v20
	v_sub_f32_e32 v29, v16, v17
	v_add_u32_e32 v16, 2, v87
	v_cvt_f32_i32_e32 v16, v16
	v_mov_b32_e32 v40, v18
	v_max3_f32 v91, v91, v25, v29
	v_and_b32_e32 v143, 0x7fffffff, v16
	v_pk_mul_f32 v[16:17], v[40:41], v[142:143]
	v_mov_b32_e32 v40, v19
	v_sub_f32_e32 v18, v16, v17
	v_add_u32_e32 v16, 3, v87
	v_cvt_f32_i32_e32 v16, v16
	v_max3_f32 v93, v93, v22, v18
	v_and_b32_e32 v143, 0x7fffffff, v16
	v_pk_mul_f32 v[16:17], v[40:41], v[142:143]
	s_nop 0
	v_sub_f32_e32 v17, v16, v17
	v_mov_b32_dpp v16, v21 quad_perm:[1,0,3,2] row_mask:0xf bank_mask:0xf bound_ctrl:1
	v_max_f32_e32 v16, v16, v16
	v_max_f32_e32 v16, v21, v16
	v_max3_f32 v19, v77, v23, v17
	s_nop 0
	v_mov_b32_dpp v21, v16 quad_perm:[2,3,0,1] row_mask:0xf bank_mask:0xf bound_ctrl:1
	v_max_f32_e32 v21, v21, v21
	v_max_f32_e32 v16, v16, v21
	s_nop 1
	v_mov_b32_dpp v21, v16 row_half_mirror row_mask:0xf bank_mask:0xf bound_ctrl:1
	v_max_f32_e32 v21, v21, v21
	v_max_f32_e32 v16, v16, v21
	s_nop 1
	v_mov_b32_dpp v21, v16 row_mirror row_mask:0xf bank_mask:0xf bound_ctrl:1
	v_max3_f32 v21, v16, v21, v54
	v_sub_f32_e32 v16, v96, v21
	v_mul_f32_e32 v16, 0x3fb8aa3b, v16
	v_sub_f32_e32 v77, v98, v21
	v_exp_f32_e32 v16, v16
	v_mul_f32_e32 v77, 0x3fb8aa3b, v77
	v_exp_f32_e32 v77, v77
	v_sub_f32_e32 v87, v88, v21
	v_cndmask_b32_e32 v40, 0, v16, vcc
	v_cmp_lt_f32_e32 vcc, s25, v98
	v_mul_f32_e32 v87, 0x3fb8aa3b, v87
	v_exp_f32_e32 v87, v87
	v_cndmask_b32_e32 v77, 0, v77, vcc
	v_cmp_lt_f32_e32 vcc, s25, v78
	v_sub_f32_e32 v78, v78, v21
	v_mul_f32_e32 v78, 0x3fb8aa3b, v78
	v_exp_f32_e32 v78, v78
	v_add_f32_e32 v16, 0, v40
	v_add_f32_e32 v16, v77, v16
	v_cndmask_b32_e32 v78, 0, v78, vcc
	v_cmp_lt_f32_e32 vcc, s25, v82
	v_sub_f32_e32 v82, v82, v21
	v_mul_f32_e32 v82, 0x3fb8aa3b, v82
	v_exp_f32_e32 v82, v82
	v_add_f32_e32 v16, v78, v16
	v_cndmask_b32_e32 v82, 0, v82, vcc
	v_cmp_lt_f32_e32 vcc, s25, v81
	v_sub_f32_e32 v81, v81, v21
	v_mul_f32_e32 v81, 0x3fb8aa3b, v81
	v_exp_f32_e32 v81, v81
	v_add_f32_e32 v16, v82, v16
	v_cndmask_b32_e32 v81, 0, v81, vcc
	v_cmp_lt_f32_e32 vcc, s25, v88
	v_add_f32_e32 v16, v81, v16
	s_nop 0
	v_cndmask_b32_e32 v87, 0, v87, vcc
	v_cmp_lt_f32_e32 vcc, s25, v74
	v_sub_f32_e32 v74, v74, v21
	v_mul_f32_e32 v74, 0x3fb8aa3b, v74
	v_exp_f32_e32 v74, v74
	v_add_f32_e32 v16, v87, v16
	v_cndmask_b32_e32 v74, 0, v74, vcc
	v_cmp_lt_f32_e32 vcc, s25, v36
	v_sub_f32_e32 v36, v36, v21
	v_mul_f32_e32 v36, 0x3fb8aa3b, v36
	v_exp_f32_e32 v36, v36
	v_add_f32_e32 v16, v74, v16
	v_cndmask_b32_e32 v36, 0, v36, vcc
	v_cmp_lt_f32_e32 vcc, s25, v32
	v_sub_f32_e32 v32, v32, v21
	v_mul_f32_e32 v32, 0x3fb8aa3b, v32
	v_exp_f32_e32 v32, v32
	v_add_f32_e32 v16, v36, v16
	v_cndmask_b32_e32 v32, 0, v32, vcc
	v_cmp_lt_f32_e32 vcc, s25, v28
	v_sub_f32_e32 v28, v28, v21
	v_mul_f32_e32 v28, 0x3fb8aa3b, v28
	v_exp_f32_e32 v28, v28
	v_add_f32_e32 v16, v32, v16
	v_cndmask_b32_e32 v28, 0, v28, vcc
	v_cmp_lt_f32_e32 vcc, s25, v24
	v_sub_f32_e32 v24, v24, v21
	v_mul_f32_e32 v24, 0x3fb8aa3b, v24
	v_exp_f32_e32 v24, v24
	v_add_f32_e32 v16, v28, v16
	v_cndmask_b32_e32 v24, 0, v24, vcc
	v_add_f32_e32 v88, v24, v16
	v_sub_f32_e32 v16, v20, v21
	v_mul_f32_e32 v16, 0x3fb8aa3b, v16
	v_exp_f32_e32 v16, v16
	v_cmp_lt_f32_e32 vcc, s25, v20
	v_sub_f32_e32 v21, v54, v21
	v_mul_f32_e32 v21, 0x3fb8aa3b, v21
	v_cndmask_b32_e32 v16, 0, v16, vcc
	v_add_f32_e32 v20, v16, v88
	v_exp_f32_e32 v21, v21
	s_nop 0
	v_add_f32_dpp v20, v20, v20 quad_perm:[1,0,3,2] row_mask:0xf bank_mask:0xf bound_ctrl:1
	s_nop 1
	v_add_f32_dpp v20, v20, v20 quad_perm:[2,3,0,1] row_mask:0xf bank_mask:0xf bound_ctrl:1
	s_nop 1
	v_add_f32_dpp v20, v20, v20 row_half_mirror row_mask:0xf bank_mask:0xf bound_ctrl:1
	s_nop 1
	v_add_f32_dpp v20, v20, v20 row_mirror row_mask:0xf bank_mask:0xf bound_ctrl:1
	v_add_f32_e32 v20, v21, v20
; DI float row16_sum(float v) { v += dppf<0xB1>(v); v += dppf<0x4E>(v); v += dppf<0x141>(v); v += dppf<0x140>(v); return v; }
; DI float row16_max(float v) { v = fmaxf(v, dppf<0xB1>(v)); v = fmaxf(v, dppf<0x4E>(v)); v = fmaxf(v, dppf<0x141>(v)); v = fmaxf(v, dppf<0x140>(v)); return v; }
; DI void attn_unit(const bf16_t* proj, bf16_t* ycat, const float* sinks, int b, int n, int kvh, LAS unsigned char* lds) {
;     ...
;         float den[4];
; #pragma unroll
;         for (int j = 0; j < 4; ++j) {
;             float m = mx[j];
;             m = row16_max(m);
;             m = fmaxf(m, sink); mx[j] = m;
;             float ssum = 0.f;
; #pragma unroll
;             for (int kt = 0; kt < 12; ++kt) { const float p = (sc[kt][j] > -1.0e38f) ? __expf(sc[kt][j] - m) : 0.f; sc[kt][j] = p; ssum += p; }
;             ssum = row16_sum(ssum);
;             den[j] = 1.0f / (ssum + __expf(sink - m));
;         }
	v_div_scale_f32 v21, s[42:43], v20, v20, 1.0
	v_rcp_f32_e32 v88, v21
	s_nop 0
	v_fma_f32 v94, -v21, v88, 1.0
	v_fmac_f32_e32 v88, v94, v88
	v_div_scale_f32 v94, vcc, 1.0, v20, 1.0
	v_mul_f32_e32 v95, v94, v88
	v_fma_f32 v96, -v21, v95, v94
	v_fmac_f32_e32 v95, v96, v88
	v_fma_f32 v21, -v21, v95, v94
	v_div_fmas_f32 v21, v21, v88, v95
	v_div_fixup_f32 v20, v21, v20, 1.0
	v_cmp_lt_f32_e32 vcc, s25, v97
	v_mov_b32_dpp v21, v91 quad_perm:[1,0,3,2] row_mask:0xf bank_mask:0xf bound_ctrl:1
	v_max_f32_e32 v21, v21, v21
	v_max_f32_e32 v21, v91, v21
	v_mul_f32_e32 v40, v40, v20
	v_mul_f32_e32 v36, v36, v20
	v_mov_b32_dpp v88, v21 quad_perm:[2,3,0,1] row_mask:0xf bank_mask:0xf bound_ctrl:1
	v_max_f32_e32 v88, v88, v88
	v_max_f32_e32 v21, v21, v88
	v_mul_f32_e32 v32, v32, v20
	v_mul_f32_e32 v28, v28, v20
	v_mov_b32_dpp v88, v21 row_half_mirror row_mask:0xf bank_mask:0xf bound_ctrl:1
	v_max_f32_e32 v88, v88, v88
	v_max_f32_e32 v21, v21, v88
	v_mul_f32_e32 v16, v16, v20
	v_mul_f32_e32 v24, v24, v20
	v_mov_b32_dpp v88, v21 row_mirror row_mask:0xf bank_mask:0xf bound_ctrl:1
	v_max3_f32 v21, v21, v88, v54
	v_sub_f32_e32 v88, v97, v21
	v_mul_f32_e32 v88, 0x3fb8aa3b, v88
	v_sub_f32_e32 v94, v99, v21
	v_exp_f32_e32 v88, v88
	v_mul_f32_e32 v94, 0x3fb8aa3b, v94
	v_exp_f32_e32 v94, v94
	v_cndmask_b32_e32 v88, 0, v88, vcc
	v_cmp_lt_f32_e32 vcc, s25, v99
	v_add_f32_e32 v91, 0, v88
	s_nop 0
	v_cndmask_b32_e32 v94, 0, v94, vcc
	v_cmp_lt_f32_e32 vcc, s25, v79
	v_sub_f32_e32 v79, v79, v21
	v_mul_f32_e32 v79, 0x3fb8aa3b, v79
	v_exp_f32_e32 v79, v79
	v_add_f32_e32 v91, v94, v91
	v_cndmask_b32_e32 v79, 0, v79, vcc
	v_cmp_lt_f32_e32 vcc, s25, v83
	v_sub_f32_e32 v83, v83, v21
	v_mul_f32_e32 v83, 0x3fb8aa3b, v83
	v_exp_f32_e32 v83, v83
	v_add_f32_e32 v91, v79, v91
	v_cndmask_b32_e32 v83, 0, v83, vcc
	v_cmp_lt_f32_e32 vcc, s25, v85
	v_sub_f32_e32 v85, v85, v21
	v_mul_f32_e32 v85, 0x3fb8aa3b, v85
	v_exp_f32_e32 v85, v85
	v_add_f32_e32 v91, v83, v91
	v_cndmask_b32_e32 v85, 0, v85, vcc
	v_cmp_lt_f32_e32 vcc, s25, v90
	v_sub_f32_e32 v90, v90, v21
	v_mul_f32_e32 v90, 0x3fb8aa3b, v90
	v_exp_f32_e32 v90, v90
	v_add_f32_e32 v91, v85, v91
	v_cndmask_b32_e32 v90, 0, v90, vcc
	v_cmp_lt_f32_e32 vcc, s25, v75
	v_sub_f32_e32 v75, v75, v21
	v_mul_f32_e32 v75, 0x3fb8aa3b, v75
	v_exp_f32_e32 v75, v75
	v_add_f32_e32 v91, v90, v91
	v_cndmask_b32_e32 v75, 0, v75, vcc
	v_cmp_lt_f32_e32 vcc, s25, v89
	v_sub_f32_e32 v89, v89, v21
	v_mul_f32_e32 v89, 0x3fb8aa3b, v89
	v_exp_f32_e32 v89, v89
	v_add_f32_e32 v91, v75, v91
	v_cndmask_b32_e32 v89, 0, v89, vcc
	v_cmp_lt_f32_e32 vcc, s25, v33
	v_sub_f32_e32 v33, v33, v21
	v_mul_f32_e32 v33, 0x3fb8aa3b, v33
	v_exp_f32_e32 v33, v33
	v_add_f32_e32 v91, v89, v91
	v_cndmask_b32_e32 v33, 0, v33, vcc
	v_cmp_lt_f32_e32 vcc, s25, v37
	v_sub_f32_e32 v37, v37, v21
	v_mul_f32_e32 v37, 0x3fb8aa3b, v37
	v_exp_f32_e32 v37, v37
	v_add_f32_e32 v91, v33, v91
	v_cndmask_b32_e32 v37, 0, v37, vcc
	v_cmp_lt_f32_e32 vcc, s25, v25
	v_sub_f32_e32 v25, v25, v21
	v_mul_f32_e32 v25, 0x3fb8aa3b, v25
	v_exp_f32_e32 v25, v25
	v_add_f32_e32 v91, v37, v91
	v_cndmask_b32_e32 v25, 0, v25, vcc
	v_cmp_lt_f32_e32 vcc, s25, v29
	v_sub_f32_e32 v29, v29, v21
	v_mul_f32_e32 v29, 0x3fb8aa3b, v29
	v_exp_f32_e32 v29, v29
	v_add_f32_e32 v91, v25, v91
	v_sub_f32_e32 v21, v54, v21
	v_mul_f32_e32 v21, 0x3fb8aa3b, v21
	v_cndmask_b32_e32 v29, 0, v29, vcc
	v_add_f32_e32 v91, v29, v91
	v_exp_f32_e32 v21, v21
	s_nop 0
	v_add_f32_dpp v91, v91, v91 quad_perm:[1,0,3,2] row_mask:0xf bank_mask:0xf bound_ctrl:1
	s_nop 1
	v_add_f32_dpp v91, v91, v91 quad_perm:[2,3,0,1] row_mask:0xf bank_mask:0xf bound_ctrl:1
	s_nop 1
	v_add_f32_dpp v91, v91, v91 row_half_mirror row_mask:0xf bank_mask:0xf bound_ctrl:1
	s_nop 1
	v_add_f32_dpp v91, v91, v91 row_mirror row_mask:0xf bank_mask:0xf bound_ctrl:1
	v_add_f32_e32 v21, v21, v91
	v_div_scale_f32 v91, s[42:43], v21, v21, 1.0
	v_rcp_f32_e32 v95, v91
	s_nop 0
	v_fma_f32 v96, -v91, v95, 1.0
	v_fmac_f32_e32 v95, v96, v95
	v_div_scale_f32 v96, vcc, 1.0, v21, 1.0
	v_mul_f32_e32 v97, v96, v95
	v_fma_f32 v98, -v91, v97, v96
	v_fmac_f32_e32 v97, v98, v95
	v_fma_f32 v91, -v91, v97, v96
	v_div_fmas_f32 v91, v91, v95, v97
	v_div_fixup_f32 v21, v91, v21, 1.0
	v_cmp_lt_f32_e32 vcc, s25, v50
	v_mov_b32_dpp v91, v93 quad_perm:[1,0,3,2] row_mask:0xf bank_mask:0xf bound_ctrl:1
	v_max_f32_e32 v91, v91, v91
	v_max_f32_e32 v91, v93, v91
	s_nop 1
	v_mov_b32_dpp v93, v91 quad_perm:[2,3,0,1] row_mask:0xf bank_mask:0xf bound_ctrl:1
	v_max_f32_e32 v93, v93, v93
	v_max_f32_e32 v91, v91, v93
	s_nop 1
	v_mov_b32_dpp v93, v91 row_half_mirror row_mask:0xf bank_mask:0xf bound_ctrl:1
	v_max_f32_e32 v93, v93, v93
	v_max_f32_e32 v91, v91, v93
	s_nop 1
	v_mov_b32_dpp v93, v91 row_mirror row_mask:0xf bank_mask:0xf bound_ctrl:1
	v_max3_f32 v91, v91, v93, v54
	v_sub_f32_e32 v50, v50, v91
	v_mul_f32_e32 v50, 0x3fb8aa3b, v50
	v_exp_f32_e32 v50, v50
	s_nop 0
	v_cndmask_b32_e32 v50, 0, v50, vcc
	v_cmp_lt_f32_e32 vcc, s25, v76
	v_sub_f32_e32 v76, v76, v91
	v_mul_f32_e32 v76, 0x3fb8aa3b, v76
	v_exp_f32_e32 v76, v76
	v_add_f32_e32 v93, 0, v50
	v_cndmask_b32_e32 v76, 0, v76, vcc
	v_cmp_lt_f32_e32 vcc, s25, v80
	v_sub_f32_e32 v80, v80, v91
	v_mul_f32_e32 v80, 0x3fb8aa3b, v80
	v_exp_f32_e32 v80, v80
	v_add_f32_e32 v93, v76, v93
	v_cndmask_b32_e32 v80, 0, v80, vcc
	v_cmp_lt_f32_e32 vcc, s25, v84
	v_sub_f32_e32 v84, v84, v91
	v_mul_f32_e32 v84, 0x3fb8aa3b, v84
	v_exp_f32_e32 v84, v84
	v_add_f32_e32 v93, v80, v93
	v_cndmask_b32_e32 v84, 0, v84, vcc
	v_cmp_lt_f32_e32 vcc, s25, v86
	v_sub_f32_e32 v86, v86, v91
	v_mul_f32_e32 v86, 0x3fb8aa3b, v86
	v_exp_f32_e32 v86, v86
	v_add_f32_e32 v93, v84, v93
	v_cndmask_b32_e32 v86, 0, v86, vcc
; DI float row16_sum(float v) { v += dppf<0xB1>(v); v += dppf<0x4E>(v); v += dppf<0x141>(v); v += dppf<0x140>(v); return v; }
; DI float row16_max(float v) { v = fmaxf(v, dppf<0xB1>(v)); v = fmaxf(v, dppf<0x4E>(v)); v = fmaxf(v, dppf<0x141>(v)); v = fmaxf(v, dppf<0x140>(v)); return v; }
; DI void attn_unit(const bf16_t* proj, bf16_t* ycat, const float* sinks, int b, int n, int kvh, LAS unsigned char* lds) {
;     ...
;         float den[4];
; #pragma unroll
;         for (int j = 0; j < 4; ++j) {
;             float m = mx[j];
;             m = row16_max(m);
;             m = fmaxf(m, sink); mx[j] = m;
;             float ssum = 0.f;
; #pragma unroll
;             for (int kt = 0; kt < 12; ++kt) { const float p = (sc[kt][j] > -1.0e38f) ? __expf(sc[kt][j] - m) : 0.f; sc[kt][j] = p; ssum += p; }
;             ssum = row16_sum(ssum);
;             den[j] = 1.0f / (ssum + __expf(sink - m));
;         }
	v_cmp_lt_f32_e32 vcc, s25, v92
	v_sub_f32_e32 v92, v92, v91
	v_mul_f32_e32 v92, 0x3fb8aa3b, v92
	v_exp_f32_e32 v92, v92
	v_add_f32_e32 v93, v86, v93
	v_cndmask_b32_e32 v92, 0, v92, vcc
	v_cmp_lt_f32_e32 vcc, s25, v38
	v_sub_f32_e32 v38, v38, v91
	v_mul_f32_e32 v38, 0x3fb8aa3b, v38
	v_exp_f32_e32 v38, v38
	v_add_f32_e32 v93, v92, v93
	v_cndmask_b32_e32 v38, 0, v38, vcc
	v_cmp_lt_f32_e32 vcc, s25, v34
	v_sub_f32_e32 v34, v34, v91
	v_mul_f32_e32 v34, 0x3fb8aa3b, v34
	v_exp_f32_e32 v34, v34
	v_add_f32_e32 v93, v38, v93
	v_cndmask_b32_e32 v34, 0, v34, vcc
	v_cmp_lt_f32_e32 vcc, s25, v30
	v_sub_f32_e32 v30, v30, v91
	v_mul_f32_e32 v30, 0x3fb8aa3b, v30
	v_exp_f32_e32 v30, v30
	v_add_f32_e32 v93, v34, v93
	v_cndmask_b32_e32 v30, 0, v30, vcc
	v_cmp_lt_f32_e32 vcc, s25, v26
	v_sub_f32_e32 v26, v26, v91
	v_mul_f32_e32 v26, 0x3fb8aa3b, v26
	v_exp_f32_e32 v26, v26
	v_add_f32_e32 v93, v30, v93
	v_cndmask_b32_e32 v26, 0, v26, vcc
	v_cmp_lt_f32_e32 vcc, s25, v22
	v_sub_f32_e32 v22, v22, v91
	v_mul_f32_e32 v22, 0x3fb8aa3b, v22
	v_exp_f32_e32 v22, v22
	v_add_f32_e32 v93, v26, v93
	v_cndmask_b32_e32 v22, 0, v22, vcc
	v_cmp_lt_f32_e32 vcc, s25, v18
	v_sub_f32_e32 v18, v18, v91
	v_mul_f32_e32 v18, 0x3fb8aa3b, v18
	v_exp_f32_e32 v18, v18
	v_add_f32_e32 v93, v22, v93
	v_sub_f32_e32 v91, v54, v91
	v_mul_f32_e32 v91, 0x3fb8aa3b, v91
	v_cndmask_b32_e32 v18, 0, v18, vcc
	v_add_f32_e32 v93, v18, v93
	v_exp_f32_e32 v91, v91
	s_nop 0
	v_add_f32_dpp v93, v93, v93 quad_perm:[1,0,3,2] row_mask:0xf bank_mask:0xf bound_ctrl:1
	s_nop 1
	v_add_f32_dpp v93, v93, v93 quad_perm:[2,3,0,1] row_mask:0xf bank_mask:0xf bound_ctrl:1
	s_nop 1
	v_add_f32_dpp v93, v93, v93 row_half_mirror row_mask:0xf bank_mask:0xf bound_ctrl:1
	s_nop 1
	v_add_f32_dpp v93, v93, v93 row_mirror row_mask:0xf bank_mask:0xf bound_ctrl:1
	v_add_f32_e32 v91, v91, v93
	v_div_scale_f32 v93, s[42:43], v91, v91, 1.0
	v_rcp_f32_e32 v95, v93
	s_nop 0
	v_fma_f32 v96, -v93, v95, 1.0
	v_fmac_f32_e32 v95, v96, v95
	v_div_scale_f32 v96, vcc, 1.0, v91, 1.0
	v_mul_f32_e32 v97, v96, v95
	v_fma_f32 v98, -v93, v97, v96
	v_fmac_f32_e32 v97, v98, v95
	v_fma_f32 v93, -v93, v97, v96
	v_div_fmas_f32 v93, v93, v95, v97
	v_div_fixup_f32 v91, v93, v91, 1.0
	v_cmp_lt_f32_e32 vcc, s25, v45
	v_mov_b32_dpp v93, v19 quad_perm:[1,0,3,2] row_mask:0xf bank_mask:0xf bound_ctrl:1
	v_max_f32_e32 v93, v93, v93
	v_max_f32_e32 v19, v19, v93
	v_mul_f32_e32 v38, v38, v91
	v_mul_f32_e32 v34, v34, v91
	v_mov_b32_dpp v93, v19 quad_perm:[2,3,0,1] row_mask:0xf bank_mask:0xf bound_ctrl:1
	v_max_f32_e32 v93, v93, v93
	v_max_f32_e32 v19, v19, v93
	v_mul_f32_e32 v30, v30, v91
	v_mul_f32_e32 v26, v26, v91
	v_mov_b32_dpp v93, v19 row_half_mirror row_mask:0xf bank_mask:0xf bound_ctrl:1
	v_max_f32_e32 v93, v93, v93
	v_max_f32_e32 v19, v19, v93
	v_mul_f32_e32 v22, v22, v91
	s_nop 0
	v_mov_b32_dpp v93, v19 row_mirror row_mask:0xf bank_mask:0xf bound_ctrl:1
	v_max3_f32 v19, v19, v93, v54
	v_sub_f32_e32 v45, v45, v19
	v_mul_f32_e32 v45, 0x3fb8aa3b, v45
	v_exp_f32_e32 v45, v45
	s_nop 0
	v_cndmask_b32_e32 v45, 0, v45, vcc
	v_cmp_lt_f32_e32 vcc, s25, v46
	v_sub_f32_e32 v46, v46, v19
	v_mul_f32_e32 v46, 0x3fb8aa3b, v46
	v_exp_f32_e32 v46, v46
	v_add_f32_e32 v93, 0, v45
	v_cndmask_b32_e32 v46, 0, v46, vcc
	v_cmp_lt_f32_e32 vcc, s25, v47
	v_sub_f32_e32 v47, v47, v19
	v_mul_f32_e32 v47, 0x3fb8aa3b, v47
	v_exp_f32_e32 v47, v47
	v_add_f32_e32 v93, v46, v93
	v_cndmask_b32_e32 v47, 0, v47, vcc
	v_cmp_lt_f32_e32 vcc, s25, v48
	v_sub_f32_e32 v48, v48, v19
	v_mul_f32_e32 v48, 0x3fb8aa3b, v48
	v_exp_f32_e32 v48, v48
	v_add_f32_e32 v93, v47, v93
	v_cndmask_b32_e32 v48, 0, v48, vcc
	v_cmp_lt_f32_e32 vcc, s25, v49
	v_sub_f32_e32 v49, v49, v19
	v_mul_f32_e32 v49, 0x3fb8aa3b, v49
	v_exp_f32_e32 v49, v49
	v_add_f32_e32 v93, v48, v93
	v_cndmask_b32_e32 v49, 0, v49, vcc
	v_cmp_lt_f32_e32 vcc, s25, v51
	v_sub_f32_e32 v51, v51, v19
	v_mul_f32_e32 v51, 0x3fb8aa3b, v51
	v_exp_f32_e32 v51, v51
	v_add_f32_e32 v93, v49, v93
	v_cndmask_b32_e32 v51, 0, v51, vcc
	v_cmp_lt_f32_e32 vcc, s25, v39
	v_sub_f32_e32 v39, v39, v19
	v_mul_f32_e32 v39, 0x3fb8aa3b, v39
	v_exp_f32_e32 v39, v39
	v_add_f32_e32 v93, v51, v93
	v_cndmask_b32_e32 v39, 0, v39, vcc
	v_cmp_lt_f32_e32 vcc, s25, v35
	v_sub_f32_e32 v35, v35, v19
	v_mul_f32_e32 v35, 0x3fb8aa3b, v35
	v_exp_f32_e32 v35, v35
	v_add_f32_e32 v93, v39, v93
	v_cndmask_b32_e32 v35, 0, v35, vcc
	v_cmp_lt_f32_e32 vcc, s25, v31
	v_sub_f32_e32 v31, v31, v19
	v_mul_f32_e32 v31, 0x3fb8aa3b, v31
	v_exp_f32_e32 v31, v31
	v_add_f32_e32 v93, v35, v93
	v_cndmask_b32_e32 v31, 0, v31, vcc
	v_cmp_lt_f32_e32 vcc, s25, v27
	v_sub_f32_e32 v27, v27, v19
	v_mul_f32_e32 v27, 0x3fb8aa3b, v27
	v_exp_f32_e32 v27, v27
	v_add_f32_e32 v93, v31, v93
	v_cndmask_b32_e32 v27, 0, v27, vcc
	v_cmp_lt_f32_e32 vcc, s25, v23
	v_sub_f32_e32 v23, v23, v19
	v_mul_f32_e32 v23, 0x3fb8aa3b, v23
	v_exp_f32_e32 v23, v23
	v_add_f32_e32 v93, v27, v93
	v_cndmask_b32_e32 v23, 0, v23, vcc
	v_cmp_lt_f32_e32 vcc, s25, v17
	v_sub_f32_e32 v17, v17, v19
	v_mul_f32_e32 v17, 0x3fb8aa3b, v17
	v_exp_f32_e32 v17, v17
	v_add_f32_e32 v93, v23, v93
	v_sub_f32_e32 v19, v54, v19
	v_mul_f32_e32 v19, 0x3fb8aa3b, v19
	v_cndmask_b32_e32 v17, 0, v17, vcc
	v_add_f32_e32 v93, v17, v93
	v_exp_f32_e32 v19, v19
	s_nop 0
	v_add_f32_dpp v93, v93, v93 quad_perm:[1,0,3,2] row_mask:0xf bank_mask:0xf bound_ctrl:1
	s_nop 1
	v_add_f32_dpp v93, v93, v93 quad_perm:[2,3,0,1] row_mask:0xf bank_mask:0xf bound_ctrl:1
	s_nop 1
	v_add_f32_dpp v93, v93, v93 row_half_mirror row_mask:0xf bank_mask:0xf bound_ctrl:1
	s_nop 1
	v_add_f32_dpp v93, v93, v93 row_mirror row_mask:0xf bank_mask:0xf bound_ctrl:1
	v_add_f32_e32 v19, v19, v93
; #define LAS __attribute__((address_space(3)))
; DI unsigned f2bf(float f) { unsigned u = __float_as_uint(f); u += 0x7FFFu + ((u >> 16) & 1u); return u >> 16; }
; DI void attn_unit(const bf16_t* proj, bf16_t* ycat, const float* sinks, int b, int n, int kvh, LAS unsigned char* lds) {
;     ...
;             den[j] = 1.0f / (ssum + __expf(sink - m));
;         }
; #pragma unroll
;         for (int kt = 0; kt < 12; ++kt)
; #pragma unroll
;             for (int j = 0; j < 4; ++j) *(LAS bf16_t*)(Ps + (fq * 4 + j) * 400 + (kt * 16 + fr) * 2) = (bf16_t)f2bf(sc[kt][j] * den[j]);
	v_div_scale_f32 v93, s[42:43], v19, v19, 1.0
	v_rcp_f32_e32 v95, v93
	s_nop 0
	v_fma_f32 v96, -v93, v95, 1.0
	v_fmac_f32_e32 v95, v96, v95
	v_div_scale_f32 v96, vcc, 1.0, v19, 1.0
	v_mul_f32_e32 v97, v96, v95
	v_fma_f32 v98, -v93, v97, v96
	v_fmac_f32_e32 v97, v98, v95
	v_fma_f32 v93, -v93, v97, v96
	v_div_fmas_f32 v93, v93, v95, v97
	v_div_fixup_f32 v19, v93, v19, 1.0
	v_bfe_u32 v93, v40, 16, 1
	v_add3_u32 v40, v40, v93, s68
	ds_write_b16_d16_hi v69, v40 offset:53248
	v_mul_f32_e32 v40, v88, v21
	v_bfe_u32 v88, v40, 16, 1
	v_add3_u32 v40, v40, v88, s68
	ds_write_b16_d16_hi v69, v40 offset:53648
	v_mul_f32_e32 v40, v50, v91
	v_cvt_pk_bf16_f32 v40, v40, v40
	ds_write_b16_d16_hi v69, v40 offset:54048
	v_mul_f32_e32 v40, v45, v19
	v_cvt_pk_bf16_f32 v40, v40, v40
	ds_write_b16_d16_hi v69, v40 offset:54448
	v_mul_f32_e32 v40, v77, v20
	v_cvt_pk_bf16_f32 v40, v40, v40
	ds_write_b16_d16_hi v69, v40 offset:53280
	v_mul_f32_e32 v40, v94, v21
	v_cvt_pk_bf16_f32 v40, v40, v40
	ds_write_b16_d16_hi v69, v40 offset:53680
	v_mul_f32_e32 v40, v76, v91
	v_cvt_pk_bf16_f32 v40, v40, v40
	ds_write_b16_d16_hi v69, v40 offset:54080
	v_mul_f32_e32 v40, v46, v19
	v_cvt_pk_bf16_f32 v40, v40, v40
	ds_write_b16_d16_hi v69, v40 offset:54480
	v_mul_f32_e32 v40, v78, v20
	v_cvt_pk_bf16_f32 v40, v40, v40
	ds_write_b16_d16_hi v69, v40 offset:53312
	v_mul_f32_e32 v40, v79, v21
	v_cvt_pk_bf16_f32 v40, v40, v40
	ds_write_b16_d16_hi v69, v40 offset:53712
	v_mul_f32_e32 v40, v80, v91
	v_cvt_pk_bf16_f32 v40, v40, v40
	ds_write_b16_d16_hi v69, v40 offset:54112
	v_mul_f32_e32 v40, v47, v19
	v_cvt_pk_bf16_f32 v40, v40, v40
	ds_write_b16_d16_hi v69, v40 offset:54512
	v_mul_f32_e32 v40, v82, v20
	v_cvt_pk_bf16_f32 v40, v40, v40
	ds_write_b16_d16_hi v69, v40 offset:53344
	v_mul_f32_e32 v40, v83, v21
	v_cvt_pk_bf16_f32 v40, v40, v40
	ds_write_b16_d16_hi v69, v40 offset:53744
	v_mul_f32_e32 v40, v84, v91
	v_cvt_pk_bf16_f32 v40, v40, v40
	ds_write_b16_d16_hi v69, v40 offset:54144
	v_mul_f32_e32 v40, v48, v19
	v_cvt_pk_bf16_f32 v40, v40, v40
	ds_write_b16_d16_hi v69, v40 offset:54544
	v_mul_f32_e32 v40, v81, v20
	v_cvt_pk_bf16_f32 v40, v40, v40
	ds_write_b16_d16_hi v69, v40 offset:53376
	v_mul_f32_e32 v40, v85, v21
	v_cvt_pk_bf16_f32 v40, v40, v40
	ds_write_b16_d16_hi v69, v40 offset:53776
	v_mul_f32_e32 v40, v86, v91
	v_cvt_pk_bf16_f32 v40, v40, v40
	ds_write_b16_d16_hi v69, v40 offset:54176
	v_mul_f32_e32 v40, v49, v19
	v_cvt_pk_bf16_f32 v40, v40, v40
	ds_write_b16_d16_hi v69, v40 offset:54576
	v_mul_f32_e32 v40, v87, v20
	v_cvt_pk_bf16_f32 v40, v40, v40
	ds_write_b16_d16_hi v69, v40 offset:53408
	v_mul_f32_e32 v40, v90, v21
	v_cvt_pk_bf16_f32 v40, v40, v40
	ds_write_b16_d16_hi v69, v40 offset:53808
	v_mul_f32_e32 v40, v92, v91
	v_cvt_pk_bf16_f32 v40, v40, v40
	ds_write_b16_d16_hi v69, v40 offset:54208
	v_mul_f32_e32 v40, v51, v19
	v_cvt_pk_bf16_f32 v40, v40, v40
	ds_write_b16_d16_hi v69, v40 offset:54608
	v_mul_f32_e32 v40, v74, v20
	v_cvt_pk_bf16_f32 v40, v40, v40
	ds_write_b16_d16_hi v69, v40 offset:53440
	v_mul_f32_e32 v40, v75, v21
	v_cvt_pk_bf16_f32 v40, v40, v40
	ds_write_b16_d16_hi v69, v40 offset:53840
	v_cvt_pk_bf16_f32 v38, v38, v38
	ds_write_b16_d16_hi v69, v38 offset:54240
	v_mul_f32_e32 v38, v39, v19
	v_cvt_pk_bf16_f32 v38, v38, v38
	ds_write_b16_d16_hi v69, v38 offset:54640
	v_cvt_pk_bf16_f32 v36, v36, v36
	ds_write_b16_d16_hi v69, v36 offset:53472
	v_mul_f32_e32 v36, v89, v21
	v_cvt_pk_bf16_f32 v36, v36, v36
	ds_write_b16_d16_hi v69, v36 offset:53872
	v_cvt_pk_bf16_f32 v34, v34, v34
	ds_write_b16_d16_hi v69, v34 offset:54272
	v_mul_f32_e32 v34, v35, v19
	v_cvt_pk_bf16_f32 v34, v34, v34
	ds_write_b16_d16_hi v69, v34 offset:54672
	v_cvt_pk_bf16_f32 v32, v32, v32
	ds_write_b16_d16_hi v69, v32 offset:53504
	v_mul_f32_e32 v32, v33, v21
	v_cvt_pk_bf16_f32 v32, v32, v32
	ds_write_b16_d16_hi v69, v32 offset:53904
	v_cvt_pk_bf16_f32 v30, v30, v30
	ds_write_b16_d16_hi v69, v30 offset:54304
	v_mul_f32_e32 v30, v31, v19
	v_cvt_pk_bf16_f32 v30, v30, v30
	ds_write_b16_d16_hi v69, v30 offset:54704
	v_cvt_pk_bf16_f32 v28, v28, v28
	ds_write_b16_d16_hi v69, v28 offset:53536
	v_mul_f32_e32 v28, v37, v21
	v_cvt_pk_bf16_f32 v28, v28, v28
	ds_write_b16_d16_hi v69, v28 offset:53936
	v_cvt_pk_bf16_f32 v26, v26, v26
	ds_write_b16_d16_hi v69, v26 offset:54336
	v_mul_f32_e32 v26, v27, v19
	v_cvt_pk_bf16_f32 v26, v26, v26
	ds_write_b16_d16_hi v69, v26 offset:54736
	v_cvt_pk_bf16_f32 v16, v16, v16
	v_cvt_pk_bf16_f32 v24, v24, v24
	ds_write_b16_d16_hi v69, v16 offset:53600
	v_mul_f32_e32 v16, v29, v21
	ds_write_b16_d16_hi v69, v24 offset:53568
	v_mul_f32_e32 v24, v25, v21
	v_cvt_pk_bf16_f32 v16, v16, v16
	v_cvt_pk_bf16_f32 v24, v24, v24
	ds_write_b16_d16_hi v69, v16 offset:54000
	v_mul_f32_e32 v16, v18, v91
	ds_write_b16_d16_hi v69, v24 offset:53968
	v_cvt_pk_bf16_f32 v22, v22, v22
	v_cvt_pk_bf16_f32 v16, v16, v16
	ds_write_b16_d16_hi v69, v22 offset:54368
	v_mul_f32_e32 v22, v23, v19
	ds_write_b16_d16_hi v69, v16 offset:54400
	v_mul_f32_e32 v16, v17, v19
	v_cvt_pk_bf16_f32 v22, v22, v22
	v_cvt_pk_bf16_f32 v16, v16, v16
	ds_write_b16_d16_hi v69, v22 offset:54768
	ds_write_b16_d16_hi v69, v16 offset:54800
	s_waitcnt lgkmcnt(0)
	s_barrier
; DI unsigned f2bf(float f) { unsigned u = __float_as_uint(f); u += 0x7FFFu + ((u >> 16) & 1u); return u >> 16; }
; #define MFMA16(a, b, c) __builtin_amdgcn_mfma_f32_16x16x32_bf16((a), (b), (c), 0, 0, 0)
; DI void attn_unit(const bf16_t* proj, bf16_t* ycat, const float* sinks, int b, int n, int kvh, LAS unsigned char* lds) {
;     ...
;         __syncthreads();
; #pragma unroll
;         for (int dt = 0; dt < 4; ++dt) {
;             f32x4 o = (f32x4){0.f, 0.f, 0.f, 0.f};
; #pragma unroll
;             for (int ks = 0; ks < 6; ++ks)
;                 o = MFMA16(ldsfrag(Ps + fr * 400 + (ks * 32 + fq * 8) * 2), ldsfrag(lds + VT_OFF + (dt * 16 + fr) * 400 + (ks * 32 + fq * 8) * 2), o);
; #pragma unroll
;             for (int j = 0; j < 4; ++j)
;                 ycat[(size_t)(b * SEQ_ + n * 64 + c0 + fq * 4 + j) * D_ + hh * 64 + dt * 16 + fr] = (bf16_t)f2bf(o[j]);
;         }
;         __syncthreads();
;     }
	ds_read_b128 v[36:39], v70 offset:53248
	ds_read_b128 v[16:19], v71 offset:27648
	ds_read_b128 v[32:35], v70 offset:53312
	ds_read_b128 v[20:23], v71 offset:27712
	s_waitcnt lgkmcnt(2)
	v_mfma_f32_16x16x32_bf16 v[16:19], v[36:39], v[16:19], 0
	v_or_b32_e32 v74, v56, v44
	v_ashrrev_i32_e32 v75, 31, v74
	s_and_b64 vcc, exec, s[0:1]
	s_waitcnt lgkmcnt(0)
	v_mfma_f32_16x16x32_bf16 v[16:19], v[32:35], v[20:23], v[16:19]
	ds_read_b128 v[20:23], v70 offset:53376
	ds_read_b128 v[24:27], v71 offset:27776
	s_mov_b64 s[0:1], 0
	s_waitcnt lgkmcnt(0)
	v_mfma_f32_16x16x32_bf16 v[24:27], v[20:23], v[24:27], v[16:19]
	s_nop 2
	ds_read_b128 v[16:19], v70 offset:53440
	ds_read_b128 v[28:31], v71 offset:27840
	s_waitcnt lgkmcnt(0)
	v_mfma_f32_16x16x32_bf16 v[28:31], v[16:19], v[28:31], v[24:27]
	s_nop 2
	ds_read_b128 v[24:27], v70 offset:53504
	ds_read_b128 v[44:47], v71 offset:27904
	s_waitcnt lgkmcnt(0)
	v_mfma_f32_16x16x32_bf16 v[44:47], v[24:27], v[44:47], v[28:31]
	s_nop 2
	ds_read_b128 v[28:31], v70 offset:53568
	ds_read_b128 v[48:51], v71 offset:27968
	s_waitcnt lgkmcnt(0)
	v_mfma_f32_16x16x32_bf16 v[48:51], v[28:31], v[48:51], v[44:47]
	s_nop 2
	v_lshlrev_b64 v[44:45], 11, v[74:75]
	v_or_b32_e32 v46, 1, v74
	s_nop 2
	s_nop 0
	v_cvt_pk_bf16_f32 v40, v48, v48
	v_lshl_add_u64 v[44:45], v[42:43], 0, v[44:45]
	v_ashrrev_i32_e32 v47, 31, v46
	global_store_short_d16_hi v[44:45], v40, off
	s_nop 0
	v_lshlrev_b64 v[46:47], 11, v[46:47]
	v_or_b32_e32 v48, 2, v74
	v_cvt_pk_bf16_f32 v40, v49, v49
	v_lshl_add_u64 v[46:47], v[42:43], 0, v[46:47]
	v_ashrrev_i32_e32 v49, 31, v48
	global_store_short_d16_hi v[46:47], v40, off
	s_nop 0
	v_lshlrev_b64 v[48:49], 11, v[48:49]
	v_cvt_pk_bf16_f32 v40, v50, v50
	v_lshl_add_u64 v[48:49], v[42:43], 0, v[48:49]
	global_store_short_d16_hi v[48:49], v40, off
	s_nop 0
	v_or_b32_e32 v50, 3, v74
	v_cvt_pk_bf16_f32 v40, v51, v51
	v_ashrrev_i32_e32 v51, 31, v50
	v_lshlrev_b64 v[50:51], 11, v[50:51]
	v_lshl_add_u64 v[50:51], v[42:43], 0, v[50:51]
	global_store_short_d16_hi v[50:51], v40, off
	v_add_u32_e32 v40, v67, v136
	ds_read_b128 v[74:77], v40 offset:27648
	ds_read_b128 v[78:81], v40 offset:27712
	s_waitcnt lgkmcnt(1)
	v_mfma_f32_16x16x32_bf16 v[74:77], v[36:39], v[74:77], 0
	s_waitcnt lgkmcnt(0)
	v_mfma_f32_16x16x32_bf16 v[74:77], v[32:35], v[78:81], v[74:77]
	ds_read_b128 v[78:81], v40 offset:27776
	s_waitcnt lgkmcnt(0)
	v_mfma_f32_16x16x32_bf16 v[74:77], v[20:23], v[78:81], v[74:77]
	ds_read_b128 v[78:81], v40 offset:27840
	s_waitcnt lgkmcnt(0)
	v_mfma_f32_16x16x32_bf16 v[74:77], v[16:19], v[78:81], v[74:77]
	ds_read_b128 v[78:81], v40 offset:27904
	s_waitcnt lgkmcnt(0)
	v_mfma_f32_16x16x32_bf16 v[74:77], v[24:27], v[78:81], v[74:77]
	ds_read_b128 v[78:81], v40 offset:27968
	s_waitcnt lgkmcnt(0)
	v_mfma_f32_16x16x32_bf16 v[74:77], v[28:31], v[78:81], v[74:77]
	ds_read_b128 v[78:81], v72 offset:27712
	s_nop 6
	s_nop 0
	v_cvt_pk_bf16_f32 v40, v74, v74
	global_store_short_d16_hi v[44:45], v40, off offset:32
	s_nop 0
	v_cvt_pk_bf16_f32 v40, v75, v75
	global_store_short_d16_hi v[46:47], v40, off offset:32
	s_nop 0
	v_cvt_pk_bf16_f32 v40, v76, v76
	global_store_short_d16_hi v[48:49], v40, off offset:32
	s_nop 0
	v_cvt_pk_bf16_f32 v40, v77, v77
	ds_read_b128 v[74:77], v72 offset:27648
	s_waitcnt lgkmcnt(0)
	v_mfma_f32_16x16x32_bf16 v[74:77], v[36:39], v[74:77], 0
	global_store_short_d16_hi v[50:51], v40, off offset:32
	v_mfma_f32_16x16x32_bf16 v[74:77], v[32:35], v[78:81], v[74:77]
	ds_read_b128 v[78:81], v72 offset:27776
	s_waitcnt lgkmcnt(0)
	v_mfma_f32_16x16x32_bf16 v[74:77], v[20:23], v[78:81], v[74:77]
	ds_read_b128 v[78:81], v72 offset:27840
	s_waitcnt lgkmcnt(0)
	v_mfma_f32_16x16x32_bf16 v[74:77], v[16:19], v[78:81], v[74:77]
	ds_read_b128 v[78:81], v72 offset:27904
	s_waitcnt lgkmcnt(0)
	v_mfma_f32_16x16x32_bf16 v[74:77], v[24:27], v[78:81], v[74:77]
	ds_read_b128 v[78:81], v72 offset:27968
	s_waitcnt lgkmcnt(0)
	v_mfma_f32_16x16x32_bf16 v[74:77], v[28:31], v[78:81], v[74:77]
	s_nop 7
	s_nop 0
	v_cvt_pk_bf16_f32 v40, v74, v74
	global_store_short_d16_hi v[44:45], v40, off offset:64
	s_nop 0
	v_cvt_pk_bf16_f32 v40, v75, v75
	global_store_short_d16_hi v[46:47], v40, off offset:64
	s_nop 0
	v_cvt_pk_bf16_f32 v40, v76, v76
	global_store_short_d16_hi v[48:49], v40, off offset:64
	s_nop 0
	v_cvt_pk_bf16_f32 v40, v77, v77
	ds_read_b128 v[74:77], v73 offset:27648
	s_waitcnt lgkmcnt(0)
	v_mfma_f32_16x16x32_bf16 v[36:39], v[36:39], v[74:77], 0
	ds_read_b128 v[74:77], v73 offset:27712
	global_store_short_d16_hi v[50:51], v40, off offset:64
	s_waitcnt lgkmcnt(0)
	v_mfma_f32_16x16x32_bf16 v[32:35], v[32:35], v[74:77], v[36:39]
	s_nop 3
	ds_read_b128 v[36:39], v73 offset:27776
	s_waitcnt lgkmcnt(0)
	v_mfma_f32_16x16x32_bf16 v[20:23], v[20:23], v[36:39], v[32:35]
	s_nop 2
	ds_read_b128 v[32:35], v73 offset:27840
	s_waitcnt lgkmcnt(0)
	v_mfma_f32_16x16x32_bf16 v[16:19], v[16:19], v[32:35], v[20:23]
	s_nop 2
	ds_read_b128 v[20:23], v73 offset:27904
	s_waitcnt lgkmcnt(0)
	v_mfma_f32_16x16x32_bf16 v[16:19], v[24:27], v[20:23], v[16:19]
	ds_read_b128 v[20:23], v73 offset:27968
	s_waitcnt lgkmcnt(0)
	v_mfma_f32_16x16x32_bf16 v[16:19], v[28:31], v[20:23], v[16:19]
	s_nop 7
	v_bfe_u32 v20, v16, 16, 1
	v_add3_u32 v16, v16, v20, s68
	global_store_short_d16_hi v[44:45], v16, off offset:96
	s_nop 0
	v_cvt_pk_bf16_f32 v16, v17, v17
	global_store_short_d16_hi v[46:47], v16, off offset:96
	s_nop 0
	v_cvt_pk_bf16_f32 v16, v18, v18
	global_store_short_d16_hi v[48:49], v16, off offset:96
	s_nop 0
	v_cvt_pk_bf16_f32 v16, v19, v19
	global_store_short_d16_hi v[50:51], v16, off offset:96
	s_barrier
	s_cbranch_vccnz .LBB0_251
	s_add_i32 s40, s40, s50
	s_cmpk_gt_i32 s40, 0x7ff
	s_movk_i32 s37, 0x90
	s_cbranch_scc0 .LBB0_244

; DI unsigned f2bf(float f) { unsigned u = __float_as_uint(f); u += 0x7FFFu + ((u >> 16) & 1u); return u >> 16; }
; DI float bf2f(unsigned b) { return __uint_as_float(b << 16); }
; DI float gelu_tanh(float x) { const float u = 0.7978845608028654f * (x + 0.044715f * x * x * x); const float e = __expf(-2.0f * fabsf(u)); const float t = (1.0f - e) / (1.0f + e); return 0.5f * x * (1.0f + (u < 0.f ? -t : t)); }
; DI void rglru_unit(const Params& P, const bf16_t* proj, bf16_t* ycat, int b, int hb, LAS unsigned char* lds) {
;     ...
; #pragma unroll
;         for (int i = 0; i < 8; ++i) {
;             const int tok = tg * 8 + i;
;             const float y = UU[tok * 64 + ch] * gelu_tanh(bf2f(bgr[i]));
;             ycat[(size_t)(t0 + tok) * D_ + 512 + hb * 64 + ch] = (bf16_t)f2bf(y);
;         }
.LBB0_298:
	s_or_b64 exec, exec, s[0:1]
	v_lshlrev_b32_e32 v1, 16, v35
	v_lshlrev_b32_e32 v0, 16, v34
	s_mov_b32 s10, 0x3d372713
	v_pk_mul_f32 v[2:3], v[0:1], s[10:11] op_sel_hi:[1,0]
	s_mov_b32 s12, 0x3f4c422a
	v_pk_mul_f32 v[2:3], v[2:3], v[0:1]
	s_waitcnt lgkmcnt(0)
	s_barrier
	v_pk_fma_f32 v[2:3], v[2:3], v[0:1], v[0:1]
	v_mul_f32_e32 v1, 0.5, v1
	v_pk_mul_f32 v[2:3], v[2:3], s[12:13] op_sel_hi:[1,0]
	v_mul_f32_e32 v0, 0.5, v0
	v_mul_f32_e64 v4, |v3|, -2.0
	v_mul_f32_e32 v4, 0x3fb8aa3b, v4
	v_exp_f32_e32 v5, v4
	v_add_u32_e32 v4, s9, v47
	s_add_i32 s7, s7, 1
	s_cmp_lg_u32 s7, 32
	v_sub_f32_e32 v6, 1.0, v5
	v_add_f32_e32 v7, 1.0, v5
	v_div_scale_f32 v8, s[0:1], v7, v7, v6
	v_rcp_f32_e32 v9, v8
	v_ashrrev_i32_e32 v5, 31, v4
	v_lshlrev_b64 v[4:5], 11, v[4:5]
	v_lshl_add_u64 v[4:5], v[16:17], 0, v[4:5]
	v_fma_f32 v10, -v8, v9, 1.0
	v_fmac_f32_e32 v9, v10, v9
	v_div_scale_f32 v10, vcc, v6, v7, v6
	v_mul_f32_e32 v11, v10, v9
	v_fma_f32 v12, -v8, v11, v10
	v_fmac_f32_e32 v11, v12, v9
	v_fma_f32 v8, -v8, v11, v10
	v_div_fmas_f32 v8, v8, v9, v11
	v_div_fixup_f32 v6, v8, v7, v6
	v_cmp_gt_f32_e32 vcc, 0, v3
	s_waitcnt vmcnt(8)
	v_mov_b32_e32 v85, v84
	v_cndmask_b32_e64 v3, v6, -v6, vcc
	v_add_f32_e32 v3, 1.0, v3
	v_mul_f32_e32 v1, v1, v3
	v_mul_f32_e64 v3, |v2|, -2.0
	v_mul_f32_e32 v3, 0x3fb8aa3b, v3
	v_exp_f32_e32 v3, v3
	ds_read_b32 v6, v66 offset:60416
	ds_read_b32 v7, v67 offset:60416
	ds_read_b32 v8, v68 offset:60416
	ds_read_b32 v9, v69 offset:60416
	ds_read_b32 v10, v70 offset:60416
	ds_read_b32 v11, v71 offset:60416
	ds_read_b32 v12, v72 offset:60416
	ds_read_b32 v13, v73 offset:60416
	s_waitcnt lgkmcnt(7)
	v_mul_f32_e32 v1, v1, v6
	s_nop 0
	v_sub_f32_e32 v6, 1.0, v3
	v_add_f32_e32 v3, 1.0, v3
	v_div_scale_f32 v14, s[0:1], v3, v3, v6
	v_rcp_f32_e32 v15, v14
	v_cvt_pk_bf16_f32 v1, v1, v1
	global_store_short_d16_hi v[4:5], v1, off offset:1024
	v_fma_f32 v1, -v14, v15, 1.0
	v_fmac_f32_e32 v15, v1, v15
	v_div_scale_f32 v1, vcc, v6, v3, v6
	v_mul_f32_e32 v4, v1, v15
	v_fma_f32 v5, -v14, v4, v1
	v_fmac_f32_e32 v4, v5, v15
	v_fma_f32 v1, -v14, v4, v1
	v_div_fmas_f32 v1, v1, v15, v4
	v_div_fixup_f32 v1, v1, v3, v6
	v_cmp_gt_f32_e32 vcc, 0, v2
	v_lshlrev_b32_e32 v3, 16, v31
	v_lshlrev_b32_e32 v2, 16, v30
	v_pk_mul_f32 v[4:5], v[2:3], s[10:11] op_sel_hi:[1,0]
	v_cndmask_b32_e64 v1, v1, -v1, vcc
	v_pk_mul_f32 v[4:5], v[4:5], v[2:3]
	v_add_f32_e32 v1, 1.0, v1
	v_pk_fma_f32 v[4:5], v[4:5], v[2:3], v[2:3]
	v_mul_f32_e32 v0, v0, v1
	v_pk_mul_f32 v[4:5], v[4:5], s[12:13] op_sel_hi:[1,0]
	s_waitcnt lgkmcnt(6)
	v_mul_f32_e32 v0, v0, v7
	v_mul_f32_e64 v7, |v5|, -2.0
	s_nop 0
	v_mul_f32_e32 v7, 0x3fb8aa3b, v7
	v_cvt_pk_bf16_f32 v6, v0, v0
	v_add_u32_e32 v0, s9, v48
	v_exp_f32_e32 v7, v7
	v_ashrrev_i32_e32 v1, 31, v0
	v_lshlrev_b64 v[0:1], 11, v[0:1]
	v_lshl_add_u64 v[0:1], v[16:17], 0, v[0:1]
	global_store_short_d16_hi v[0:1], v6, off offset:1024
	v_sub_f32_e32 v6, 1.0, v7
	v_add_f32_e32 v7, 1.0, v7
	v_div_scale_f32 v14, s[0:1], v7, v7, v6
	v_rcp_f32_e32 v15, v14
	v_mul_f32_e32 v3, 0.5, v3
	v_add_u32_e32 v0, s9, v49
	v_ashrrev_i32_e32 v1, 31, v0
	v_fma_f32 v30, -v14, v15, 1.0
	v_fmac_f32_e32 v15, v30, v15
	v_div_scale_f32 v30, vcc, v6, v7, v6
	v_mul_f32_e32 v31, v30, v15
	v_fma_f32 v34, -v14, v31, v30
	v_fmac_f32_e32 v31, v34, v15
	v_fma_f32 v14, -v14, v31, v30
	v_div_fmas_f32 v14, v14, v15, v31
	v_div_fixup_f32 v6, v14, v7, v6
	v_cmp_gt_f32_e32 vcc, 0, v5
	v_lshlrev_b64 v[0:1], 11, v[0:1]
	v_lshl_add_u64 v[0:1], v[16:17], 0, v[0:1]
	v_cndmask_b32_e64 v5, v6, -v6, vcc
	v_mul_f32_e64 v6, |v4|, -2.0
	v_mul_f32_e32 v6, 0x3fb8aa3b, v6
	v_exp_f32_e32 v6, v6
	v_add_f32_e32 v5, 1.0, v5
	v_mul_f32_e32 v3, v3, v5
	s_waitcnt lgkmcnt(5)
	v_mul_f32_e32 v3, v3, v8
	v_sub_f32_e32 v5, 1.0, v6
	v_add_f32_e32 v6, 1.0, v6
	v_div_scale_f32 v7, s[0:1], v6, v6, v5
	v_rcp_f32_e32 v8, v7
	s_nop 0
	v_cvt_pk_bf16_f32 v3, v3, v3
	global_store_short_d16_hi v[0:1], v3, off offset:1024
	v_fma_f32 v0, -v7, v8, 1.0
	v_fmac_f32_e32 v8, v0, v8
	v_div_scale_f32 v0, vcc, v5, v6, v5
	v_mul_f32_e32 v1, v0, v8
	v_fma_f32 v3, -v7, v1, v0
	v_fmac_f32_e32 v1, v3, v8
	v_fma_f32 v0, -v7, v1, v0
	v_div_fmas_f32 v0, v0, v8, v1
	v_mul_f32_e32 v1, 0.5, v2
	v_lshlrev_b32_e32 v3, 16, v23
	v_lshlrev_b32_e32 v2, 16, v22
	v_div_fixup_f32 v0, v0, v6, v5
	v_cmp_gt_f32_e32 vcc, 0, v4
	v_pk_mul_f32 v[4:5], v[2:3], s[10:11] op_sel_hi:[1,0]
	s_waitcnt vmcnt(7)
	v_mov_b64_e32 v[30:31], v[26:27]
	v_cndmask_b32_e64 v0, v0, -v0, vcc
	v_pk_mul_f32 v[4:5], v[4:5], v[2:3]
	v_add_f32_e32 v0, 1.0, v0
	v_pk_fma_f32 v[4:5], v[4:5], v[2:3], v[2:3]
	v_mul_f32_e32 v0, v1, v0
	v_pk_mul_f32 v[4:5], v[4:5], s[12:13] op_sel_hi:[1,0]
	s_waitcnt lgkmcnt(4)
; DI unsigned f2bf(float f) { unsigned u = __float_as_uint(f); u += 0x7FFFu + ((u >> 16) & 1u); return u >> 16; }
; DI float bf2f(unsigned b) { return __uint_as_float(b << 16); }
; DI float gelu_tanh(float x) { const float u = 0.7978845608028654f * (x + 0.044715f * x * x * x); const float e = __expf(-2.0f * fabsf(u)); const float t = (1.0f - e) / (1.0f + e); return 0.5f * x * (1.0f + (u < 0.f ? -t : t)); }
; DI void rglru_unit(const Params& P, const bf16_t* proj, bf16_t* ycat, int b, int hb, LAS unsigned char* lds) {
;     ...
; #pragma unroll
;         for (int i = 0; i < 8; ++i) {
;             const int tok = tg * 8 + i;
;             const float y = UU[tok * 64 + ch] * gelu_tanh(bf2f(bgr[i]));
;             ycat[(size_t)(t0 + tok) * D_ + 512 + hb * 64 + ch] = (bf16_t)f2bf(y);
;         }
	v_mul_f32_e32 v0, v0, v9
	v_mul_f32_e64 v7, |v5|, -2.0
	s_nop 0
	v_mul_f32_e32 v7, 0x3fb8aa3b, v7
	v_cvt_pk_bf16_f32 v6, v0, v0
	v_add_u32_e32 v0, s9, v50
	v_exp_f32_e32 v7, v7
	v_ashrrev_i32_e32 v1, 31, v0
	v_lshlrev_b64 v[0:1], 11, v[0:1]
	v_lshl_add_u64 v[0:1], v[16:17], 0, v[0:1]
	global_store_short_d16_hi v[0:1], v6, off offset:1024
	v_sub_f32_e32 v6, 1.0, v7
	v_add_f32_e32 v7, 1.0, v7
	v_div_scale_f32 v8, s[0:1], v7, v7, v6
	v_rcp_f32_e32 v9, v8
	v_mul_f32_e32 v3, 0.5, v3
	v_add_u32_e32 v0, s9, v51
	v_ashrrev_i32_e32 v1, 31, v0
	v_fma_f32 v14, -v8, v9, 1.0
	v_fmac_f32_e32 v9, v14, v9
	v_div_scale_f32 v14, vcc, v6, v7, v6
	v_mul_f32_e32 v15, v14, v9
	v_fma_f32 v22, -v8, v15, v14
	v_fmac_f32_e32 v15, v22, v9
	v_fma_f32 v8, -v8, v15, v14
	v_div_fmas_f32 v8, v8, v9, v15
	v_div_fixup_f32 v6, v8, v7, v6
	v_cmp_gt_f32_e32 vcc, 0, v5
	v_lshlrev_b64 v[0:1], 11, v[0:1]
	v_lshl_add_u64 v[0:1], v[16:17], 0, v[0:1]
	v_cndmask_b32_e64 v5, v6, -v6, vcc
	v_mul_f32_e64 v6, |v4|, -2.0
	v_mul_f32_e32 v6, 0x3fb8aa3b, v6
	v_exp_f32_e32 v6, v6
	v_add_f32_e32 v5, 1.0, v5
	v_mul_f32_e32 v3, v3, v5
	s_waitcnt lgkmcnt(3)
	v_mul_f32_e32 v3, v3, v10
	v_sub_f32_e32 v5, 1.0, v6
	v_add_f32_e32 v6, 1.0, v6
	v_div_scale_f32 v7, s[0:1], v6, v6, v5
	v_rcp_f32_e32 v8, v7
	s_nop 0
	v_cvt_pk_bf16_f32 v3, v3, v3
	global_store_short_d16_hi v[0:1], v3, off offset:1024
	v_fma_f32 v0, -v7, v8, 1.0
	v_fmac_f32_e32 v8, v0, v8
	v_div_scale_f32 v0, vcc, v5, v6, v5
	v_mul_f32_e32 v1, v0, v8
	v_fma_f32 v3, -v7, v1, v0
	v_fmac_f32_e32 v1, v3, v8
	v_fma_f32 v0, -v7, v1, v0
	v_div_fmas_f32 v0, v0, v8, v1
	v_mul_f32_e32 v1, 0.5, v2
	v_lshlrev_b32_e32 v3, 16, v21
	v_lshlrev_b32_e32 v2, 16, v20
	v_div_fixup_f32 v0, v0, v6, v5
	v_cmp_gt_f32_e32 vcc, 0, v4
	v_pk_mul_f32 v[4:5], v[2:3], s[10:11] op_sel_hi:[1,0]
	v_mov_b32_e32 v15, v82
	v_cndmask_b32_e64 v0, v0, -v0, vcc
	v_pk_mul_f32 v[4:5], v[4:5], v[2:3]
	v_add_f32_e32 v0, 1.0, v0
	v_pk_fma_f32 v[4:5], v[4:5], v[2:3], v[2:3]
	v_mul_f32_e32 v0, v1, v0
	v_pk_mul_f32 v[4:5], v[4:5], s[12:13] op_sel_hi:[1,0]
	s_waitcnt lgkmcnt(2)
	v_mul_f32_e32 v0, v0, v11
	v_mul_f32_e64 v7, |v5|, -2.0
	s_nop 0
	v_mul_f32_e32 v7, 0x3fb8aa3b, v7
	v_cvt_pk_bf16_f32 v6, v0, v0
	v_add_u32_e32 v0, s9, v52
	v_exp_f32_e32 v7, v7
	v_ashrrev_i32_e32 v1, 31, v0
	v_lshlrev_b64 v[0:1], 11, v[0:1]
	v_lshl_add_u64 v[0:1], v[16:17], 0, v[0:1]
	global_store_short_d16_hi v[0:1], v6, off offset:1024
	v_sub_f32_e32 v6, 1.0, v7
	v_add_f32_e32 v7, 1.0, v7
	v_div_scale_f32 v8, s[0:1], v7, v7, v6
	v_rcp_f32_e32 v9, v8
	v_mul_f32_e32 v3, 0.5, v3
	v_add_u32_e32 v0, s9, v53
	v_ashrrev_i32_e32 v1, 31, v0
	v_fma_f32 v10, -v8, v9, 1.0
	v_fmac_f32_e32 v9, v10, v9
	v_div_scale_f32 v10, vcc, v6, v7, v6
	v_mul_f32_e32 v11, v10, v9
	v_fma_f32 v14, -v8, v11, v10
	v_fmac_f32_e32 v11, v14, v9
	v_fma_f32 v8, -v8, v11, v10
	v_div_fmas_f32 v8, v8, v9, v11
	v_div_fixup_f32 v6, v8, v7, v6
	v_cmp_gt_f32_e32 vcc, 0, v5
	v_lshlrev_b64 v[0:1], 11, v[0:1]
	v_lshl_add_u64 v[0:1], v[16:17], 0, v[0:1]
	v_cndmask_b32_e64 v5, v6, -v6, vcc
	v_mul_f32_e64 v6, |v4|, -2.0
	v_mul_f32_e32 v6, 0x3fb8aa3b, v6
	v_exp_f32_e32 v6, v6
	v_add_f32_e32 v5, 1.0, v5
	v_mul_f32_e32 v3, v3, v5
	s_waitcnt lgkmcnt(1)
	v_mul_f32_e32 v3, v3, v12
	v_sub_f32_e32 v5, 1.0, v6
	v_add_f32_e32 v6, 1.0, v6
	v_div_scale_f32 v7, s[0:1], v6, v6, v5
	v_rcp_f32_e32 v8, v7
	v_bfe_u32 v9, v3, 16, 1
	v_add3_u32 v3, v3, v9, s68
	global_store_short_d16_hi v[0:1], v3, off offset:1024
	v_fma_f32 v0, -v7, v8, 1.0
	v_fmac_f32_e32 v8, v0, v8
	v_div_scale_f32 v0, vcc, v5, v6, v5
	v_mul_f32_e32 v1, v0, v8
	v_fma_f32 v3, -v7, v1, v0
	v_fmac_f32_e32 v1, v3, v8
	v_fma_f32 v0, -v7, v1, v0
	v_div_fmas_f32 v0, v0, v8, v1
	v_div_fixup_f32 v0, v0, v6, v5
	v_cmp_gt_f32_e32 vcc, 0, v4
	v_mul_f32_e32 v1, 0.5, v2
	v_mov_b32_e32 v3, v74
	v_cndmask_b32_e64 v0, v0, -v0, vcc
	v_add_f32_e32 v0, 1.0, v0
	v_mul_f32_e32 v0, v1, v0
	s_waitcnt lgkmcnt(0)
	v_mul_f32_e32 v0, v0, v13
	v_cvt_pk_bf16_f32 v2, v0, v0
	v_add_u32_e32 v0, s9, v54
	v_ashrrev_i32_e32 v1, 31, v0
	v_lshlrev_b64 v[0:1], 11, v[0:1]
	v_lshl_add_u64 v[0:1], v[16:17], 0, v[0:1]
	global_store_short_d16_hi v[0:1], v2, off offset:1024
	v_mov_b32_e32 v1, v75
	v_mov_b32_e32 v6, v76
	v_mov_b32_e32 v5, v77
	v_mov_b32_e32 v11, v78
	v_mov_b32_e32 v10, v79
	v_mov_b32_e32 v13, v80
	v_mov_b32_e32 v12, v81
	v_mov_b32_e32 v14, v83
	s_waitcnt vmcnt(8)
	v_mov_b64_e32 v[20:21], v[32:33]
	v_mov_b64_e32 v[22:23], v[28:29]
	v_mov_b64_e32 v[34:35], v[24:25]
	s_cbranch_scc0 .LBB0_262

; #define LAS __attribute__((address_space(3)))
; DI unsigned f2bf(float f) { unsigned u = __float_as_uint(f); u += 0x7FFFu + ((u >> 16) & 1u); return u >> 16; }
; DI float sigmoidf_(float x) { return __builtin_amdgcn_rcpf(1.0f + __expf(-x)); }
; DI float expm1_neg(float y) { return y > -0.03125f ? y * (1.0f + 0.5f * y * (1.0f + 0.33333334f * y * (1.0f + 0.25f * y))) : __expf(y) - 1.0f; }
; DI void lds_barrier() { asm volatile("s_waitcnt lgkmcnt(0)" ::: "memory"); __builtin_amdgcn_s_barrier(); asm volatile("" ::: "memory"); }
; #define MFMA16(a, b, c) __builtin_amdgcn_mfma_f32_16x16x32_bf16((a), (b), (c), 0, 0, 0)
; DI void rglru_unit(const Params& P, const bf16_t* proj, bf16_t* ycat, int b, int hb, LAS unsigned char* lds) {
;     ...
; #pragma unroll
;         for (int i = 0; i < 8; ++i) {
;             const float v = cb + cw[0] * raw[i] + cw[1] * raw[i + 1] + cw[2] * raw[i + 2] + cw[3] * raw[i + 3];
;             const int tok = tg * 8 + i;
;             BXF[tok * 64 + ch] = v;
;             *(LAS bf16_t*)(lds + BXC_OFF + tok * 144 + ch * 2) = (bf16_t)f2bf(v);
;         }
;         lds_barrier();
;         {
;             bf16x8 af[2];
; #pragma unroll
;             for (int ks = 0; ks < 2; ++ks) af[ks] = ldsfrag(lds + BXC_OFF + (tr * 16 + fr) * 144 + (ks * 32 + fq * 8) * 2);
; #pragma unroll
;             for (int c = 0; c < 2; ++c) {
;                 const int ct = ctb + c;
;                 f32x4 ga = (f32x4){0.f, 0.f, 0.f, 0.f}, gx = (f32x4){0.f, 0.f, 0.f, 0.f};
; #pragma unroll
;                 for (int ks = 0; ks < 2; ++ks) {
;                     ga = MFMA16(af[ks], ldsfrag(lds + WA_OFF + (ct * 16 + fr) * 144 + (ks * 32 + fq * 8) * 2), ga);
;                     gx = MFMA16(af[ks], ldsfrag(lds + WX_OFF + (ct * 16 + fr) * 144 + (ks * 32 + fq * 8) * 2), gx);
;                 }
; #pragma unroll
;                 for (int j = 0; j < 4; ++j) {
;                     const int tok = tr * 16 + fq * 4 + j, cc = ct * 16 + fr;
;                     const float r = sigmoidf_(ga[j] + ba[c]), ig = sigmoidf_(gx[j] + bxb[c]);
;                     const float la = -8.0f * r * spl[c];
;                     const float a = __expf(la);
;                     const float mult = sqrtf(fmaxf(-expm1_neg(2.0f * la), 0.f));
;                     AA[tok * 64 + cc] = a;
;                     UU[tok * 64 + cc] = mult * ig * BXF[tok * 64 + cc];
;                 }
.LBB0_301:
	v_lshlrev_b32_e32 v0, 16, v3
	v_lshlrev_b32_e32 v1, 16, v1
	v_fma_f32 v0, v36, v0, v40
	v_lshlrev_b32_e32 v2, 16, v6
	v_fmac_f32_e32 v0, v37, v1
	v_lshlrev_b32_e32 v3, 16, v5
	v_fmac_f32_e32 v0, v38, v2
	v_fmac_f32_e32 v0, v39, v3
	v_lshlrev_b32_e32 v4, 16, v11
	ds_write_b32 v66, v0 offset:27648
	v_cvt_pk_bf16_f32 v0, v0, v0
	ds_write_b16_d16_hi v61, v0 offset:18432
	v_fma_f32 v0, v36, v1, v40
	v_fmac_f32_e32 v0, v37, v2
	v_fmac_f32_e32 v0, v38, v3
	v_fmac_f32_e32 v0, v39, v4
	ds_write_b32 v67, v0 offset:27648
	v_cvt_pk_bf16_f32 v0, v0, v0
	ds_write_b16_d16_hi v62, v0 offset:18432
	v_fma_f32 v0, v36, v2, v40
	v_fmac_f32_e32 v0, v37, v3
	v_lshlrev_b32_e32 v5, 16, v10
	v_fmac_f32_e32 v0, v38, v4
	v_fmac_f32_e32 v0, v39, v5
	ds_write_b32 v68, v0 offset:27648
	v_cvt_pk_bf16_f32 v0, v0, v0
	ds_write_b16_d16_hi v62, v0 offset:18576
	v_fma_f32 v0, v36, v3, v40
	v_fmac_f32_e32 v0, v37, v4
	v_lshlrev_b32_e32 v6, 16, v13
	v_fmac_f32_e32 v0, v38, v5
	v_fmac_f32_e32 v0, v39, v6
	ds_write_b32 v69, v0 offset:27648
	v_cvt_pk_bf16_f32 v0, v0, v0
	ds_write_b16_d16_hi v62, v0 offset:18720
	v_fma_f32 v0, v36, v4, v40
	v_fmac_f32_e32 v0, v37, v5
	v_lshlrev_b32_e32 v7, 16, v12
	v_fmac_f32_e32 v0, v38, v6
	v_fmac_f32_e32 v0, v39, v7
	ds_write_b32 v70, v0 offset:27648
	v_cvt_pk_bf16_f32 v0, v0, v0
	ds_write_b16_d16_hi v62, v0 offset:18864
	v_fma_f32 v0, v36, v5, v40
	v_fmac_f32_e32 v0, v37, v6
	v_lshlrev_b32_e32 v8, 16, v15
	v_fmac_f32_e32 v0, v38, v7
	v_fmac_f32_e32 v0, v39, v8
	ds_write_b32 v71, v0 offset:27648
	v_cvt_pk_bf16_f32 v0, v0, v0
	ds_write_b16_d16_hi v62, v0 offset:19008
	v_fma_f32 v0, v36, v6, v40
	v_fmac_f32_e32 v0, v37, v7
	v_lshlrev_b32_e32 v9, 16, v14
	v_fmac_f32_e32 v0, v38, v8
	v_fmac_f32_e32 v0, v39, v9
	ds_write_b32 v72, v0 offset:27648
	v_cvt_pk_bf16_f32 v0, v0, v0
	ds_write_b16_d16_hi v62, v0 offset:19152
	v_fma_f32 v0, v36, v7, v40
	v_fmac_f32_e32 v0, v37, v8
	v_lshlrev_b32_e32 v10, 16, v85
	v_fmac_f32_e32 v0, v38, v9
	v_fmac_f32_e32 v0, v39, v10
	ds_write_b32 v73, v0 offset:27648
	v_cvt_pk_bf16_f32 v0, v0, v0
	ds_write_b16_d16_hi v62, v0 offset:19296
	s_waitcnt lgkmcnt(0)
	s_barrier
	ds_read_b128 v[4:7], v63 offset:18432
	ds_read_b128 v[0:3], v63 offset:18496
	ds_read_b128 v[8:11], v64
	ds_read_b128 v[12:15], v64 offset:64
	s_waitcnt lgkmcnt(1)
	v_mfma_f32_16x16x32_bf16 v[8:11], v[4:7], v[8:11], 0
	ds_read_b128 v[86:89], v64 offset:9216
	s_mov_b32 s0, 0xbd000000
	s_waitcnt lgkmcnt(1)
	v_mfma_f32_16x16x32_bf16 v[12:15], v[0:3], v[12:15], v[8:11]
	s_nop 7
	v_add_f32_e32 v8, v41, v12
	v_mul_f32_e32 v8, 0xbfb8aa3b, v8
	v_exp_f32_e32 v12, v8
	ds_read_b128 v[8:11], v64 offset:9280
	s_waitcnt lgkmcnt(1)
	v_mfma_f32_16x16x32_bf16 v[86:89], v[4:7], v[86:89], 0
	v_add_f32_e32 v12, 1.0, v12
	v_rcp_f32_e32 v12, v12
	s_waitcnt lgkmcnt(0)
	v_mfma_f32_16x16x32_bf16 v[8:11], v[0:3], v[8:11], v[86:89]
	v_mul_f32_e32 v12, 0xc1000000, v12
	v_mul_f32_e32 v85, v43, v12
	v_add_f32_e32 v12, v85, v85
	v_cmp_nlt_f32_e32 vcc, s0, v12
	s_and_saveexec_b64 s[0:1], vcc
	s_xor_b64 s[0:1], exec, s[0:1]
	v_mul_f32_e32 v12, 0x3fb8aa3b, v12
	v_exp_f32_e32 v12, v12
	s_nop 0
	v_add_f32_e32 v86, -1.0, v12
	s_andn2_saveexec_b64 s[0:1], s[0:1]
	s_mov_b32 s10, 0x3eaaaaab
	s_mov_b32 s11, 0x3e800000
	v_pk_mul_f32 v[86:87], v[12:13], s[10:11] op_sel_hi:[0,1]
	v_add_f32_e32 v87, 1.0, v87
	v_mul_f32_e32 v88, 0.5, v12
	v_fma_f32 v86, v86, v87, 1.0
	v_fma_f32 v86, v88, v86, 1.0
	v_mul_f32_e32 v86, v12, v86
	s_or_b64 exec, exec, s[0:1]
	v_max_f32_e64 v12, -v86, -v86
	v_max_f32_e32 v12, 0, v12
	s_mov_b32 s0, 0xf800000
	v_mul_f32_e32 v86, 0x4f800000, v12
	v_cmp_gt_f32_e32 vcc, s0, v12
	v_add_f32_e32 v8, v42, v8
	v_mul_f32_e32 v8, 0xbfb8aa3b, v8
	v_cndmask_b32_e32 v12, v12, v86, vcc
	v_sqrt_f32_e32 v86, v12
	v_exp_f32_e32 v8, v8
	v_add_f32_e32 v13, v41, v13
	v_mul_f32_e32 v13, 0xbfb8aa3b, v13
	v_add_u32_e32 v87, -1, v86
	v_fma_f32 v88, -v87, v86, v12
	v_cmp_ge_f32_e64 s[0:1], 0, v88
	v_add_u32_e32 v88, 1, v86
	v_exp_f32_e32 v13, v13
	v_cndmask_b32_e64 v87, v86, v87, s[0:1]
	v_fma_f32 v86, -v88, v86, v12
	v_cmp_lt_f32_e64 s[0:1], 0, v86
	v_add_f32_e32 v8, 1.0, v8
	v_rcp_f32_e32 v8, v8
	v_cndmask_b32_e64 v86, v87, v88, s[0:1]
	v_mul_f32_e32 v87, 0x37800000, v86
	v_cndmask_b32_e32 v86, v86, v87, vcc
	ds_read_b32 v87, v58 offset:27648
	v_mul_f32_e32 v85, 0x3fb8aa3b, v85
	v_add_f32_e32 v13, 1.0, v13
	v_exp_f32_e32 v85, v85
	v_cmp_class_f32_e32 vcc, v12, v165
	v_rcp_f32_e32 v13, v13
	s_mov_b32 s0, 0xbd000000
	v_cndmask_b32_e32 v12, v86, v12, vcc
	v_mul_f32_e32 v8, v8, v12
	s_waitcnt lgkmcnt(0)
	v_mul_f32_e32 v8, v87, v8
	ds_write2st64_b32 v58, v85, v8 offset0:172 offset1:236
	v_mul_f32_e32 v8, 0xc1000000, v13
	v_mul_f32_e32 v12, v43, v8
	v_add_f32_e32 v8, v12, v12
	v_cmp_nlt_f32_e32 vcc, s0, v8
	s_and_saveexec_b64 s[0:1], vcc
	s_xor_b64 s[0:1], exec, s[0:1]
	v_mul_f32_e32 v8, 0x3fb8aa3b, v8
	v_exp_f32_e32 v8, v8
	s_nop 0
	v_add_f32_e32 v13, -1.0, v8
	s_andn2_saveexec_b64 s[0:1], s[0:1]
	s_mov_b32 s10, 0x3eaaaaab
	s_mov_b32 s11, 0x3e800000
	v_pk_mul_f32 v[86:87], v[8:9], s[10:11] op_sel_hi:[0,1]
	v_add_f32_e32 v85, 1.0, v87
	v_mul_f32_e32 v13, 0.5, v8
	v_fma_f32 v85, v86, v85, 1.0
	v_fma_f32 v13, v13, v85, 1.0
	v_mul_f32_e32 v13, v8, v13
	s_or_b64 exec, exec, s[0:1]
	v_add_f32_e32 v8, v42, v9
	v_max_f32_e64 v9, -v13, -v13
	v_max_f32_e32 v9, 0, v9
	s_mov_b32 s0, 0xf800000
	v_mul_f32_e32 v13, 0x4f800000, v9
	v_cmp_gt_f32_e32 vcc, s0, v9
	v_mul_f32_e32 v8, 0xbfb8aa3b, v8
	v_exp_f32_e32 v8, v8
	v_cndmask_b32_e32 v9, v9, v13, vcc
	v_sqrt_f32_e32 v13, v9
	v_add_f32_e32 v14, v41, v14
	v_mul_f32_e32 v14, 0xbfb8aa3b, v14
	v_exp_f32_e32 v14, v14
	v_add_u32_e32 v85, -1, v13
	v_fma_f32 v86, -v85, v13, v9
	v_cmp_ge_f32_e64 s[0:1], 0, v86
	v_add_u32_e32 v86, 1, v13
	v_add_f32_e32 v8, 1.0, v8
	v_cndmask_b32_e64 v85, v13, v85, s[0:1]
	v_fma_f32 v13, -v86, v13, v9
	v_cmp_lt_f32_e64 s[0:1], 0, v13
	v_rcp_f32_e32 v8, v8
	v_mul_f32_e32 v12, 0x3fb8aa3b, v12
	v_cndmask_b32_e64 v13, v85, v86, s[0:1]
	v_mul_f32_e32 v85, 0x37800000, v13
	v_cndmask_b32_e32 v13, v13, v85, vcc
	ds_read_b32 v85, v58 offset:27904
	v_cmp_class_f32_e32 vcc, v9, v165
	v_exp_f32_e32 v12, v12
	s_mov_b32 s0, 0xbd000000
	v_cndmask_b32_e32 v9, v13, v9, vcc
	v_add_f32_e32 v13, 1.0, v14
	v_rcp_f32_e32 v13, v13
	v_mul_f32_e32 v8, v8, v9
	s_waitcnt lgkmcnt(0)
; DI float sigmoidf_(float x) { return __builtin_amdgcn_rcpf(1.0f + __expf(-x)); }
; DI float expm1_neg(float y) { return y > -0.03125f ? y * (1.0f + 0.5f * y * (1.0f + 0.33333334f * y * (1.0f + 0.25f * y))) : __expf(y) - 1.0f; }
; #define MFMA16(a, b, c) __builtin_amdgcn_mfma_f32_16x16x32_bf16((a), (b), (c), 0, 0, 0)
; DI void rglru_unit(const Params& P, const bf16_t* proj, bf16_t* ycat, int b, int hb, LAS unsigned char* lds) {
;     ...
; #pragma unroll
;             for (int c = 0; c < 2; ++c) {
;                 const int ct = ctb + c;
;                 f32x4 ga = (f32x4){0.f, 0.f, 0.f, 0.f}, gx = (f32x4){0.f, 0.f, 0.f, 0.f};
; #pragma unroll
;                 for (int ks = 0; ks < 2; ++ks) {
;                     ga = MFMA16(af[ks], ldsfrag(lds + WA_OFF + (ct * 16 + fr) * 144 + (ks * 32 + fq * 8) * 2), ga);
;                     gx = MFMA16(af[ks], ldsfrag(lds + WX_OFF + (ct * 16 + fr) * 144 + (ks * 32 + fq * 8) * 2), gx);
;                 }
; #pragma unroll
;                 for (int j = 0; j < 4; ++j) {
;                     const int tok = tr * 16 + fq * 4 + j, cc = ct * 16 + fr;
;                     const float r = sigmoidf_(ga[j] + ba[c]), ig = sigmoidf_(gx[j] + bxb[c]);
;                     const float la = -8.0f * r * spl[c];
;                     const float a = __expf(la);
;                     const float mult = sqrtf(fmaxf(-expm1_neg(2.0f * la), 0.f));
;                     AA[tok * 64 + cc] = a;
;                     UU[tok * 64 + cc] = mult * ig * BXF[tok * 64 + cc];
;                 }
	v_mul_f32_e32 v8, v85, v8
	ds_write2st64_b32 v58, v12, v8 offset0:173 offset1:237
	v_mul_f32_e32 v8, 0xc1000000, v13
	v_mul_f32_e32 v9, v43, v8
	v_add_f32_e32 v8, v9, v9
	v_cmp_nlt_f32_e32 vcc, s0, v8
	s_and_saveexec_b64 s[0:1], vcc
	s_xor_b64 s[0:1], exec, s[0:1]
	v_mul_f32_e32 v8, 0x3fb8aa3b, v8
	v_exp_f32_e32 v8, v8
	s_nop 0
	v_add_f32_e32 v12, -1.0, v8
	s_andn2_saveexec_b64 s[0:1], s[0:1]
	s_mov_b32 s10, 0x3eaaaaab
	s_mov_b32 s11, 0x3e800000
	v_pk_mul_f32 v[12:13], v[8:9], s[10:11] op_sel_hi:[0,1]
	v_add_f32_e32 v13, 1.0, v13
	v_mul_f32_e32 v14, 0.5, v8
	v_fma_f32 v12, v12, v13, 1.0
	v_fma_f32 v12, v14, v12, 1.0
	v_mul_f32_e32 v12, v8, v12
	s_or_b64 exec, exec, s[0:1]
	v_add_f32_e32 v8, v42, v10
	v_max_f32_e64 v10, -v12, -v12
	v_max_f32_e32 v10, 0, v10
	s_mov_b32 s0, 0xf800000
	v_mul_f32_e32 v12, 0x4f800000, v10
	v_cmp_gt_f32_e32 vcc, s0, v10
	v_mul_f32_e32 v8, 0xbfb8aa3b, v8
	v_exp_f32_e32 v8, v8
	v_cndmask_b32_e32 v10, v10, v12, vcc
	v_sqrt_f32_e32 v12, v10
	v_mul_f32_e32 v9, 0x3fb8aa3b, v9
	v_add_f32_e32 v8, 1.0, v8
	v_rcp_f32_e32 v8, v8
	v_add_u32_e32 v13, -1, v12
	v_fma_f32 v14, -v13, v12, v10
	v_cmp_ge_f32_e64 s[0:1], 0, v14
	v_add_u32_e32 v14, 1, v12
	v_exp_f32_e32 v9, v9
	v_cndmask_b32_e64 v13, v12, v13, s[0:1]
	v_fma_f32 v12, -v14, v12, v10
	v_cmp_lt_f32_e64 s[0:1], 0, v12
	s_nop 1
	v_cndmask_b32_e64 v12, v13, v14, s[0:1]
	v_mul_f32_e32 v13, 0x37800000, v12
	v_cndmask_b32_e32 v12, v12, v13, vcc
	v_add_f32_e32 v13, v41, v15
	v_mul_f32_e32 v13, 0xbfb8aa3b, v13
	v_exp_f32_e32 v13, v13
	ds_read_b32 v14, v58 offset:28160
	v_cmp_class_f32_e32 vcc, v10, v165
	s_mov_b32 s0, 0xbd000000
	s_nop 0
	v_cndmask_b32_e32 v10, v12, v10, vcc
	v_add_f32_e32 v12, 1.0, v13
	v_rcp_f32_e32 v12, v12
	v_mul_f32_e32 v8, v8, v10
	s_waitcnt lgkmcnt(0)
	v_mul_f32_e32 v8, v14, v8
	ds_write2st64_b32 v58, v9, v8 offset0:174 offset1:238
	v_mul_f32_e32 v8, 0xc1000000, v12
	v_mul_f32_e32 v10, v43, v8
	v_add_f32_e32 v8, v10, v10
	v_cmp_nlt_f32_e32 vcc, s0, v8
	s_and_saveexec_b64 s[0:1], vcc
	s_xor_b64 s[0:1], exec, s[0:1]
	v_mul_f32_e32 v8, 0x3fb8aa3b, v8
	v_exp_f32_e32 v8, v8
	s_nop 0
	v_add_f32_e32 v9, -1.0, v8
	s_andn2_saveexec_b64 s[0:1], s[0:1]
	s_mov_b32 s10, 0x3eaaaaab
	v_mul_f32_e32 v9, 0.5, v8
	s_mov_b32 s11, 0x3e800000
	v_pk_mul_f32 v[12:13], v[8:9], s[10:11] op_sel_hi:[0,1]
	v_add_f32_e32 v13, 1.0, v13
	v_fma_f32 v12, v12, v13, 1.0
	v_fma_f32 v9, v9, v12, 1.0
	v_mul_f32_e32 v9, v8, v9
	s_or_b64 exec, exec, s[0:1]
	v_max_f32_e64 v9, -v9, -v9
	v_max_f32_e32 v9, 0, v9
	s_mov_b32 s0, 0xf800000
	v_add_f32_e32 v8, v42, v11
	v_cmp_gt_f32_e32 vcc, s0, v9
	v_mul_f32_e32 v11, 0x4f800000, v9
	v_mul_f32_e32 v8, 0xbfb8aa3b, v8
	v_cndmask_b32_e32 v9, v9, v11, vcc
	v_sqrt_f32_e32 v11, v9
	v_exp_f32_e32 v8, v8
	v_mul_f32_e32 v10, 0x3fb8aa3b, v10
	v_exp_f32_e32 v10, v10
	v_add_u32_e32 v12, -1, v11
	v_fma_f32 v13, -v12, v11, v9
	v_cmp_ge_f32_e64 s[0:1], 0, v13
	v_add_u32_e32 v13, 1, v11
	v_add_f32_e32 v8, 1.0, v8
	v_cndmask_b32_e64 v12, v11, v12, s[0:1]
	v_fma_f32 v11, -v13, v11, v9
	v_cmp_lt_f32_e64 s[0:1], 0, v11
	v_rcp_f32_e32 v8, v8
	s_nop 0
	v_cndmask_b32_e64 v11, v12, v13, s[0:1]
	v_mul_f32_e32 v12, 0x37800000, v11
	v_cndmask_b32_e32 v11, v11, v12, vcc
	v_cmp_class_f32_e32 vcc, v9, v165
	s_mov_b32 s0, 0xbd000000
	s_nop 0
	v_cndmask_b32_e32 v9, v11, v9, vcc
	v_mul_f32_e32 v8, v8, v9
	ds_read_b32 v9, v58 offset:28416
	s_waitcnt lgkmcnt(0)
	v_mul_f32_e32 v8, v9, v8
	ds_write2st64_b32 v58, v10, v8 offset0:175 offset1:239
	ds_read_b128 v[8:11], v65
	ds_read_b128 v[12:15], v65 offset:9216
	s_waitcnt lgkmcnt(1)
	v_mfma_f32_16x16x32_bf16 v[8:11], v[4:7], v[8:11], 0
	s_waitcnt lgkmcnt(0)
	v_mfma_f32_16x16x32_bf16 v[12:15], v[4:7], v[12:15], 0
	ds_read_b128 v[4:7], v65 offset:64
	s_waitcnt lgkmcnt(0)
	v_mfma_f32_16x16x32_bf16 v[4:7], v[0:3], v[4:7], v[8:11]
	s_nop 2
	ds_read_b128 v[8:11], v65 offset:9280
	s_waitcnt lgkmcnt(0)
	v_mfma_f32_16x16x32_bf16 v[0:3], v[0:3], v[8:11], v[12:15]
	s_nop 1
	v_add_f32_e32 v4, v44, v4
	v_mul_f32_e32 v4, 0xbfb8aa3b, v4
	v_exp_f32_e32 v4, v4
	s_nop 0
	v_add_f32_e32 v4, 1.0, v4
	v_rcp_f32_e32 v4, v4
	s_nop 0
	v_mul_f32_e32 v4, 0xc1000000, v4
	v_mul_f32_e32 v8, v46, v4
	v_add_f32_e32 v4, v8, v8
	v_cmp_nlt_f32_e32 vcc, s0, v4
	s_and_saveexec_b64 s[0:1], vcc
	s_xor_b64 s[0:1], exec, s[0:1]
	v_mul_f32_e32 v4, 0x3fb8aa3b, v4
	v_exp_f32_e32 v4, v4
	s_nop 0
	v_add_f32_e32 v9, -1.0, v4
	s_andn2_saveexec_b64 s[0:1], s[0:1]
	s_mov_b32 s10, 0x3eaaaaab
	s_mov_b32 s11, 0x3e800000
	v_pk_mul_f32 v[10:11], v[4:5], s[10:11] op_sel_hi:[0,1]
	v_add_f32_e32 v11, 1.0, v11
	v_mul_f32_e32 v9, 0.5, v4
	v_fma_f32 v10, v10, v11, 1.0
	v_fma_f32 v9, v9, v10, 1.0
	v_mul_f32_e32 v9, v4, v9
	s_or_b64 exec, exec, s[0:1]
	v_max_f32_e64 v4, -v9, -v9
	v_max_f32_e32 v4, 0, v4
	s_mov_b32 s0, 0xf800000
	v_mul_f32_e32 v9, 0x4f800000, v4
	v_cmp_gt_f32_e32 vcc, s0, v4
	v_add_f32_e32 v0, v45, v0
	v_mul_f32_e32 v0, 0xbfb8aa3b, v0
	v_cndmask_b32_e32 v4, v4, v9, vcc
	v_sqrt_f32_e32 v9, v4
	v_exp_f32_e32 v0, v0
	v_add_f32_e32 v5, v44, v5
	v_mul_f32_e32 v5, 0xbfb8aa3b, v5
	v_add_u32_e32 v10, -1, v9
	v_fma_f32 v11, -v10, v9, v4
	v_cmp_ge_f32_e64 s[0:1], 0, v11
	v_add_u32_e32 v11, 1, v9
	v_add_f32_e32 v0, 1.0, v0
	v_cndmask_b32_e64 v10, v9, v10, s[0:1]
	v_fma_f32 v9, -v11, v9, v4
	v_cmp_lt_f32_e64 s[0:1], 0, v9
	v_rcp_f32_e32 v0, v0
	v_exp_f32_e32 v5, v5
	v_cndmask_b32_e64 v9, v10, v11, s[0:1]
	v_mul_f32_e32 v10, 0x37800000, v9
	v_cndmask_b32_e32 v9, v9, v10, vcc
	v_cmp_class_f32_e32 vcc, v4, v165
	ds_read_b32 v10, v58 offset:27712
	v_mul_f32_e32 v8, 0x3fb8aa3b, v8
	v_cndmask_b32_e32 v4, v9, v4, vcc
	v_mul_f32_e32 v0, v0, v4
	v_add_f32_e32 v4, 1.0, v5
	v_exp_f32_e32 v8, v8
	v_rcp_f32_e32 v4, v4
	s_waitcnt lgkmcnt(0)
; DI float sigmoidf_(float x) { return __builtin_amdgcn_rcpf(1.0f + __expf(-x)); }
; DI float expm1_neg(float y) { return y > -0.03125f ? y * (1.0f + 0.5f * y * (1.0f + 0.33333334f * y * (1.0f + 0.25f * y))) : __expf(y) - 1.0f; }
; DI void lds_barrier() { asm volatile("s_waitcnt lgkmcnt(0)" ::: "memory"); __builtin_amdgcn_s_barrier(); asm volatile("" ::: "memory"); }
; #define MFMA16(a, b, c) __builtin_amdgcn_mfma_f32_16x16x32_bf16((a), (b), (c), 0, 0, 0)
; DI void rglru_unit(const Params& P, const bf16_t* proj, bf16_t* ycat, int b, int hb, LAS unsigned char* lds) {
;     ...
; #pragma unroll
;             for (int c = 0; c < 2; ++c) {
;                 const int ct = ctb + c;
;                 f32x4 ga = (f32x4){0.f, 0.f, 0.f, 0.f}, gx = (f32x4){0.f, 0.f, 0.f, 0.f};
; #pragma unroll
;                 for (int ks = 0; ks < 2; ++ks) {
;                     ga = MFMA16(af[ks], ldsfrag(lds + WA_OFF + (ct * 16 + fr) * 144 + (ks * 32 + fq * 8) * 2), ga);
;                     gx = MFMA16(af[ks], ldsfrag(lds + WX_OFF + (ct * 16 + fr) * 144 + (ks * 32 + fq * 8) * 2), gx);
;                 }
; #pragma unroll
;                 for (int j = 0; j < 4; ++j) {
;                     const int tok = tr * 16 + fq * 4 + j, cc = ct * 16 + fr;
;                     const float r = sigmoidf_(ga[j] + ba[c]), ig = sigmoidf_(gx[j] + bxb[c]);
;                     const float la = -8.0f * r * spl[c];
;                     const float a = __expf(la);
;                     const float mult = sqrtf(fmaxf(-expm1_neg(2.0f * la), 0.f));
;                     AA[tok * 64 + cc] = a;
;                     UU[tok * 64 + cc] = mult * ig * BXF[tok * 64 + cc];
;                 }
;             }
;         }
;         lds_barrier();
;         if (wave == 0) {
; #pragma unroll 1
;             for (int t8 = 0; t8 < 64; t8 += 8) {
	v_mul_f32_e32 v0, v10, v0
	v_add_u32_e32 v5, 64, v58
	ds_write2st64_b32 v5, v8, v0 offset0:172 offset1:236
	v_mul_f32_e32 v0, 0xc1000000, v4
	v_mul_f32_e32 v4, v46, v0
	v_add_f32_e32 v0, v4, v4
	s_mov_b32 s0, 0xbd000000
	v_cmp_nlt_f32_e32 vcc, s0, v0
	s_and_saveexec_b64 s[0:1], vcc
	s_xor_b64 s[0:1], exec, s[0:1]
	v_mul_f32_e32 v0, 0x3fb8aa3b, v0
	v_exp_f32_e32 v0, v0
	s_nop 0
	v_add_f32_e32 v5, -1.0, v0
	s_andn2_saveexec_b64 s[0:1], s[0:1]
	s_mov_b32 s10, 0x3eaaaaab
	s_mov_b32 s11, 0x3e800000
	v_pk_mul_f32 v[8:9], v[0:1], s[10:11] op_sel_hi:[0,1]
	v_add_f32_e32 v9, 1.0, v9
	v_mul_f32_e32 v5, 0.5, v0
	v_fma_f32 v8, v8, v9, 1.0
	v_fma_f32 v5, v5, v8, 1.0
	v_mul_f32_e32 v5, v0, v5
	s_or_b64 exec, exec, s[0:1]
	v_add_f32_e32 v0, v45, v1
	v_max_f32_e64 v1, -v5, -v5
	v_max_f32_e32 v1, 0, v1
	s_mov_b32 s0, 0xf800000
	v_mul_f32_e32 v5, 0x4f800000, v1
	v_cmp_gt_f32_e32 vcc, s0, v1
	v_mul_f32_e32 v0, 0xbfb8aa3b, v0
	v_exp_f32_e32 v0, v0
	v_cndmask_b32_e32 v1, v1, v5, vcc
	v_sqrt_f32_e32 v5, v1
	v_add_f32_e32 v6, v44, v6
	v_mul_f32_e32 v6, 0xbfb8aa3b, v6
	v_exp_f32_e32 v6, v6
	v_add_u32_e32 v8, -1, v5
	v_fma_f32 v9, -v8, v5, v1
	v_cmp_ge_f32_e64 s[0:1], 0, v9
	v_add_u32_e32 v9, 1, v5
	v_add_f32_e32 v0, 1.0, v0
	v_cndmask_b32_e64 v8, v5, v8, s[0:1]
	v_fma_f32 v5, -v9, v5, v1
	v_cmp_lt_f32_e64 s[0:1], 0, v5
	v_rcp_f32_e32 v0, v0
	v_mul_f32_e32 v4, 0x3fb8aa3b, v4
	v_cndmask_b32_e64 v5, v8, v9, s[0:1]
	v_mul_f32_e32 v8, 0x37800000, v5
	v_cndmask_b32_e32 v5, v5, v8, vcc
	ds_read_b32 v8, v59 offset:27904
	v_cmp_class_f32_e32 vcc, v1, v165
	v_exp_f32_e32 v4, v4
	s_mov_b32 s0, 0xbd000000
	v_cndmask_b32_e32 v1, v5, v1, vcc
	v_add_f32_e32 v5, 1.0, v6
	v_rcp_f32_e32 v5, v5
	v_mul_f32_e32 v0, v0, v1
	s_waitcnt lgkmcnt(0)
	v_mul_f32_e32 v0, v8, v0
	ds_write2st64_b32 v59, v4, v0 offset0:173 offset1:237
	v_mul_f32_e32 v0, 0xc1000000, v5
	v_mul_f32_e32 v1, v46, v0
	v_add_f32_e32 v0, v1, v1
	v_cmp_nlt_f32_e32 vcc, s0, v0
	s_and_saveexec_b64 s[0:1], vcc
	s_xor_b64 s[0:1], exec, s[0:1]
	v_mul_f32_e32 v0, 0x3fb8aa3b, v0
	v_exp_f32_e32 v0, v0
	s_nop 0
	v_add_f32_e32 v4, -1.0, v0
	s_andn2_saveexec_b64 s[0:1], s[0:1]
	s_mov_b32 s10, 0x3eaaaaab
	s_mov_b32 s11, 0x3e800000
	v_pk_mul_f32 v[4:5], v[0:1], s[10:11] op_sel_hi:[0,1]
	v_add_f32_e32 v5, 1.0, v5
	v_mul_f32_e32 v6, 0.5, v0
	v_fma_f32 v4, v4, v5, 1.0
	v_fma_f32 v4, v6, v4, 1.0
	v_mul_f32_e32 v4, v0, v4
	s_or_b64 exec, exec, s[0:1]
	v_add_f32_e32 v0, v45, v2
	v_max_f32_e64 v2, -v4, -v4
	v_max_f32_e32 v2, 0, v2
	s_mov_b32 s0, 0xf800000
	v_mul_f32_e32 v4, 0x4f800000, v2
	v_cmp_gt_f32_e32 vcc, s0, v2
	v_mul_f32_e32 v0, 0xbfb8aa3b, v0
	v_exp_f32_e32 v0, v0
	v_cndmask_b32_e32 v2, v2, v4, vcc
	v_sqrt_f32_e32 v4, v2
	v_mul_f32_e32 v1, 0x3fb8aa3b, v1
	v_add_f32_e32 v0, 1.0, v0
	v_rcp_f32_e32 v0, v0
	v_add_u32_e32 v5, -1, v4
	v_fma_f32 v6, -v5, v4, v2
	v_cmp_ge_f32_e64 s[0:1], 0, v6
	v_add_u32_e32 v6, 1, v4
	v_exp_f32_e32 v1, v1
	v_cndmask_b32_e64 v5, v4, v5, s[0:1]
	v_fma_f32 v4, -v6, v4, v2
	v_cmp_lt_f32_e64 s[0:1], 0, v4
	s_nop 1
	v_cndmask_b32_e64 v4, v5, v6, s[0:1]
	v_mul_f32_e32 v5, 0x37800000, v4
	v_cndmask_b32_e32 v4, v4, v5, vcc
	v_add_f32_e32 v5, v44, v7
	v_mul_f32_e32 v5, 0xbfb8aa3b, v5
	v_exp_f32_e32 v5, v5
	ds_read_b32 v6, v59 offset:28160
	v_cmp_class_f32_e32 vcc, v2, v165
	s_mov_b32 s0, 0xbd000000
	s_nop 0
	v_cndmask_b32_e32 v2, v4, v2, vcc
	v_add_f32_e32 v4, 1.0, v5
	v_rcp_f32_e32 v4, v4
	v_mul_f32_e32 v0, v0, v2
	s_waitcnt lgkmcnt(0)
	v_mul_f32_e32 v0, v6, v0
	ds_write2st64_b32 v59, v1, v0 offset0:174 offset1:238
	v_mul_f32_e32 v0, 0xc1000000, v4
	v_mul_f32_e32 v1, v46, v0
	v_add_f32_e32 v0, v1, v1
	v_cmp_nlt_f32_e32 vcc, s0, v0
	s_and_saveexec_b64 s[0:1], vcc
	s_xor_b64 s[0:1], exec, s[0:1]
	v_mul_f32_e32 v0, 0x3fb8aa3b, v0
	v_exp_f32_e32 v0, v0
	s_nop 0
	v_add_f32_e32 v2, -1.0, v0
	s_andn2_saveexec_b64 s[0:1], s[0:1]
	s_mov_b32 s10, 0x3eaaaaab
	s_mov_b32 s11, 0x3e800000
	v_pk_mul_f32 v[4:5], v[0:1], s[10:11] op_sel_hi:[0,1]
	v_add_f32_e32 v5, 1.0, v5
	v_mul_f32_e32 v2, 0.5, v0
	v_fma_f32 v4, v4, v5, 1.0
	v_fma_f32 v2, v2, v4, 1.0
	v_mul_f32_e32 v2, v0, v2
	s_or_b64 exec, exec, s[0:1]
	v_max_f32_e64 v2, -v2, -v2
	v_max_f32_e32 v2, 0, v2
	s_mov_b32 s0, 0xf800000
	v_add_f32_e32 v0, v45, v3
	v_mul_f32_e32 v3, 0x4f800000, v2
	v_cmp_gt_f32_e32 vcc, s0, v2
	v_mul_f32_e32 v0, 0xbfb8aa3b, v0
	v_exp_f32_e32 v0, v0
	v_cndmask_b32_e32 v2, v2, v3, vcc
	v_sqrt_f32_e32 v3, v2
	v_mul_f32_e32 v1, 0x3fb8aa3b, v1
	v_add_f32_e32 v0, 1.0, v0
	v_rcp_f32_e32 v0, v0
	v_add_u32_e32 v4, -1, v3
	v_fma_f32 v5, -v4, v3, v2
	v_cmp_ge_f32_e64 s[0:1], 0, v5
	v_add_u32_e32 v5, 1, v3
	v_exp_f32_e32 v1, v1
	v_cndmask_b32_e64 v4, v3, v4, s[0:1]
	v_fma_f32 v3, -v5, v3, v2
	v_cmp_lt_f32_e64 s[0:1], 0, v3
	s_nop 1
	v_cndmask_b32_e64 v3, v4, v5, s[0:1]
	ds_read_b32 v5, v59 offset:28416
	v_mul_f32_e32 v4, 0x37800000, v3
	v_cndmask_b32_e32 v3, v3, v4, vcc
	v_cmp_class_f32_e32 vcc, v2, v165
	s_nop 1
	v_cndmask_b32_e32 v2, v3, v2, vcc
	v_mul_f32_e32 v0, v0, v2
	s_waitcnt lgkmcnt(0)
	v_mul_f32_e32 v0, v5, v0
	ds_write2st64_b32 v59, v1, v0 offset0:175 offset1:239
	s_waitcnt lgkmcnt(0)
	s_barrier
	s_and_saveexec_b64 s[0:1], s[4:5]
	s_cbranch_execz .LBB0_298
	s_mov_b32 s10, -8
	v_mov_b32_e32 v0, v60

; #define LAS __attribute__((address_space(3)))
; DI unsigned f2bf(float f) { unsigned u = __float_as_uint(f); u += 0x7FFFu + ((u >> 16) & 1u); return u >> 16; }
; DI void gdn_unit(const Params& P, bf16_t* proj, const float* gb, int b, int h, LAS unsigned char* lds) {
;     ...
;             } else {
; #pragma unroll
;                 for (int i = 0; i < 32; ++i) *(LAS bf16_t*)(T22n + i * 64 + cl * 2) = (bf16_t)f2bf(Tc[i]);
;             }
.LBB0_494:
	s_or_b64 exec, exec, s[0:1]
	v_bfe_u32 v36, v37, 16, 1
	v_cmp_lt_u32_e32 vcc, 31, v67
	v_add3_u32 v36, v37, v36, s68
	s_and_saveexec_b64 s[0:1], vcc
	s_xor_b64 s[0:1], exec, s[0:1]
	s_cbranch_execz .LBB0_496
	v_lshl_add_u32 v33, v33, 1, 0
	v_add_u32_e32 v33, 0x21400, v33
	ds_write_b16_d16_hi v33, v36
	v_bfe_u32 v36, v32, 16, 1
	v_add3_u32 v32, v32, v36, s68
	ds_write_b16_d16_hi v33, v32 offset:64
	v_cvt_pk_bf16_f32 v32, v34, v34
	ds_write_b16_d16_hi v33, v32 offset:128
	v_cvt_pk_bf16_f32 v32, v35, v35
	ds_write_b16_d16_hi v33, v32 offset:192
	v_cvt_pk_bf16_f32 v32, v39, v39
	ds_write_b16_d16_hi v33, v32 offset:256
	v_cvt_pk_bf16_f32 v32, v38, v38
	ds_write_b16_d16_hi v33, v32 offset:320
	v_cvt_pk_bf16_f32 v32, v43, v43
	ds_write_b16_d16_hi v33, v32 offset:384
	v_cvt_pk_bf16_f32 v32, v44, v44
	ds_write_b16_d16_hi v33, v32 offset:448
	v_cvt_pk_bf16_f32 v32, v45, v45
	ds_write_b16_d16_hi v33, v32 offset:512
	v_cvt_pk_bf16_f32 v32, v47, v47
	ds_write_b16_d16_hi v33, v32 offset:576
	v_cvt_pk_bf16_f32 v32, v46, v46
	ds_write_b16_d16_hi v33, v32 offset:640
	v_cvt_pk_bf16_f32 v32, v48, v48
	ds_write_b16_d16_hi v33, v32 offset:704
	v_cvt_pk_bf16_f32 v32, v50, v50
	ds_write_b16_d16_hi v33, v32 offset:768
	v_cvt_pk_bf16_f32 v32, v52, v52
	ds_write_b16_d16_hi v33, v32 offset:832
	v_cvt_pk_bf16_f32 v32, v51, v51
	ds_write_b16_d16_hi v33, v32 offset:896
	v_cvt_pk_bf16_f32 v32, v53, v53
	ds_write_b16_d16_hi v33, v32 offset:960
	v_cvt_pk_bf16_f32 v32, v54, v54
	ds_write_b16_d16_hi v33, v32 offset:1024
	v_cvt_pk_bf16_f32 v32, v56, v56
	ds_write_b16_d16_hi v33, v32 offset:1088
	v_cvt_pk_bf16_f32 v32, v55, v55
	ds_write_b16_d16_hi v33, v32 offset:1152
	v_cvt_pk_bf16_f32 v32, v57, v57
	ds_write_b16_d16_hi v33, v32 offset:1216
	v_cvt_pk_bf16_f32 v32, v58, v58
	ds_write_b16_d16_hi v33, v32 offset:1280
	v_cvt_pk_bf16_f32 v32, v62, v62
	ds_write_b16_d16_hi v33, v32 offset:1344
	v_cvt_pk_bf16_f32 v32, v59, v59
	ds_write_b16_d16_hi v33, v32 offset:1408
	v_cvt_pk_bf16_f32 v32, v63, v63
	ds_write_b16_d16_hi v33, v32 offset:1472
	v_cvt_pk_bf16_f32 v32, v64, v64
	ds_write_b16_d16_hi v33, v32 offset:1536
	v_cvt_pk_bf16_f32 v32, v114, v114
	ds_write_b16_d16_hi v33, v32 offset:1600
	v_cvt_pk_bf16_f32 v32, v65, v65
	ds_write_b16_d16_hi v33, v32 offset:1664
	v_cvt_pk_bf16_f32 v32, v115, v115
	ds_write_b16_d16_hi v33, v32 offset:1728
	v_cvt_pk_bf16_f32 v32, v49, v49
	ds_write_b16_d16_hi v33, v32 offset:1792
	v_cvt_pk_bf16_f32 v32, v117, v117
	ds_write_b16_d16_hi v33, v32 offset:1856
	v_cvt_pk_bf16_f32 v32, v116, v116
	ds_write_b16_d16_hi v33, v32 offset:1920
	v_cvt_pk_bf16_f32 v32, v118, v118
	ds_write_b16_d16_hi v33, v32 offset:1984

; #define LAS __attribute__((address_space(3)))
; DI unsigned f2bf(float f) { unsigned u = __float_as_uint(f); u += 0x7FFFu + ((u >> 16) & 1u); return u >> 16; }
; DI unsigned pk2(float lo, float hi) { return f2bf(lo) | (f2bf(hi) << 16); }
; #define MFMA16(a, b, c) __builtin_amdgcn_mfma_f32_16x16x32_bf16((a), (b), (c), 0, 0, 0)
; DI void gdn_unit(const Params& P, bf16_t* proj, const float* gb, int b, int h, LAS unsigned char* lds) {
;     ...
;             f32x4 xacc[2][2];
; #pragma unroll
;             for (int ti = 0; ti < 2; ++ti)
; #pragma unroll
;                 for (int tj = 0; tj < 2; ++tj)
;                     xacc[ti][tj] = MFMA16(ldsfrag(L21b + (ti * 16 + fr) * 64 + fq * 16), ldsfrag(T11t + (tj * 16 + fr) * 64 + fq * 16), ((f32x4){0.f, 0.f, 0.f, 0.f}));
; #pragma unroll
;             for (int ti = 0; ti < 2; ++ti)
; #pragma unroll
;                 for (int tj = 0; tj < 2; ++tj) {
;                     u32x2 w; w.x = pk2(xacc[ti][tj][0], xacc[ti][tj][1]); w.y = pk2(xacc[ti][tj][2], xacc[ti][tj][3]);
;                     *(LAS u32x2*)(Xt + (tj * 16 + fr) * 64 + (ti * 16 + fq * 4) * 2) = w;
;                 }
; #pragma unroll
;             for (int tj = 0; tj < 2; ++tj) {
;                 const int col = tj * 16 + fr;
;                 const float c1 = -betas[col] * egcs[col], c2 = -betas[col];
; #pragma unroll
;                 for (int ti = 0; ti < 2; ++ti) {
;                     const f32x4 t = MFMA16(ldsfrag(T22n + (ti * 16 + fr) * 64 + fq * 16), ldsfrag(Xt + (tj * 16 + fr) * 64 + fq * 16), ((f32x4){0.f, 0.f, 0.f, 0.f}));
; #pragma unroll
;                     for (int jj = 0; jj < 4; ++jj) {
;                         const int row = 32 + ti * 16 + fq * 4 + jj;
;                         *(LAS bf16_t*)(lds + TP_OFF + row * 144 + col * 2) = (bf16_t)f2bf(t[jj] * c1);
;                         *(LAS bf16_t*)(lds + TPP_OFF + row * 144 + col * 2) = (bf16_t)f2bf(t[jj] * c2);
;                     }
;                 }
;             }
.LBB0_498:
	s_or_b64 exec, exec, s[0:1]
	v_lshlrev_b32_e32 v56, 6, v148
	v_add3_u32 v43, s2, v56, v134
	ds_read_b128 v[32:35], v43
	v_readlane_b32 s0, v255, 7
	v_readlane_b32 s2, v255, 11
	s_add_i32 s1, 0, 0x24d00
	v_add3_u32 v44, s0, v56, v134
	ds_read_b128 v[36:39], v44
	ds_read_b128 v[44:47], v44 offset:1024
	ds_read_b128 v[48:51], v43 offset:1024
	v_add3_u32 v43, s2, v56, v42
	s_add_i32 s0, 0, 0x21400
	v_readlane_b32 s3, v255, 10
	s_waitcnt lgkmcnt(2)
	v_mfma_f32_16x16x32_bf16 v[52:55], v[32:35], v[36:39], 0
	v_lshlrev_b32_e32 v57, 6, v113
	v_mov_b32_e32 v207, v42
	s_waitcnt lgkmcnt(1)
	v_mfma_f32_16x16x32_bf16 v[32:35], v[32:35], v[44:47], 0
	s_waitcnt lgkmcnt(0)
	v_mfma_f32_16x16x32_bf16 v[36:39], v[48:51], v[36:39], 0
	v_mfma_f32_16x16x32_bf16 v[44:47], v[48:51], v[44:47], 0
	s_nop 0
	s_nop 0
	s_nop 0
	s_nop 0
	s_nop 0
	s_nop 0
	s_nop 0
	v_cvt_pk_bf16_f32 v48, v52, v53
	s_nop 0
	s_nop 0
	s_nop 0
	s_nop 0
	v_cvt_pk_bf16_f32 v49, v54, v55
	v_cvt_pk_bf16_f32 v32, v32, v33
	v_cvt_pk_bf16_f32 v33, v34, v35
	v_cvt_pk_bf16_f32 v34, v36, v37
	v_cvt_pk_bf16_f32 v35, v38, v39
	ds_write2_b64 v43, v[48:49], v[34:35] offset1:4
	v_cvt_pk_bf16_f32 v34, v44, v45
	v_cvt_pk_bf16_f32 v35, v46, v47
	v_add_u32_e32 v45, s0, v134
	s_add_i32 s0, 0, 0x24e00
	ds_write2_b64 v43, v[32:33], v[34:35] offset0:128 offset1:132
	v_add_u32_e32 v32, s1, v111
	v_add_u32_e32 v33, s0, v111
	v_add_u32_e32 v43, v45, v56
	ds_read_b32 v46, v32
	ds_read_b32 v47, v33
	ds_read_b128 v[32:35], v43
	v_add_u32_e32 v44, s2, v134
	v_add_u32_e32 v48, v44, v56
	ds_read_b128 v[36:39], v48
	s_waitcnt lgkmcnt(0)
	v_mfma_f32_16x16x32_bf16 v[32:35], v[32:35], v[36:39], 0
	v_mul_f32_e64 v47, v47, -v46
	v_readlane_b32 s2, v255, 9
	v_mul_lo_u32 v52, v205, s37
	s_nop 4
	v_mul_f32_e32 v36, v47, v32
	v_add_u32_e32 v49, s2, v112
	s_nop 0
	v_add_u32_e32 v53, 0x1200, v52
	v_cvt_pk_bf16_f32 v36, v36, v36
	v_add_u32_e32 v37, v49, v53
	v_mul_f32_e64 v32, v32, -v46
	v_add_u32_e32 v50, s3, v112
	ds_write_b16_d16_hi v37, v36
	v_cvt_pk_bf16_f32 v32, v32, v32
	v_add_u32_e32 v36, v50, v53
	v_add_u32_e32 v51, s1, v110
	ds_write_b16_d16_hi v36, v32
	v_mul_f32_e32 v32, v47, v33
	s_movk_i32 s1, 0x240
	v_mul_lo_u32 v54, v61, s1
	v_cvt_pk_bf16_f32 v32, v32, v32
	v_add_u32_e32 v55, v49, v54
	ds_write_b16_d16_hi v55, v32 offset:4752
	v_mul_f32_e64 v32, v33, -v46
	v_cvt_pk_bf16_f32 v32, v32, v32
	v_add_u32_e32 v56, v50, v54
	ds_write_b16_d16_hi v56, v32 offset:4752
	v_mul_f32_e32 v32, v47, v34
	v_cvt_pk_bf16_f32 v32, v32, v32
	ds_write_b16_d16_hi v55, v32 offset:4896
	v_mul_f32_e64 v32, v34, -v46
	v_cvt_pk_bf16_f32 v32, v32, v32
	ds_write_b16_d16_hi v56, v32 offset:4896
	v_mul_f32_e32 v32, v47, v35
	v_cvt_pk_bf16_f32 v32, v32, v32
	ds_write_b16_d16_hi v55, v32 offset:5040
	v_mul_f32_e64 v32, v35, -v46
	v_cvt_pk_bf16_f32 v32, v32, v32
	ds_write_b16_d16_hi v56, v32 offset:5040
	v_add_u32_e32 v45, v45, v57
	ds_read_b32 v51, v51
	ds_read_b128 v[32:35], v45
	ds_read_b128 v[36:39], v48
	s_waitcnt lgkmcnt(0)
	v_mfma_f32_16x16x32_bf16 v[32:35], v[32:35], v[36:39], 0
	v_add_u32_e32 v48, 0x1b00, v52
	v_add_u32_e32 v44, v44, v57
	s_nop 5
	v_mul_f32_e32 v36, v47, v32
	s_nop 0
	v_cvt_pk_bf16_f32 v36, v36, v36
	v_add_u32_e32 v37, v49, v48
	v_mul_f32_e64 v32, v32, -v46
	ds_write_b16_d16_hi v37, v36
	s_nop 0
	v_cvt_pk_bf16_f32 v32, v32, v32
	v_add_u32_e32 v36, v50, v48
	ds_write_b16_d16_hi v36, v32
	v_mul_f32_e32 v32, v47, v33
	v_cvt_pk_bf16_f32 v32, v32, v32
	ds_write_b16_d16_hi v55, v32 offset:7056
	v_mul_f32_e64 v32, v33, -v46
	v_cvt_pk_bf16_f32 v32, v32, v32
	ds_write_b16_d16_hi v56, v32 offset:7056
	v_mul_f32_e32 v32, v47, v34
	v_cvt_pk_bf16_f32 v32, v32, v32
	ds_write_b16_d16_hi v55, v32 offset:7200
	v_mul_f32_e64 v32, v34, -v46
	v_cvt_pk_bf16_f32 v32, v32, v32
	ds_write_b16_d16_hi v56, v32 offset:7200
	v_mul_f32_e32 v32, v47, v35
	v_cvt_pk_bf16_f32 v32, v32, v32
	ds_write_b16_d16_hi v55, v32 offset:7344
	v_mul_f32_e64 v32, v35, -v46
	v_cvt_pk_bf16_f32 v32, v32, v32
	ds_write_b16_d16_hi v56, v32 offset:7344
	v_add_u32_e32 v36, s0, v110
	ds_read_b128 v[32:35], v43
	ds_read_b32 v43, v36
	ds_read_b128 v[36:39], v44
	s_waitcnt lgkmcnt(0)
	v_mfma_f32_16x16x32_bf16 v[32:35], v[32:35], v[36:39], 0
	v_mul_f32_e64 v43, v43, -v51
	v_add_u32_e32 v46, s2, v66
	v_add_u32_e32 v47, s3, v66
	s_nop 4
	v_mul_f32_e32 v36, v43, v32
	s_nop 0
	v_cvt_pk_bf16_f32 v36, v36, v36
	v_add_u32_e32 v37, v46, v53
	v_mul_f32_e64 v32, v32, -v51
	ds_write_b16_d16_hi v37, v36
	s_nop 0
	v_cvt_pk_bf16_f32 v32, v32, v32
	v_add_u32_e32 v36, v47, v53
	ds_write_b16_d16_hi v36, v32
	v_mul_f32_e32 v32, v43, v33
	v_cvt_pk_bf16_f32 v32, v32, v32
	v_add_u32_e32 v49, v46, v54
	ds_write_b16_d16_hi v49, v32 offset:4752
	v_mul_f32_e64 v32, v33, -v51
	v_cvt_pk_bf16_f32 v32, v32, v32
	v_add_u32_e32 v50, v47, v54
	ds_write_b16_d16_hi v50, v32 offset:4752
	v_mul_f32_e32 v32, v43, v34
	v_cvt_pk_bf16_f32 v32, v32, v32
	ds_write_b16_d16_hi v49, v32 offset:4896
	v_mul_f32_e64 v32, v34, -v51
	v_cvt_pk_bf16_f32 v32, v32, v32
	ds_write_b16_d16_hi v50, v32 offset:4896
	v_mul_f32_e32 v32, v43, v35
	v_cvt_pk_bf16_f32 v32, v32, v32
	ds_write_b16_d16_hi v49, v32 offset:5040
	v_mul_f32_e64 v32, v35, -v51
	v_cvt_pk_bf16_f32 v32, v32, v32
	ds_write_b16_d16_hi v50, v32 offset:5040
	ds_read_b128 v[32:35], v45
	ds_read_b128 v[36:39], v44
	s_waitcnt lgkmcnt(0)
	v_mfma_f32_16x16x32_bf16 v[32:35], v[32:35], v[36:39], 0
	s_nop 7
	v_mul_f32_e32 v36, v43, v32
	s_nop 0
	v_cvt_pk_bf16_f32 v36, v36, v36
	v_add_u32_e32 v37, v46, v48
	v_mul_f32_e64 v32, v32, -v51
	ds_write_b16_d16_hi v37, v36
	s_nop 0
	v_cvt_pk_bf16_f32 v32, v32, v32
	v_add_u32_e32 v36, v47, v48
	ds_write_b16_d16_hi v36, v32
	v_mul_f32_e32 v32, v43, v33
	v_bfe_u32 v36, v32, 16, 1
	v_add3_u32 v32, v32, v36, s68
	ds_write_b16_d16_hi v49, v32 offset:7056
	v_mul_f32_e64 v32, v33, -v51
	v_cvt_pk_bf16_f32 v32, v32, v32
	ds_write_b16_d16_hi v50, v32 offset:7056
	v_mul_f32_e32 v32, v43, v34
	v_cvt_pk_bf16_f32 v32, v32, v32
	ds_write_b16_d16_hi v49, v32 offset:7200
	v_mul_f32_e64 v32, v34, -v51
	v_cvt_pk_bf16_f32 v32, v32, v32
	ds_write_b16_d16_hi v50, v32 offset:7200
	v_mul_f32_e32 v32, v43, v35
	v_cvt_pk_bf16_f32 v32, v32, v32
	ds_write_b16_d16_hi v49, v32 offset:7344
	v_mul_f32_e64 v32, v35, -v51
	v_bfe_u32 v33, v32, 16, 1
	v_add3_u32 v32, v32, v33, s68
	ds_write_b16_d16_hi v50, v32 offset:7344
	v_mov_b32_e32 v50, v40
	v_mov_b32_e32 v49, v41
; #define LAS __attribute__((address_space(3)))
; DI unsigned f2bf(float f) { unsigned u = __float_as_uint(f); u += 0x7FFFu + ((u >> 16) & 1u); return u >> 16; }
; DI void lds_barrier() { asm volatile("s_waitcnt lgkmcnt(0)" ::: "memory"); __builtin_amdgcn_s_barrier(); asm volatile("" ::: "memory"); }
; #define MFMA16(a, b, c) __builtin_amdgcn_mfma_f32_16x16x32_bf16((a), (b), (c), 0, 0, 0)
; DI void gdn_unit(const Params& P, bf16_t* proj, const float* gb, int b, int h, LAS unsigned char* lds) {
;     ...
;         lds_barrier();
;         f32x4 uacc[4];
;         {
;             bf16x8 vb[2], kb[2];
; #pragma unroll
;             for (int ks = 0; ks < 2; ++ks) { vb[ks] = ldsfrag(lds + VT_OFF + (16 * wave + fr) * 144 + (ks * 32 + fq * 8) * 2); kb[ks] = ldsfrag(lds + KT_OFF + (16 * wave + fr) * 144 + (ks * 32 + fq * 8) * 2); }
; #pragma unroll
;             for (int tt = 0; tt < 4; ++tt) {
;                 f32x4 au = (f32x4){0.f, 0.f, 0.f, 0.f}, aw = (f32x4){0.f, 0.f, 0.f, 0.f};
; #pragma unroll
;                 for (int ks = 0; ks < 2; ++ks) {
;                     au = MFMA16(ldsfrag(lds + TPP_OFF + (tt * 16 + fr) * 144 + (ks * 32 + fq * 8) * 2), vb[ks], au);
;                     aw = MFMA16(ldsfrag(lds + TP_OFF + (tt * 16 + fr) * 144 + (ks * 32 + fq * 8) * 2), kb[ks], aw);
;                 }
;                 uacc[tt] = au;
; #pragma unroll
;                 for (int jj = 0; jj < 4; ++jj) *(LAS bf16_t*)(lds + K_OFF + (tt * 16 + fq * 4 + jj) * 272 + (16 * wave + fr) * 2) = (bf16_t)f2bf(aw[jj]);
;             }
;         }
.LBB0_499:
	v_mul_u32_u24_e32 v150, 0x90, v148
	v_readlane_b32 s16, v255, 10
	s_waitcnt lgkmcnt(0)
	s_barrier
	v_or_b32_e32 v51, s4, v148
	v_add3_u32 v44, s16, v150, v134
	ds_read_b128 v[32:35], v44
	v_mul_lo_u32 v60, v51, s37
	v_add_u32_e32 v48, 0, v60
	v_readlane_b32 s3, v255, 9
	v_add_u32_e32 v64, v48, v134
	ds_read_b128 v[40:43], v64 offset:53248
	v_add3_u32 v62, s3, v150, v134
	ds_read_b128 v[36:39], v62
	ds_read_b128 v[52:55], v64 offset:34816
	ds_read_b128 v[44:47], v44 offset:64
	ds_read_b128 v[56:59], v64 offset:53312
	ds_read_b128 v[108:111], v62 offset:64
	ds_read_b128 v[112:115], v64 offset:34880
	s_waitcnt lgkmcnt(6)
	v_mfma_f32_16x16x32_bf16 v[32:35], v[32:35], v[40:43], 0
	s_movk_i32 s0, 0xff72
	v_mad_u64_u32 v[62:63], s[0:1], v51, s0, v[48:49]
	s_waitcnt lgkmcnt(4)
	v_mfma_f32_16x16x32_bf16 v[36:39], v[36:39], v[52:55], 0
	s_movk_i32 s0, 0x440
	v_mad_u64_u32 v[66:67], s[0:1], v61, s0, v[62:63]
	s_waitcnt lgkmcnt(2)
	v_mfma_f32_16x16x32_bf16 v[44:47], v[44:47], v[56:59], v[32:35]
	v_mad_u32_u24 v224, v148, s37, v252
	v_add3_u32 v65, s3, v224, v134
	v_add3_u32 v63, s16, v224, v134
	s_waitcnt lgkmcnt(0)
	v_mfma_f32_16x16x32_bf16 v[32:35], v[108:111], v[112:115], v[36:39]
	s_movk_i32 s2, 0x110
	v_mad_u32_u24 v153, v148, s37, v164
	v_mad_u32_u24 v152, v148, s37, v167
	v_mul_lo_u32 v51, v51, s2
	v_lshlrev_b32_e32 v225, 2, v205
	s_nop 2
	s_nop 0
	v_cvt_pk_bf16_f32 v32, v32, v32
	ds_write_b16_d16_hi v66, v32 offset:17408
	s_nop 0
	v_cvt_pk_bf16_f32 v32, v33, v33
	ds_write_b16_d16_hi v66, v32 offset:17680
	v_cvt_pk_bf16_f32 v32, v34, v34
	ds_write_b16_d16_hi v66, v32 offset:17952
	v_cvt_pk_bf16_f32 v32, v35, v35
	ds_write_b16_d16_hi v66, v32 offset:18224
	ds_read_b128 v[36:39], v65
	ds_read_b128 v[32:35], v63
	s_waitcnt lgkmcnt(1)
	v_mfma_f32_16x16x32_bf16 v[108:111], v[36:39], v[52:55], 0
	ds_read_b128 v[36:39], v63 offset:64
	v_add_u32_e32 v151, s3, v60
	s_waitcnt lgkmcnt(1)
	v_mfma_f32_16x16x32_bf16 v[32:35], v[32:35], v[40:43], 0
	s_waitcnt lgkmcnt(0)
	v_mfma_f32_16x16x32_bf16 v[36:39], v[36:39], v[56:59], v[32:35]
	s_nop 5
	ds_read_b128 v[32:35], v65 offset:64
	s_waitcnt lgkmcnt(0)
	v_mfma_f32_16x16x32_bf16 v[32:35], v[32:35], v[112:115], v[108:111]
	v_add3_u32 v65, s3, v153, v134
	s_nop 6
	v_bfe_u32 v63, v32, 16, 1
	v_add3_u32 v32, v32, v63, s68
	v_mad_u64_u32 v[108:109], s[0:1], v205, s2, v[62:63]
	ds_write_b16_d16_hi v108, v32 offset:21760
	s_nop 0
	v_cvt_pk_bf16_f32 v32, v33, v33
	ds_write_b16_d16_hi v66, v32 offset:22032
	s_nop 0
	v_cvt_pk_bf16_f32 v32, v34, v34
	ds_write_b16_d16_hi v66, v32 offset:22304
	v_cvt_pk_bf16_f32 v32, v35, v35
	ds_write_b16_d16_hi v66, v32 offset:22576
	v_add3_u32 v63, s16, v153, v134
	ds_read_b128 v[32:35], v63
	ds_read_b128 v[116:119], v63 offset:64
	s_waitcnt lgkmcnt(1)
	v_mfma_f32_16x16x32_bf16 v[32:35], v[32:35], v[40:43], 0
	ds_read_b128 v[108:111], v65
	s_waitcnt lgkmcnt(1)
	v_mfma_f32_16x16x32_bf16 v[32:35], v[116:119], v[56:59], v[32:35]
	ds_read_b128 v[116:119], v65 offset:64
	v_add3_u32 v65, s3, v152, v134
	s_mov_b32 s3, 0x18001000
	s_waitcnt lgkmcnt(1)
	v_mfma_f32_16x16x32_bf16 v[108:111], v[108:111], v[52:55], 0
	s_waitcnt lgkmcnt(0)
	v_mfma_f32_16x16x32_bf16 v[108:111], v[116:119], v[112:115], v[108:111]
	s_nop 7
	v_bfe_u32 v63, v108, 16, 1
	v_add3_u32 v63, v108, v63, s68
	v_mad_u64_u32 v[66:67], s[0:1], v50, s2, v[62:63]
	ds_write_b16_d16_hi v66, v63 offset:17408
	s_nop 0
	v_cvt_pk_bf16_f32 v63, v109, v109
	ds_write_b16_d16_hi v66, v63 offset:17680
	s_nop 0
	v_cvt_pk_bf16_f32 v63, v110, v110
	ds_write_b16_d16_hi v66, v63 offset:17952
	s_nop 0
	v_cvt_pk_bf16_f32 v63, v111, v111
	ds_write_b16_d16_hi v66, v63 offset:18224
	v_add3_u32 v63, s16, v152, v134
	ds_read_b128 v[108:111], v63
	s_waitcnt lgkmcnt(0)
	v_mfma_f32_16x16x32_bf16 v[40:43], v[108:111], v[40:43], 0
	ds_read_b128 v[108:111], v65
	s_waitcnt lgkmcnt(0)
	v_mfma_f32_16x16x32_bf16 v[52:55], v[108:111], v[52:55], 0
	ds_read_b128 v[108:111], v65 offset:64
	ds_read_b128 v[116:119], v63 offset:64
	v_add_u32_e32 v65, 0, v225
	v_add_u32_e32 v227, 0x24e00, v65
	s_waitcnt lgkmcnt(1)
	v_mfma_f32_16x16x32_bf16 v[52:55], v[108:111], v[112:115], v[52:55]
	s_waitcnt lgkmcnt(0)
	v_mfma_f32_16x16x32_bf16 v[40:43], v[116:119], v[56:59], v[40:43]
	s_nop 5
	v_bfe_u32 v63, v52, 16, 1
	v_add3_u32 v52, v52, v63, s68
	v_mad_u64_u32 v[62:63], s[0:1], v49, s2, v[62:63]
	ds_write_b16_d16_hi v62, v52 offset:17408
	s_nop 0
	v_cvt_pk_bf16_f32 v52, v53, v53
	ds_write_b16_d16_hi v62, v52 offset:17680
	s_nop 0
	v_cvt_pk_bf16_f32 v52, v54, v54
	ds_write_b16_d16_hi v62, v52 offset:17952
	s_nop 0
	v_cvt_pk_bf16_f32 v52, v55, v55
	ds_write_b16_d16_hi v62, v52 offset:18224
	s_waitcnt lgkmcnt(0)
	s_barrier
; #define LAS __attribute__((address_space(3)))
; DI unsigned pk2(float lo, float hi) { return f2bf(lo) | (f2bf(hi) << 16); }
; DI void lds_barrier() { asm volatile("s_waitcnt lgkmcnt(0)" ::: "memory"); __builtin_amdgcn_s_barrier(); asm volatile("" ::: "memory"); }
; #define MFMA16(a, b, c) __builtin_amdgcn_mfma_f32_16x16x32_bf16((a), (b), (c), 0, 0, 0)
; DI void gdn_unit(const Params& P, bf16_t* proj, const float* gb, int b, int h, LAS unsigned char* lds) {
;     ...
;         lds_barrier();
;         {
;             bf16x8 sb[4];
; #pragma unroll
;             for (int ks = 0; ks < 4; ++ks) sb[ks] = ldsfrag(lds + ST_OFF + (16 * wave + fr) * 272 + (ks * 32 + fq * 8) * 2);
; #pragma unroll
;             for (int tt = 0; tt < 4; ++tt) {
;                 f32x4 a = (f32x4){0.f, 0.f, 0.f, 0.f};
;                 bf16x8 wf[4];
; #pragma unroll
;                 for (int ks = 0; ks < 4; ++ks) wf[ks] = ldsfrag(lds + K_OFF + (tt * 16 + fr) * 272 + (ks * 32 + fq * 8) * 2);
;                 const f32x4 d4 = *(const LAS f32x4*)(djs + tt * 16 + fq * 4);
; #pragma unroll
;                 for (int ks = 0; ks < 4; ++ks) a = MFMA16(wf[ks], sb[ks], a);
;                 const f32x4 vn = uacc[tt] - a;
;                 u32x2 p0, p1;
;                 p0.x = pk2(vn[0], vn[1]); p0.y = pk2(vn[2], vn[3]);
;                 p1.x = pk2(vn[0] * d4[0], vn[1] * d4[1]); p1.y = pk2(vn[2] * d4[2], vn[3] * d4[3]);
;                 *(LAS u32x2*)(lds + VN_OFF + (16 * wave + fr) * 144 + (tt * 16 + fq * 4) * 2) = p0;
;                 *(LAS u32x2*)(lds + VNS_OFF + (16 * wave + fr) * 144 + (tt * 16 + fq * 4) * 2) = p1;
;             }
;         }
	ds_read_b128 v[108:111], v149 offset:17408
	s_add_i32 s0, 0, 0x16000
	v_add_u32_e32 v219, s0, v51
	v_add_u32_e32 v52, v219, v134
	ds_read_b128 v[112:115], v52
	ds_read_b128 v[54:57], v149 offset:17472
	ds_read_b128 v[116:119], v52 offset:64
	s_waitcnt lgkmcnt(2)
	v_mfma_f32_16x16x32_bf16 v[108:111], v[108:111], v[112:115], 0
	ds_read_b128 v[120:123], v149 offset:17536
	ds_read_b128 v[124:127], v52 offset:128
	ds_read_b128 v[128:131], v149 offset:17600
	v_add_u32_e32 v51, 0x24f00, v65
	s_add_u32 s0, s5, s14
	s_waitcnt lgkmcnt(3)
	v_mfma_f32_16x16x32_bf16 v[54:57], v[54:57], v[116:119], v[108:111]
	s_addc_u32 s1, s69, s15
	s_mov_b32 s2, 0x18003000
	s_nop 0
	ds_read_b128 v[108:111], v52 offset:192
	s_waitcnt lgkmcnt(2)
	v_mfma_f32_16x16x32_bf16 v[54:57], v[120:123], v[124:127], v[54:57]
	ds_read_b128 v[120:123], v51
	s_waitcnt lgkmcnt(1)
	v_mfma_f32_16x16x32_bf16 v[54:57], v[128:131], v[108:111], v[54:57]
	s_nop 7
	v_sub_f32_e32 v47, v47, v57
	v_sub_f32_e32 v45, v45, v55
	v_sub_f32_e32 v46, v46, v56
	s_nop 0
	v_sub_f32_e32 v44, v44, v54
	v_and_b32_sdwa v53, v46, v166 dst_sel:DWORD dst_unused:UNUSED_PAD src0_sel:WORD_1 src1_sel:DWORD
	s_nop 0
	v_cvt_pk_bf16_f32 v55, v47, v47
	v_and_b32_sdwa v54, v44, v166 dst_sel:DWORD dst_unused:UNUSED_PAD src0_sel:WORD_1 src1_sel:DWORD
	v_add3_u32 v53, v46, v53, s68
	v_cvt_pk_bf16_f32 v56, v45, v45
	v_and_b32_e32 v55, 0xffff0000, v55
	s_waitcnt lgkmcnt(0)
	v_pk_mul_f32 v[46:47], v[122:123], v[46:47]
	v_add3_u32 v54, v44, v54, s68
	v_and_b32_e32 v56, 0xffff0000, v56
	v_or_b32_sdwa v55, v55, v53 dst_sel:DWORD dst_unused:UNUSED_PAD src0_sel:DWORD src1_sel:WORD_1
	v_pk_mul_f32 v[44:45], v[120:121], v[44:45]
	v_and_b32_sdwa v53, v46, v166 dst_sel:DWORD dst_unused:UNUSED_PAD src0_sel:WORD_1 src1_sel:DWORD
	v_or_b32_sdwa v54, v56, v54 dst_sel:DWORD dst_unused:UNUSED_PAD src0_sel:DWORD src1_sel:WORD_1
	v_and_b32_sdwa v56, v44, v166 dst_sel:DWORD dst_unused:UNUSED_PAD src0_sel:WORD_1 src1_sel:DWORD
	v_add3_u32 v46, v46, v53, s68
	v_add3_u32 v44, v44, v56, s68
	v_cvt_pk_bf16_f32 v47, v47, v47
	v_cvt_pk_bf16_f32 v45, v45, v45
	v_and_b32_e32 v47, 0xffff0000, v47
	v_and_b32_e32 v53, 0xffff0000, v45
	v_or_b32_sdwa v45, v47, v46 dst_sel:DWORD dst_unused:UNUSED_PAD src0_sel:DWORD src1_sel:WORD_1
	v_add_u32_e32 v46, v48, v207
	v_or_b32_sdwa v44, v53, v44 dst_sel:DWORD dst_unused:UNUSED_PAD src0_sel:DWORD src1_sel:WORD_1
	ds_write_b64 v46, v[54:55] offset:53248
	v_add_u32_e32 v46, v151, v207
	ds_write_b64 v46, v[44:45]
	ds_read_b128 v[44:47], v149 offset:21760
	ds_read_b128 v[54:57], v149 offset:21824
	s_waitcnt lgkmcnt(1)
	v_mfma_f32_16x16x32_bf16 v[44:47], v[44:47], v[112:115], 0
	s_waitcnt lgkmcnt(0)
	v_mfma_f32_16x16x32_bf16 v[44:47], v[54:57], v[116:119], v[44:47]
	ds_read_b128 v[54:57], v149 offset:21888
	s_waitcnt lgkmcnt(0)
	v_mfma_f32_16x16x32_bf16 v[44:47], v[54:57], v[124:127], v[44:47]
	ds_read_b128 v[54:57], v149 offset:21952
	ds_read_b128 v[120:123], v51 offset:64
	s_waitcnt lgkmcnt(1)
	v_mfma_f32_16x16x32_bf16 v[44:47], v[54:57], v[108:111], v[44:47]
	s_nop 7
	v_sub_f32_e32 v36, v36, v44
	v_sub_f32_e32 v37, v37, v45
	v_sub_f32_e32 v39, v39, v47
	v_and_b32_sdwa v45, v36, v166 dst_sel:DWORD dst_unused:UNUSED_PAD src0_sel:WORD_1 src1_sel:DWORD
	v_sub_f32_e32 v38, v38, v46
	v_add3_u32 v46, v36, v45, s68
	s_nop 0
	s_nop 0
	v_and_b32_sdwa v44, v38, v166 dst_sel:DWORD dst_unused:UNUSED_PAD src0_sel:WORD_1 src1_sel:DWORD
	v_cvt_pk_bf16_f32 v45, v39, v39
	v_cvt_pk_bf16_f32 v47, v37, v37
	v_add3_u32 v44, v38, v44, s68
	v_and_b32_e32 v45, 0xffff0000, v45
	v_and_b32_e32 v47, 0xffff0000, v47
	s_waitcnt lgkmcnt(0)
	v_pk_mul_f32 v[38:39], v[122:123], v[38:39]
	v_or_b32_sdwa v45, v45, v44 dst_sel:DWORD dst_unused:UNUSED_PAD src0_sel:DWORD src1_sel:WORD_1
	v_or_b32_sdwa v44, v47, v46 dst_sel:DWORD dst_unused:UNUSED_PAD src0_sel:DWORD src1_sel:WORD_1
	v_pk_mul_f32 v[36:37], v[120:121], v[36:37]
	v_and_b32_sdwa v46, v38, v166 dst_sel:DWORD dst_unused:UNUSED_PAD src0_sel:WORD_1 src1_sel:DWORD
	v_and_b32_sdwa v47, v36, v166 dst_sel:DWORD dst_unused:UNUSED_PAD src0_sel:WORD_1 src1_sel:DWORD
	v_add3_u32 v38, v38, v46, s68
	v_add3_u32 v36, v36, v47, s68
	v_cvt_pk_bf16_f32 v39, v39, v39
	v_cvt_pk_bf16_f32 v37, v37, v37
	v_and_b32_e32 v39, 0xffff0000, v39
	v_and_b32_e32 v46, 0xffff0000, v37
	v_or_b32_sdwa v37, v39, v38 dst_sel:DWORD dst_unused:UNUSED_PAD src0_sel:DWORD src1_sel:WORD_1
	v_lshl_add_u32 v38, v205, 1, 32
	v_or_b32_sdwa v36, v46, v36 dst_sel:DWORD dst_unused:UNUSED_PAD src0_sel:DWORD src1_sel:WORD_1
	v_add_u32_e32 v39, v48, v38
	v_add_u32_e32 v38, v151, v38
	ds_write_b64 v39, v[44:45] offset:53248
	ds_write_b64 v38, v[36:37]
	ds_read_b128 v[36:39], v149 offset:26112
	ds_read_b128 v[44:47], v149 offset:26176
	s_waitcnt lgkmcnt(1)
	v_mfma_f32_16x16x32_bf16 v[36:39], v[36:39], v[112:115], 0
	s_waitcnt lgkmcnt(0)
	v_mfma_f32_16x16x32_bf16 v[36:39], v[44:47], v[116:119], v[36:39]
	ds_read_b128 v[44:47], v149 offset:26240
	s_waitcnt lgkmcnt(0)
	v_mfma_f32_16x16x32_bf16 v[36:39], v[44:47], v[124:127], v[36:39]
	ds_read_b128 v[44:47], v149 offset:26304
	ds_read_b128 v[54:57], v51 offset:128
	s_waitcnt lgkmcnt(1)
	v_mfma_f32_16x16x32_bf16 v[36:39], v[44:47], v[108:111], v[36:39]
	s_nop 7
	v_sub_f32_e32 v32, v32, v36
	v_sub_f32_e32 v33, v33, v37
	v_sub_f32_e32 v35, v35, v39
	v_and_b32_sdwa v37, v32, v166 dst_sel:DWORD dst_unused:UNUSED_PAD src0_sel:WORD_1 src1_sel:DWORD
	v_sub_f32_e32 v34, v34, v38
	v_add3_u32 v38, v32, v37, s68
	s_nop 0
	s_nop 0
	v_and_b32_sdwa v36, v34, v166 dst_sel:DWORD dst_unused:UNUSED_PAD src0_sel:WORD_1 src1_sel:DWORD
	v_cvt_pk_bf16_f32 v37, v35, v35
	v_cvt_pk_bf16_f32 v39, v33, v33
	v_add3_u32 v36, v34, v36, s68
	v_and_b32_e32 v37, 0xffff0000, v37
	v_and_b32_e32 v39, 0xffff0000, v39
	s_waitcnt lgkmcnt(0)
; #define LAS __attribute__((address_space(3)))
; DI unsigned pk2(float lo, float hi) { return f2bf(lo) | (f2bf(hi) << 16); }
; DI void lds_barrier() { asm volatile("s_waitcnt lgkmcnt(0)" ::: "memory"); __builtin_amdgcn_s_barrier(); asm volatile("" ::: "memory"); }
; #define MFMA16(a, b, c) __builtin_amdgcn_mfma_f32_16x16x32_bf16((a), (b), (c), 0, 0, 0)
; DI void gdn_unit(const Params& P, bf16_t* proj, const float* gb, int b, int h, LAS unsigned char* lds) {
;     ...
; #pragma unroll
;                 for (int ks = 0; ks < 4; ++ks) a = MFMA16(wf[ks], sb[ks], a);
;                 const f32x4 vn = uacc[tt] - a;
;                 u32x2 p0, p1;
;                 p0.x = pk2(vn[0], vn[1]); p0.y = pk2(vn[2], vn[3]);
;                 p1.x = pk2(vn[0] * d4[0], vn[1] * d4[1]); p1.y = pk2(vn[2] * d4[2], vn[3] * d4[3]);
;                 *(LAS u32x2*)(lds + VN_OFF + (16 * wave + fr) * 144 + (tt * 16 + fq * 4) * 2) = p0;
;                 *(LAS u32x2*)(lds + VNS_OFF + (16 * wave + fr) * 144 + (tt * 16 + fq * 4) * 2) = p1;
;             }
;         }
;         lds_barrier();
;         f32x4 oacc[4];
;         unsigned zr[4][4];
;         const bf16_t* zbase = proj + (size_t)t0 * PJ1 + 3072 + h * 128 + 16 * wave;
;         const int zoffl = fq * 4 * PJ1 + fr;
;         {
; #pragma unroll
;             for (int tt = 0; tt < 4; ++tt)
; #pragma unroll
;                 for (int jj = 0; jj < 4; ++jj) zr[tt][jj] = zbase[(tt * 16 + jj) * PJ1 + zoffl];
	v_pk_mul_f32 v[34:35], v[56:57], v[34:35]
	v_or_b32_sdwa v37, v37, v36 dst_sel:DWORD dst_unused:UNUSED_PAD src0_sel:DWORD src1_sel:WORD_1
	v_or_b32_sdwa v36, v39, v38 dst_sel:DWORD dst_unused:UNUSED_PAD src0_sel:DWORD src1_sel:WORD_1
	v_pk_mul_f32 v[32:33], v[54:55], v[32:33]
	v_and_b32_sdwa v38, v34, v166 dst_sel:DWORD dst_unused:UNUSED_PAD src0_sel:WORD_1 src1_sel:DWORD
	v_and_b32_sdwa v39, v32, v166 dst_sel:DWORD dst_unused:UNUSED_PAD src0_sel:WORD_1 src1_sel:DWORD
	v_add3_u32 v34, v34, v38, s68
	v_add3_u32 v32, v32, v39, s68
	v_cvt_pk_bf16_f32 v35, v35, v35
	v_cvt_pk_bf16_f32 v33, v33, v33
	v_and_b32_e32 v35, 0xffff0000, v35
	v_and_b32_e32 v38, 0xffff0000, v33
	v_or_b32_sdwa v33, v35, v34 dst_sel:DWORD dst_unused:UNUSED_PAD src0_sel:DWORD src1_sel:WORD_1
	v_lshlrev_b32_e32 v34, 1, v50
	v_or_b32_sdwa v32, v38, v32 dst_sel:DWORD dst_unused:UNUSED_PAD src0_sel:DWORD src1_sel:WORD_1
	v_add_u32_e32 v35, v48, v34
	v_add_u32_e32 v34, v151, v34
	ds_write_b64 v35, v[36:37] offset:53248
	ds_write_b64 v34, v[32:33]
	ds_read_b128 v[32:35], v149 offset:30464
	ds_read_b128 v[36:39], v149 offset:30528
	s_waitcnt lgkmcnt(1)
	v_mfma_f32_16x16x32_bf16 v[32:35], v[32:35], v[112:115], 0
	s_waitcnt lgkmcnt(0)
	v_mfma_f32_16x16x32_bf16 v[32:35], v[36:39], v[116:119], v[32:35]
	ds_read_b128 v[36:39], v149 offset:30592
	s_waitcnt lgkmcnt(0)
	v_mfma_f32_16x16x32_bf16 v[32:35], v[36:39], v[124:127], v[32:35]
	ds_read_b128 v[36:39], v149 offset:30656
	ds_read_b128 v[44:47], v51 offset:192
	s_waitcnt lgkmcnt(1)
	v_mfma_f32_16x16x32_bf16 v[32:35], v[36:39], v[108:111], v[32:35]
	s_nop 7
	v_sub_f32_e32 v32, v40, v32
	v_sub_f32_e32 v33, v41, v33
	v_sub_f32_e32 v35, v43, v35
	v_and_b32_sdwa v37, v32, v166 dst_sel:DWORD dst_unused:UNUSED_PAD src0_sel:WORD_1 src1_sel:DWORD
	v_sub_f32_e32 v34, v42, v34
	v_add3_u32 v38, v32, v37, s68
	s_nop 0
	s_nop 0
	v_and_b32_sdwa v36, v34, v166 dst_sel:DWORD dst_unused:UNUSED_PAD src0_sel:WORD_1 src1_sel:DWORD
	v_cvt_pk_bf16_f32 v37, v35, v35
	v_cvt_pk_bf16_f32 v39, v33, v33
	v_add3_u32 v36, v34, v36, s68
	v_and_b32_e32 v37, 0xffff0000, v37
	v_and_b32_e32 v39, 0xffff0000, v39
	s_waitcnt lgkmcnt(0)
	v_pk_mul_f32 v[34:35], v[46:47], v[34:35]
	v_or_b32_sdwa v37, v37, v36 dst_sel:DWORD dst_unused:UNUSED_PAD src0_sel:DWORD src1_sel:WORD_1
	v_or_b32_sdwa v36, v39, v38 dst_sel:DWORD dst_unused:UNUSED_PAD src0_sel:DWORD src1_sel:WORD_1
	v_pk_mul_f32 v[32:33], v[44:45], v[32:33]
	v_and_b32_sdwa v38, v34, v166 dst_sel:DWORD dst_unused:UNUSED_PAD src0_sel:WORD_1 src1_sel:DWORD
	v_and_b32_sdwa v39, v32, v166 dst_sel:DWORD dst_unused:UNUSED_PAD src0_sel:WORD_1 src1_sel:DWORD
	v_add3_u32 v34, v34, v38, s68
	v_add3_u32 v32, v32, v39, s68
	v_cvt_pk_bf16_f32 v35, v35, v35
	v_cvt_pk_bf16_f32 v33, v33, v33
	v_and_b32_e32 v35, 0xffff0000, v35
	v_and_b32_e32 v38, 0xffff0000, v33
	v_or_b32_sdwa v33, v35, v34 dst_sel:DWORD dst_unused:UNUSED_PAD src0_sel:DWORD src1_sel:WORD_1
	v_lshlrev_b32_e32 v34, 1, v49
	v_or_b32_sdwa v32, v38, v32 dst_sel:DWORD dst_unused:UNUSED_PAD src0_sel:DWORD src1_sel:WORD_1
	v_add_u32_e32 v35, v48, v34
	v_add_u32_e32 v34, v151, v34
	ds_write_b64 v34, v[32:33]
	v_lshl_or_b32 v32, v61, 14, v148
	v_ashrrev_i32_e32 v33, 31, v32
	v_lshl_add_u64 v[118:119], v[32:33], 1, s[0:1]
	ds_write_b64 v35, v[36:37] offset:53248
	v_add_co_u32_e32 v34, vcc, s3, v118
	s_waitcnt lgkmcnt(0)
	s_barrier
	s_nop 0
	v_addc_co_u32_e32 v35, vcc, 0, v119, vcc
	global_load_ushort v223, v[34:35], off offset:2048
	v_add_co_u32_e32 v34, vcc, s2, v118
	s_mov_b32 s2, 0x18005000
	s_nop 0
	v_addc_co_u32_e32 v35, vcc, 0, v119, vcc
	global_load_ushort v222, v[34:35], off offset:2048
	v_add_co_u32_e32 v34, vcc, s2, v118
	s_mov_b32 s2, 0x18007000
	s_nop 0
	v_addc_co_u32_e32 v35, vcc, 0, v119, vcc
	global_load_ushort v221, v[34:35], off offset:2048
	v_add_co_u32_e32 v34, vcc, s2, v118
	s_nop 1
	v_addc_co_u32_e32 v35, vcc, 0, v119, vcc
	global_load_ushort v220, v[34:35], off offset:2048
	v_add_u32_e32 v34, 0x10000, v32
	v_ashrrev_i32_e32 v35, 31, v34
	v_lshl_add_u64 v[120:121], v[34:35], 1, s[0:1]
	v_add_co_u32_e32 v34, vcc, s3, v120
	s_nop 1
	v_addc_co_u32_e32 v35, vcc, 0, v121, vcc
	global_load_ushort v218, v[34:35], off offset:2048
	v_add_u32_e32 v34, 0x11000, v32
	v_ashrrev_i32_e32 v35, 31, v34
	v_lshl_add_u64 v[124:125], v[34:35], 1, s[0:1]
	v_add_co_u32_e32 v34, vcc, s3, v124
	s_nop 1
	v_addc_co_u32_e32 v35, vcc, 0, v125, vcc
	global_load_ushort v217, v[34:35], off offset:2048
	v_add_u32_e32 v34, 0x12000, v32
	v_ashrrev_i32_e32 v35, 31, v34
	v_lshl_add_u64 v[116:117], v[34:35], 1, s[0:1]
	v_add_co_u32_e32 v34, vcc, s3, v116
	s_nop 1
	v_addc_co_u32_e32 v35, vcc, 0, v117, vcc
	global_load_ushort v216, v[34:35], off offset:2048
	v_add_u32_e32 v34, 0x13000, v32
	v_ashrrev_i32_e32 v35, 31, v34
	v_lshl_add_u64 v[122:123], v[34:35], 1, s[0:1]
	v_add_co_u32_e32 v34, vcc, s3, v122
	s_nop 1
	v_addc_co_u32_e32 v35, vcc, 0, v123, vcc
	global_load_ushort v215, v[34:35], off offset:2048
	v_add_u32_e32 v34, 0x20000, v32
	v_ashrrev_i32_e32 v35, 31, v34
	v_lshl_add_u64 v[128:129], v[34:35], 1, s[0:1]
	v_add_co_u32_e32 v34, vcc, s3, v128
	s_nop 1
	v_addc_co_u32_e32 v35, vcc, 0, v129, vcc
	global_load_ushort v214, v[34:35], off offset:2048
	v_add_u32_e32 v34, 0x21000, v32
	v_ashrrev_i32_e32 v35, 31, v34
	v_lshl_add_u64 v[126:127], v[34:35], 1, s[0:1]
	v_add_co_u32_e32 v34, vcc, s3, v126
	s_nop 1
	v_addc_co_u32_e32 v35, vcc, 0, v127, vcc
	global_load_ushort v213, v[34:35], off offset:2048
	v_add_u32_e32 v34, 0x22000, v32
	v_ashrrev_i32_e32 v35, 31, v34
	v_lshl_add_u64 v[130:131], v[34:35], 1, s[0:1]
	v_add_co_u32_e32 v34, vcc, s3, v130
	s_nop 1
	v_addc_co_u32_e32 v35, vcc, 0, v131, vcc
; #define LAS __attribute__((address_space(3)))
; #define MFMA16(a, b, c) __builtin_amdgcn_mfma_f32_16x16x32_bf16((a), (b), (c), 0, 0, 0)
; DI float row16_sum(float v) { v += dppf<0xB1>(v); v += dppf<0x4E>(v); v += dppf<0x141>(v); v += dppf<0x140>(v); return v; }
; DI void gdn_unit(const Params& P, bf16_t* proj, const float* gb, int b, int h, LAS unsigned char* lds) {
;     ...
;         f32x4 oacc[4];
;         unsigned zr[4][4];
;         const bf16_t* zbase = proj + (size_t)t0 * PJ1 + 3072 + h * 128 + 16 * wave;
;         const int zoffl = fq * 4 * PJ1 + fr;
;         {
; #pragma unroll
;             for (int tt = 0; tt < 4; ++tt)
; #pragma unroll
;                 for (int jj = 0; jj < 4; ++jj) zr[tt][jj] = zbase[(tt * 16 + jj) * PJ1 + zoffl];
;             bf16x8 sb[4], vnb[2];
; #pragma unroll
;             for (int ks = 0; ks < 4; ++ks) sb[ks] = ldsfrag(lds + ST_OFF + (16 * wave + fr) * 272 + (ks * 32 + fq * 8) * 2);
; #pragma unroll
;             for (int ks = 0; ks < 2; ++ks) vnb[ks] = ldsfrag(lds + VN_OFF + (16 * wave + fr) * 144 + (ks * 32 + fq * 8) * 2);
; #pragma unroll
;             for (int tt = 0; tt < 4; ++tt) {
;                 f32x4 a = (f32x4){0.f, 0.f, 0.f, 0.f};
;                 bf16x8 qf[4], atf[2];
; #pragma unroll
;                 for (int ks = 0; ks < 4; ++ks) qf[ks] = ldsfrag(lds + Q_OFF + (tt * 16 + fr) * 272 + (ks * 32 + fq * 8) * 2);
; #pragma unroll
;                 for (int ks = 0; ks < 2; ++ks) atf[ks] = ldsfrag(lds + ATT_OFF + (tt * 16 + fr) * 144 + (ks * 32 + fq * 8) * 2);
;                 const f32x4 e4 = *(const LAS f32x4*)(egcs + tt * 16 + fq * 4);
; #pragma unroll
;                 for (int ks = 0; ks < 4; ++ks) a = MFMA16(qf[ks], sb[ks], a);
;                 a = a * e4;
; #pragma unroll
;                 for (int ks = 0; ks < 2; ++ks) a = MFMA16(atf[ks], vnb[ks], a);
;                 oacc[tt] = a;
; #pragma unroll
;                 for (int jj = 0; jj < 4; ++jj) {
;                     const float s = row16_sum(a[jj] * a[jj]);
;                     if (fr == 0) part[wave * 64 + tt * 16 + fq * 4 + jj] = s;
;                 }
;             }
	global_load_ushort v212, v[34:35], off offset:2048
	v_add_u32_e32 v34, 0x23000, v32
	v_ashrrev_i32_e32 v35, 31, v34
	v_lshl_add_u64 v[132:133], v[34:35], 1, s[0:1]
	v_add_co_u32_e32 v34, vcc, s3, v132
	s_nop 1
	v_addc_co_u32_e32 v35, vcc, 0, v133, vcc
	global_load_ushort v211, v[34:35], off offset:2048
	v_add_u32_e32 v34, 0x30000, v32
	v_ashrrev_i32_e32 v35, 31, v34
	v_lshl_add_u64 v[108:109], v[34:35], 1, s[0:1]
	v_add_co_u32_e32 v34, vcc, s3, v108
	s_nop 1
	v_addc_co_u32_e32 v35, vcc, 0, v109, vcc
	global_load_ushort v210, v[34:35], off offset:2048
	v_add_u32_e32 v34, 0x31000, v32
	v_ashrrev_i32_e32 v35, 31, v34
	v_lshl_add_u64 v[110:111], v[34:35], 1, s[0:1]
	v_add_co_u32_e32 v34, vcc, s3, v110
	s_nop 1
	v_addc_co_u32_e32 v35, vcc, 0, v111, vcc
	global_load_ushort v209, v[34:35], off offset:2048
	v_add_u32_e32 v34, 0x32000, v32
	v_ashrrev_i32_e32 v35, 31, v34
	v_lshl_add_u64 v[112:113], v[34:35], 1, s[0:1]
	v_add_u32_e32 v32, 0x33000, v32
	v_add_co_u32_e32 v34, vcc, s3, v112
	v_ashrrev_i32_e32 v33, 31, v32
	s_nop 0
	v_addc_co_u32_e32 v35, vcc, 0, v113, vcc
	v_lshl_add_u64 v[114:115], v[32:33], 1, s[0:1]
	v_add_co_u32_e32 v32, vcc, s3, v114
	global_load_ushort v208, v[34:35], off offset:2048
	s_nop 0
	v_addc_co_u32_e32 v33, vcc, 0, v115, vcc
	global_load_ushort v206, v[32:33], off offset:2048
	ds_read_b128 v[32:35], v149
	ds_read_b128 v[56:59], v52
	ds_read_b128 v[36:39], v149 offset:64
	ds_read_b128 v[48:51], v52 offset:64
	ds_read_b128 v[40:43], v149 offset:128
	s_waitcnt lgkmcnt(3)
	v_mfma_f32_16x16x32_bf16 v[32:35], v[32:35], v[56:59], 0
	ds_read_b128 v[60:63], v52 offset:128
	ds_read_b128 v[52:55], v52 offset:192
	ds_read_b128 v[44:47], v149 offset:192
	v_readlane_b32 s0, v255, 8
	ds_read_b128 v[228:231], v227
	s_waitcnt lgkmcnt(5)
	v_mfma_f32_16x16x32_bf16 v[36:39], v[36:39], v[48:51], v[32:35]
	v_add_u32_e32 v226, s0, v134
	v_mad_u32_u24 v66, v148, s37, v226
	v_cmp_eq_u32_e32 vcc, 0, v148
	ds_read_b128 v[32:35], v64 offset:53248
	s_waitcnt lgkmcnt(4)
	v_mfma_f32_16x16x32_bf16 v[36:39], v[40:43], v[60:63], v[36:39]
	ds_read_b128 v[40:43], v66
	v_add_u32_e32 v148, s49, v225
	s_waitcnt lgkmcnt(3)
	v_mfma_f32_16x16x32_bf16 v[36:39], v[44:47], v[52:55], v[36:39]
	ds_read_b128 v[44:47], v66 offset:64
	ds_read_b128 v[64:67], v64 offset:53312
	s_waitcnt lgkmcnt(4)
	s_nop 4
	v_pk_mul_f32 v[38:39], v[230:231], v[38:39]
	v_pk_mul_f32 v[36:37], v[228:229], v[36:37]
	s_waitcnt lgkmcnt(2)
	s_nop 0
	v_mfma_f32_16x16x32_bf16 v[36:39], v[40:43], v[32:35], v[36:39]
	s_waitcnt lgkmcnt(0)
	v_mfma_f32_16x16x32_bf16 v[44:47], v[44:47], v[64:67], v[36:39]
	s_nop 7
	v_mul_f32_e32 v36, v44, v44
	s_nop 1
	v_mov_b32_dpp v36, v36 quad_perm:[1,0,3,2] row_mask:0xf bank_mask:0xf bound_ctrl:1
	v_fmac_f32_e32 v36, v44, v44
	s_nop 1
	v_add_f32_dpp v36, v36, v36 quad_perm:[2,3,0,1] row_mask:0xf bank_mask:0xf bound_ctrl:1
	s_nop 1
	v_add_f32_dpp v36, v36, v36 row_half_mirror row_mask:0xf bank_mask:0xf bound_ctrl:1
	s_nop 1
	v_mov_b32_dpp v37, v36 row_mirror row_mask:0xf bank_mask:0xf bound_ctrl:1
	s_and_saveexec_b64 s[0:1], vcc
	v_add_f32_e32 v36, v36, v37
	ds_write_b32 v148, v36
	s_or_b64 exec, exec, s[0:1]
	v_mul_f32_e32 v36, v45, v45
	s_nop 1
	v_mov_b32_dpp v36, v36 quad_perm:[1,0,3,2] row_mask:0xf bank_mask:0xf bound_ctrl:1
	v_fmac_f32_e32 v36, v45, v45
	s_nop 1
	v_add_f32_dpp v36, v36, v36 quad_perm:[2,3,0,1] row_mask:0xf bank_mask:0xf bound_ctrl:1
	s_nop 1
	v_add_f32_dpp v36, v36, v36 row_half_mirror row_mask:0xf bank_mask:0xf bound_ctrl:1
	s_nop 1
	v_mov_b32_dpp v37, v36 row_mirror row_mask:0xf bank_mask:0xf bound_ctrl:1
	s_and_saveexec_b64 s[0:1], vcc
	v_add_f32_e32 v36, v36, v37
	ds_write_b32 v148, v36 offset:4
	s_or_b64 exec, exec, s[0:1]
	v_mul_f32_e32 v36, v46, v46
	s_nop 1
	v_mov_b32_dpp v36, v36 quad_perm:[1,0,3,2] row_mask:0xf bank_mask:0xf bound_ctrl:1
	v_fmac_f32_e32 v36, v46, v46
	s_nop 1
	v_add_f32_dpp v36, v36, v36 quad_perm:[2,3,0,1] row_mask:0xf bank_mask:0xf bound_ctrl:1
	s_nop 1
	v_add_f32_dpp v36, v36, v36 row_half_mirror row_mask:0xf bank_mask:0xf bound_ctrl:1
	s_nop 1
	v_mov_b32_dpp v37, v36 row_mirror row_mask:0xf bank_mask:0xf bound_ctrl:1
	s_and_saveexec_b64 s[0:1], vcc
	v_add_f32_e32 v36, v36, v37
	ds_write_b32 v148, v36 offset:8
	s_or_b64 exec, exec, s[0:1]
	v_mul_f32_e32 v36, v47, v47
	s_nop 1
	v_mov_b32_dpp v36, v36 quad_perm:[1,0,3,2] row_mask:0xf bank_mask:0xf bound_ctrl:1
	v_fmac_f32_e32 v36, v47, v47
	s_nop 1
	v_add_f32_dpp v36, v36, v36 quad_perm:[2,3,0,1] row_mask:0xf bank_mask:0xf bound_ctrl:1
	s_nop 1
	v_add_f32_dpp v36, v36, v36 row_half_mirror row_mask:0xf bank_mask:0xf bound_ctrl:1
	s_nop 1
	v_mov_b32_dpp v37, v36 row_mirror row_mask:0xf bank_mask:0xf bound_ctrl:1
	s_and_saveexec_b64 s[0:1], vcc
	v_add_f32_e32 v36, v36, v37
	ds_write_b32 v148, v36 offset:12
	s_or_b64 exec, exec, s[0:1]
	ds_read_b128 v[36:39], v149 offset:4352
	ds_read_b128 v[40:43], v149 offset:4416
	v_add_u32_e32 v138, v226, v224
	ds_read_b128 v[228:231], v138
	s_waitcnt lgkmcnt(2)
	v_mfma_f32_16x16x32_bf16 v[36:39], v[36:39], v[56:59], 0
	s_waitcnt lgkmcnt(1)
	v_mfma_f32_16x16x32_bf16 v[36:39], v[40:43], v[48:51], v[36:39]
	ds_read_b128 v[40:43], v149 offset:4480
	s_waitcnt lgkmcnt(0)
	v_mfma_f32_16x16x32_bf16 v[36:39], v[40:43], v[60:63], v[36:39]
	ds_read_b128 v[40:43], v149 offset:4544
	s_waitcnt lgkmcnt(0)
	v_mfma_f32_16x16x32_bf16 v[36:39], v[40:43], v[52:55], v[36:39]
	ds_read_b128 v[40:43], v227 offset:64
	s_waitcnt lgkmcnt(0)
	s_nop 5
	v_pk_mul_f32 v[38:39], v[42:43], v[38:39]
	v_pk_mul_f32 v[36:37], v[40:41], v[36:37]
	ds_read_b128 v[40:43], v138 offset:64
	s_nop 0
	v_mfma_f32_16x16x32_bf16 v[36:39], v[228:231], v[32:35], v[36:39]
	s_waitcnt lgkmcnt(0)
; #define LAS __attribute__((address_space(3)))
; #define MFMA16(a, b, c) __builtin_amdgcn_mfma_f32_16x16x32_bf16((a), (b), (c), 0, 0, 0)
; DI float row16_sum(float v) { v += dppf<0xB1>(v); v += dppf<0x4E>(v); v += dppf<0x141>(v); v += dppf<0x140>(v); return v; }
; DI void gdn_unit(const Params& P, bf16_t* proj, const float* gb, int b, int h, LAS unsigned char* lds) {
;     ...
;             for (int tt = 0; tt < 4; ++tt) {
;                 f32x4 a = (f32x4){0.f, 0.f, 0.f, 0.f};
;                 bf16x8 qf[4], atf[2];
; #pragma unroll
;                 for (int ks = 0; ks < 4; ++ks) qf[ks] = ldsfrag(lds + Q_OFF + (tt * 16 + fr) * 272 + (ks * 32 + fq * 8) * 2);
; #pragma unroll
;                 for (int ks = 0; ks < 2; ++ks) atf[ks] = ldsfrag(lds + ATT_OFF + (tt * 16 + fr) * 144 + (ks * 32 + fq * 8) * 2);
;                 const f32x4 e4 = *(const LAS f32x4*)(egcs + tt * 16 + fq * 4);
; #pragma unroll
;                 for (int ks = 0; ks < 4; ++ks) a = MFMA16(qf[ks], sb[ks], a);
;                 a = a * e4;
; #pragma unroll
;                 for (int ks = 0; ks < 2; ++ks) a = MFMA16(atf[ks], vnb[ks], a);
;                 oacc[tt] = a;
; #pragma unroll
;                 for (int jj = 0; jj < 4; ++jj) {
;                     const float s = row16_sum(a[jj] * a[jj]);
;                     if (fr == 0) part[wave * 64 + tt * 16 + fq * 4 + jj] = s;
;                 }
;             }
	v_mfma_f32_16x16x32_bf16 v[40:43], v[40:43], v[64:67], v[36:39]
	s_nop 7
	v_mul_f32_e32 v36, v40, v40
	s_nop 1
	v_mov_b32_dpp v36, v36 quad_perm:[1,0,3,2] row_mask:0xf bank_mask:0xf bound_ctrl:1
	v_fmac_f32_e32 v36, v40, v40
	s_nop 1
	v_add_f32_dpp v36, v36, v36 quad_perm:[2,3,0,1] row_mask:0xf bank_mask:0xf bound_ctrl:1
	s_nop 1
	v_add_f32_dpp v36, v36, v36 row_half_mirror row_mask:0xf bank_mask:0xf bound_ctrl:1
	s_nop 1
	v_mov_b32_dpp v37, v36 row_mirror row_mask:0xf bank_mask:0xf bound_ctrl:1
	s_and_saveexec_b64 s[0:1], vcc
	v_add_f32_e32 v36, v36, v37
	ds_write_b32 v148, v36 offset:64
	s_or_b64 exec, exec, s[0:1]
	v_mul_f32_e32 v36, v41, v41
	s_nop 1
	v_mov_b32_dpp v36, v36 quad_perm:[1,0,3,2] row_mask:0xf bank_mask:0xf bound_ctrl:1
	v_fmac_f32_e32 v36, v41, v41
	s_nop 1
	v_add_f32_dpp v36, v36, v36 quad_perm:[2,3,0,1] row_mask:0xf bank_mask:0xf bound_ctrl:1
	s_nop 1
	v_add_f32_dpp v36, v36, v36 row_half_mirror row_mask:0xf bank_mask:0xf bound_ctrl:1
	s_nop 1
	v_mov_b32_dpp v37, v36 row_mirror row_mask:0xf bank_mask:0xf bound_ctrl:1
	s_and_saveexec_b64 s[0:1], vcc
	v_add_f32_e32 v36, v36, v37
	ds_write_b32 v148, v36 offset:68
	s_or_b64 exec, exec, s[0:1]
	v_mul_f32_e32 v36, v42, v42
	s_nop 1
	v_mov_b32_dpp v36, v36 quad_perm:[1,0,3,2] row_mask:0xf bank_mask:0xf bound_ctrl:1
	v_fmac_f32_e32 v36, v42, v42
	s_nop 1
	v_add_f32_dpp v36, v36, v36 quad_perm:[2,3,0,1] row_mask:0xf bank_mask:0xf bound_ctrl:1
	s_nop 1
	v_add_f32_dpp v36, v36, v36 row_half_mirror row_mask:0xf bank_mask:0xf bound_ctrl:1
	s_nop 1
	v_mov_b32_dpp v37, v36 row_mirror row_mask:0xf bank_mask:0xf bound_ctrl:1
	s_and_saveexec_b64 s[0:1], vcc
	v_add_f32_e32 v36, v36, v37
	ds_write_b32 v148, v36 offset:72
	s_or_b64 exec, exec, s[0:1]
	v_mul_f32_e32 v36, v43, v43
	s_nop 1
	v_mov_b32_dpp v36, v36 quad_perm:[1,0,3,2] row_mask:0xf bank_mask:0xf bound_ctrl:1
	v_fmac_f32_e32 v36, v43, v43
	s_nop 1
	v_add_f32_dpp v36, v36, v36 quad_perm:[2,3,0,1] row_mask:0xf bank_mask:0xf bound_ctrl:1
	s_nop 1
	v_add_f32_dpp v36, v36, v36 row_half_mirror row_mask:0xf bank_mask:0xf bound_ctrl:1
	s_nop 1
	v_mov_b32_dpp v37, v36 row_mirror row_mask:0xf bank_mask:0xf bound_ctrl:1
	s_and_saveexec_b64 s[0:1], vcc
	v_add_f32_e32 v36, v36, v37
	ds_write_b32 v148, v36 offset:76
	s_or_b64 exec, exec, s[0:1]
	ds_read_b128 v[36:39], v149 offset:8704
	ds_read_b128 v[228:231], v149 offset:8768
	v_add_u32_e32 v138, v226, v153
	ds_read_b128 v[232:235], v138
	s_waitcnt lgkmcnt(2)
	v_mfma_f32_16x16x32_bf16 v[36:39], v[36:39], v[56:59], 0
	s_waitcnt lgkmcnt(1)
	v_mfma_f32_16x16x32_bf16 v[36:39], v[228:231], v[48:51], v[36:39]
	ds_read_b128 v[228:231], v149 offset:8832
	s_waitcnt lgkmcnt(0)
	v_mfma_f32_16x16x32_bf16 v[36:39], v[228:231], v[60:63], v[36:39]
	ds_read_b128 v[228:231], v149 offset:8896
	s_waitcnt lgkmcnt(0)
	v_mfma_f32_16x16x32_bf16 v[36:39], v[228:231], v[52:55], v[36:39]
	ds_read_b128 v[228:231], v227 offset:128
	s_waitcnt lgkmcnt(0)
	s_nop 5
	v_pk_mul_f32 v[38:39], v[230:231], v[38:39]
	v_pk_mul_f32 v[36:37], v[228:229], v[36:37]
	ds_read_b128 v[228:231], v138 offset:64
	s_nop 0
	v_mfma_f32_16x16x32_bf16 v[36:39], v[232:235], v[32:35], v[36:39]
	s_waitcnt lgkmcnt(0)
; #define LAS __attribute__((address_space(3)))
; #define MFMA16(a, b, c) __builtin_amdgcn_mfma_f32_16x16x32_bf16((a), (b), (c), 0, 0, 0)
; DI float row16_sum(float v) { v += dppf<0xB1>(v); v += dppf<0x4E>(v); v += dppf<0x141>(v); v += dppf<0x140>(v); return v; }
; DI void gdn_unit(const Params& P, bf16_t* proj, const float* gb, int b, int h, LAS unsigned char* lds) {
;     ...
;             for (int tt = 0; tt < 4; ++tt) {
;                 f32x4 a = (f32x4){0.f, 0.f, 0.f, 0.f};
;                 bf16x8 qf[4], atf[2];
; #pragma unroll
;                 for (int ks = 0; ks < 4; ++ks) qf[ks] = ldsfrag(lds + Q_OFF + (tt * 16 + fr) * 272 + (ks * 32 + fq * 8) * 2);
; #pragma unroll
;                 for (int ks = 0; ks < 2; ++ks) atf[ks] = ldsfrag(lds + ATT_OFF + (tt * 16 + fr) * 144 + (ks * 32 + fq * 8) * 2);
;                 const f32x4 e4 = *(const LAS f32x4*)(egcs + tt * 16 + fq * 4);
; #pragma unroll
;                 for (int ks = 0; ks < 4; ++ks) a = MFMA16(qf[ks], sb[ks], a);
;                 a = a * e4;
; #pragma unroll
;                 for (int ks = 0; ks < 2; ++ks) a = MFMA16(atf[ks], vnb[ks], a);
;                 oacc[tt] = a;
; #pragma unroll
;                 for (int jj = 0; jj < 4; ++jj) {
;                     const float s = row16_sum(a[jj] * a[jj]);
;                     if (fr == 0) part[wave * 64 + tt * 16 + fq * 4 + jj] = s;
;                 }
;             }
	v_mfma_f32_16x16x32_bf16 v[36:39], v[228:231], v[64:67], v[36:39]
	s_nop 7
	v_mul_f32_e32 v138, v36, v36
	s_nop 1
	v_mov_b32_dpp v138, v138 quad_perm:[1,0,3,2] row_mask:0xf bank_mask:0xf bound_ctrl:1
	v_fmac_f32_e32 v138, v36, v36
	s_nop 1
	v_add_f32_dpp v138, v138, v138 quad_perm:[2,3,0,1] row_mask:0xf bank_mask:0xf bound_ctrl:1
	s_nop 1
	v_add_f32_dpp v153, v138, v138 row_half_mirror row_mask:0xf bank_mask:0xf bound_ctrl:1
	s_nop 1
	v_mov_b32_dpp v224, v153 row_mirror row_mask:0xf bank_mask:0xf bound_ctrl:1
	s_and_saveexec_b64 s[0:1], vcc
	v_add_f32_e32 v138, v153, v224
	ds_write_b32 v148, v138 offset:128
	s_or_b64 exec, exec, s[0:1]
	v_mul_f32_e32 v138, v37, v37
	s_nop 1
	v_mov_b32_dpp v138, v138 quad_perm:[1,0,3,2] row_mask:0xf bank_mask:0xf bound_ctrl:1
	v_fmac_f32_e32 v138, v37, v37
	s_nop 1
	v_add_f32_dpp v138, v138, v138 quad_perm:[2,3,0,1] row_mask:0xf bank_mask:0xf bound_ctrl:1
	s_nop 1
	v_add_f32_dpp v153, v138, v138 row_half_mirror row_mask:0xf bank_mask:0xf bound_ctrl:1
	s_nop 1
	v_mov_b32_dpp v224, v153 row_mirror row_mask:0xf bank_mask:0xf bound_ctrl:1
	s_and_saveexec_b64 s[0:1], vcc
	v_add_f32_e32 v138, v153, v224
	ds_write_b32 v148, v138 offset:132
	s_or_b64 exec, exec, s[0:1]
	v_mul_f32_e32 v138, v38, v38
	s_nop 1
	v_mov_b32_dpp v138, v138 quad_perm:[1,0,3,2] row_mask:0xf bank_mask:0xf bound_ctrl:1
	v_fmac_f32_e32 v138, v38, v38
	s_nop 1
	v_add_f32_dpp v138, v138, v138 quad_perm:[2,3,0,1] row_mask:0xf bank_mask:0xf bound_ctrl:1
	s_nop 1
	v_add_f32_dpp v153, v138, v138 row_half_mirror row_mask:0xf bank_mask:0xf bound_ctrl:1
	s_nop 1
	v_mov_b32_dpp v224, v153 row_mirror row_mask:0xf bank_mask:0xf bound_ctrl:1
	s_and_saveexec_b64 s[0:1], vcc
	v_add_f32_e32 v138, v153, v224
	ds_write_b32 v148, v138 offset:136
	s_or_b64 exec, exec, s[0:1]
	v_mul_f32_e32 v138, v39, v39
	s_nop 1
	v_mov_b32_dpp v138, v138 quad_perm:[1,0,3,2] row_mask:0xf bank_mask:0xf bound_ctrl:1
	v_fmac_f32_e32 v138, v39, v39
	s_nop 1
	v_add_f32_dpp v138, v138, v138 quad_perm:[2,3,0,1] row_mask:0xf bank_mask:0xf bound_ctrl:1
	s_nop 1
	v_add_f32_dpp v153, v138, v138 row_half_mirror row_mask:0xf bank_mask:0xf bound_ctrl:1
	s_nop 1
	v_mov_b32_dpp v224, v153 row_mirror row_mask:0xf bank_mask:0xf bound_ctrl:1
	s_and_saveexec_b64 s[0:1], vcc
	v_add_f32_e32 v138, v153, v224
	ds_write_b32 v148, v138 offset:140
	s_or_b64 exec, exec, s[0:1]
	ds_read_b128 v[228:231], v149 offset:13056
	v_add_u32_e32 v138, v226, v152
	s_waitcnt lgkmcnt(0)
	v_mfma_f32_16x16x32_bf16 v[56:59], v[228:231], v[56:59], 0
	ds_read_b128 v[228:231], v149 offset:13120
	s_waitcnt lgkmcnt(0)
	v_mfma_f32_16x16x32_bf16 v[48:51], v[228:231], v[48:51], v[56:59]
	s_nop 4
	ds_read_b128 v[56:59], v149 offset:13184
	s_waitcnt lgkmcnt(0)
	v_mfma_f32_16x16x32_bf16 v[48:51], v[56:59], v[60:63], v[48:51]
	ds_read_b128 v[56:59], v149 offset:13248
	ds_read_b128 v[60:63], v138
	s_waitcnt lgkmcnt(1)
	v_mfma_f32_16x16x32_bf16 v[48:51], v[56:59], v[52:55], v[48:51]
	ds_read_b128 v[52:55], v227 offset:192
	s_waitcnt lgkmcnt(0)
	s_nop 5
	v_pk_mul_f32 v[50:51], v[54:55], v[50:51]
	v_pk_mul_f32 v[48:49], v[52:53], v[48:49]
	s_nop 1
	v_mfma_f32_16x16x32_bf16 v[32:35], v[60:63], v[32:35], v[48:51]
	s_nop 2
	ds_read_b128 v[48:51], v138 offset:64
	s_waitcnt lgkmcnt(0)
	v_mfma_f32_16x16x32_bf16 v[32:35], v[48:51], v[64:67], v[32:35]
	s_nop 7
	v_mul_f32_e32 v48, v32, v32
	s_nop 1
	v_mov_b32_dpp v48, v48 quad_perm:[1,0,3,2] row_mask:0xf bank_mask:0xf bound_ctrl:1
	v_fmac_f32_e32 v48, v32, v32
	s_nop 1
	v_add_f32_dpp v48, v48, v48 quad_perm:[2,3,0,1] row_mask:0xf bank_mask:0xf bound_ctrl:1
	s_nop 1
	v_add_f32_dpp v48, v48, v48 row_half_mirror row_mask:0xf bank_mask:0xf bound_ctrl:1
	s_nop 1
	v_mov_b32_dpp v49, v48 row_mirror row_mask:0xf bank_mask:0xf bound_ctrl:1
	s_and_saveexec_b64 s[0:1], vcc
	v_add_f32_e32 v48, v48, v49
	ds_write_b32 v148, v48 offset:192
	s_or_b64 exec, exec, s[0:1]
	v_mul_f32_e32 v48, v33, v33
	s_nop 1
	v_mov_b32_dpp v48, v48 quad_perm:[1,0,3,2] row_mask:0xf bank_mask:0xf bound_ctrl:1
	v_fmac_f32_e32 v48, v33, v33
	s_nop 1
	v_add_f32_dpp v48, v48, v48 quad_perm:[2,3,0,1] row_mask:0xf bank_mask:0xf bound_ctrl:1
	s_nop 1
	v_add_f32_dpp v48, v48, v48 row_half_mirror row_mask:0xf bank_mask:0xf bound_ctrl:1
	s_nop 1
	v_mov_b32_dpp v49, v48 row_mirror row_mask:0xf bank_mask:0xf bound_ctrl:1
	s_and_saveexec_b64 s[0:1], vcc
	v_add_f32_e32 v48, v48, v49
	ds_write_b32 v148, v48 offset:196
	s_or_b64 exec, exec, s[0:1]
	v_mul_f32_e32 v48, v34, v34
	s_nop 1
	v_mov_b32_dpp v48, v48 quad_perm:[1,0,3,2] row_mask:0xf bank_mask:0xf bound_ctrl:1
	v_fmac_f32_e32 v48, v34, v34
	s_nop 1
	v_add_f32_dpp v48, v48, v48 quad_perm:[2,3,0,1] row_mask:0xf bank_mask:0xf bound_ctrl:1
	s_nop 1
	v_add_f32_dpp v48, v48, v48 row_half_mirror row_mask:0xf bank_mask:0xf bound_ctrl:1
	s_nop 1
	v_mov_b32_dpp v49, v48 row_mirror row_mask:0xf bank_mask:0xf bound_ctrl:1
	s_and_saveexec_b64 s[0:1], vcc
	v_add_f32_e32 v48, v48, v49
	ds_write_b32 v148, v48 offset:200
	s_or_b64 exec, exec, s[0:1]
	v_mul_f32_e32 v48, v35, v35
	s_nop 1
	v_mov_b32_dpp v48, v48 quad_perm:[1,0,3,2] row_mask:0xf bank_mask:0xf bound_ctrl:1
	v_fmac_f32_e32 v48, v35, v35
	s_nop 1
	v_add_f32_dpp v48, v48, v48 quad_perm:[2,3,0,1] row_mask:0xf bank_mask:0xf bound_ctrl:1
	s_nop 1
	v_add_f32_dpp v48, v48, v48 row_half_mirror row_mask:0xf bank_mask:0xf bound_ctrl:1
	s_nop 1
	v_mov_b32_dpp v49, v48 row_mirror row_mask:0xf bank_mask:0xf bound_ctrl:1
	s_and_saveexec_b64 s[0:1], vcc
	s_cbranch_execz .LBB0_414
	v_add_f32_e32 v48, v48, v49
	ds_write_b32 v148, v48 offset:204
	s_branch .LBB0_414
